# attention QK: K fragments prefetched with exact lgkmcnt counts, DMA issue inside MFMA chain; P2 rewritten by hand (16-row register window per wave)
# speedup vs baseline: 1.0223x; 1.0223x over previous
.LBB0_323:
	v_readlane_b32 s4, v240, 2
	v_readlane_b32 s5, v240, 3
	s_cmp_lt_i32 s4, 3
	s_cselect_b64 s[4:5], -1, 0
	s_and_b64 s[0:1], s[4:5], s[0:1]
	v_writelane_b32 v240, s0, 46
	s_andn2_b64 vcc, exec, s[0:1]
	s_nop 0
	v_writelane_b32 v240, s1, 47
	s_cbranch_vccnz .LBB0_499
	v_lshrrev_b32_e32 v0, 3, v160
	v_readlane_b32 s0, v240, 26
	v_mul_u32_u24_e32 v0, 0x60, v0
	s_cmp_gt_i32 s0, 0x800f
	v_mov_b32_e32 v1, 0
	v_lshlrev_b32_e32 v124, 1, v0
	v_and_b32_e32 v161, 7, v190
	v_readlane_b32 s1, v240, 27
	s_cbranch_scc1 .LBB0_495
	v_readlane_b32 s33, v240, 26
	v_readlane_b32 s34, v240, 28
	v_lshlrev_b32_e32 v156, 4, v160
	v_lshlrev_b32_e32 v157, 2, v160
	v_and_b32_e32 v234, 3, v160
	v_lshlrev_b32_e32 v158, 3, v234
	v_add_u32_e32 v158, 0x500, v158
	v_lshlrev_b32_e32 v159, 5, v234
	v_lshrrev_b32_e32 v234, 3, v160
	v_mul_u32_u24_e32 v234, 0xc0, v234
	v_and_b32_e32 v235, 7, v160
	v_lshlrev_b32_e32 v235, 3, v235
	v_add_u32_e32 v184, v234, v235
	v_add_u32_e32 v184, 0x80, v184
	v_and_b32_e32 v234, 4, v160
	v_cmp_ne_u32_e64 s[52:53], 0, v234
	v_mov_b32_e32 v187, 0x358637bd
	v_mov_b32_e32 v235, 0x80000000
	s_nop 0
	v_cndmask_b32_e64 v185, v235, 0, s[52:53]
	s_mov_b32 s46, 0xffff0000
	s_mov_b32 s47, -1
	s_mov_b32 s48, 0
	s_mov_b32 s49, -1
	s_mov_b32 s50, 0
	s_mov_b32 s51, 0xffff0000
	s_mov_b32 s56, 0xffff0000
	s_mov_b32 s57, 0x3e16c740
	s_mov_b32 s58, 0x3b2aaaab
	s_mov_b32 s59, 0x3b800000
	v_lshlrev_b32_e32 v234, 3, v160
	global_load_dwordx2 v[192:193], v234, s[8:9]
	global_load_dwordx2 v[194:195], v234, s[8:9] offset:512
	global_load_dwordx2 v[196:197], v234, s[8:9] offset:1024
	global_load_dwordx2 v[198:199], v234, s[12:13]
	global_load_dwordx2 v[200:201], v234, s[12:13] offset:512
	s_waitcnt vmcnt(0)
.Lp2_job:
	s_cmpk_ge_u32 s33, 0x810
	s_cbranch_scc1 .Lp2_done
	s_cmpk_ge_u32 s33, 0x800
	s_cbranch_scc1 .Lp2_meta
	s_lshl_b32 s37, s33, 4
	s_and_b32 s40, s33, 0xff
	s_lshl_b32 s39, s40, 4
	s_add_i32 s39, s39, 16
	s_cmp_eq_u32 s40, 0
	s_cselect_b32 s38, 0x8010, s37
	s_mov_b32 s36, 15
	s_mov_b32 s35, 16
	v_lshrrev_b32_e32 v234, 4, v160
	v_sub_u32_e32 v234, 0x7e, v234
	v_lshlrev_b32_e32 v186, 23, v234
	s_branch .Lp2_go
.Lp2_meta:
	s_sub_u32 s39, s33, 0x800
	s_add_i32 s37, s39, 0x8000
	s_mov_b32 s38, s37
	s_mov_b32 s36, s39
	s_mov_b32 s35, 1
	s_add_i32 s40, s39, 1
	v_lshrrev_b32_e32 v234, 4, v160
	v_lshlrev_b32_e64 v234, v234, 2
	v_min_u32_e32 v234, s40, v234
	v_cvt_f32_u32_e32 v234, v234
	v_rcp_f32_e32 v186, v234
.Lp2_go:
	s_mul_i32 s40, s37, 0x400
	s_add_u32 s16, s94, s40
	s_addc_u32 s17, s95, 0
	s_add_u32 s16, s16, 0xe700000
	s_addc_u32 s17, s17, 0
	s_mul_i32 s40, s37, 0x600
	s_add_u32 s18, s94, s40
	s_addc_u32 s19, s95, 0
	s_add_u32 s18, s18, 0x10800000
	s_addc_u32 s19, s19, 0
	s_mul_i32 s40, s39, 0x80
	s_add_u32 s20, s94, s40
	s_addc_u32 s21, s95, 0
	s_add_u32 s20, s20, 0x100000
	s_addc_u32 s21, s21, 0
	s_mul_i32 s40, s37, 0x400
	s_add_u32 s22, s94, s40
	s_addc_u32 s23, s95, 0
	s_add_u32 s22, s22, 0x13900000
	s_addc_u32 s23, s23, 0
	s_mul_i32 s40, s37, 0x300
	s_add_u32 s24, s94, s40
	s_addc_u32 s25, s95, 0
	s_add_u32 s24, s24, 0x15a00000
	s_addc_u32 s25, s25, 0
	s_mul_i32 s40, s37, 0x200
	s_add_u32 s26, s94, s40
	s_addc_u32 s27, s95, 0
	s_add_u32 s26, s26, 0x17300000
	s_addc_u32 s27, s27, 0
	s_mul_i32 s40, s37, 0x600
	s_add_u32 s28, s94, s40
	s_addc_u32 s29, s95, 0
	s_add_u32 s28, s28, 0x18400000
	s_addc_u32 s29, s29, 0
	s_mul_i32 s40, s38, 0x400
	s_add_u32 s30, s94, s40
	s_addc_u32 s31, s95, 0
	s_add_u32 s30, s30, 0xe700000
	s_addc_u32 s31, s31, 0
	s_sub_u32 s30, s30, 0x400
	s_subb_u32 s31, s31, 0
	s_cmp_lt_u32 s36, 1
	s_cbranch_scc1 .Lp2_pz1
	global_load_dwordx4 v[130:133], v156, s[30:31]
	s_branch .Lp2_pn1
.Lp2_pz1:
	v_mov_b32_e32 v130, 0
	v_mov_b32_e32 v131, 0
	v_mov_b32_e32 v132, 0
	v_mov_b32_e32 v133, 0
.Lp2_pn1:
	s_sub_u32 s30, s30, 0x400
	s_subb_u32 s31, s31, 0
	s_cmp_lt_u32 s36, 2
	s_cbranch_scc1 .Lp2_pz2
	global_load_dwordx4 v[116:119], v156, s[30:31]
	s_branch .Lp2_pn2
.Lp2_pz2:
	v_mov_b32_e32 v116, 0
	v_mov_b32_e32 v117, 0
	v_mov_b32_e32 v118, 0
	v_mov_b32_e32 v119, 0
.Lp2_pn2:
	s_sub_u32 s30, s30, 0x400
	s_subb_u32 s31, s31, 0
	s_cmp_lt_u32 s36, 3
	s_cbranch_scc1 .Lp2_pz3
	global_load_dwordx4 v[108:111], v156, s[30:31]
	s_branch .Lp2_pn3
.Lp2_pz3:
	v_mov_b32_e32 v108, 0
	v_mov_b32_e32 v109, 0
	v_mov_b32_e32 v110, 0
	v_mov_b32_e32 v111, 0
.Lp2_pn3:
	s_sub_u32 s30, s30, 0x400
	s_subb_u32 s31, s31, 0
	s_cmp_lt_u32 s36, 4
	s_cbranch_scc1 .Lp2_pz4
	global_load_dwordx4 v[100:103], v156, s[30:31]
	s_branch .Lp2_pn4
.Lp2_pz4:
	v_mov_b32_e32 v100, 0
	v_mov_b32_e32 v101, 0
	v_mov_b32_e32 v102, 0
	v_mov_b32_e32 v103, 0
.Lp2_pn4:
	s_sub_u32 s30, s30, 0x400
	s_subb_u32 s31, s31, 0
	s_cmp_lt_u32 s36, 5
	s_cbranch_scc1 .Lp2_pz5
	global_load_dwordx4 v[92:95], v156, s[30:31]
	s_branch .Lp2_pn5
.Lp2_pz5:
	v_mov_b32_e32 v92, 0
	v_mov_b32_e32 v93, 0
	v_mov_b32_e32 v94, 0
	v_mov_b32_e32 v95, 0
.Lp2_pn5:
	s_sub_u32 s30, s30, 0x400
	s_subb_u32 s31, s31, 0
	s_cmp_lt_u32 s36, 6
	s_cbranch_scc1 .Lp2_pz6
	global_load_dwordx4 v[84:87], v156, s[30:31]
	s_branch .Lp2_pn6
.Lp2_pz6:
	v_mov_b32_e32 v84, 0
	v_mov_b32_e32 v85, 0
	v_mov_b32_e32 v86, 0
	v_mov_b32_e32 v87, 0
.Lp2_pn6:
	s_sub_u32 s30, s30, 0x400
	s_subb_u32 s31, s31, 0
	s_cmp_lt_u32 s36, 7
	s_cbranch_scc1 .Lp2_pz7
	global_load_dwordx4 v[76:79], v156, s[30:31]
	s_branch .Lp2_pn7
.Lp2_pz7:
	v_mov_b32_e32 v76, 0
	v_mov_b32_e32 v77, 0
	v_mov_b32_e32 v78, 0
	v_mov_b32_e32 v79, 0
.Lp2_pn7:
	s_sub_u32 s30, s30, 0x400
	s_subb_u32 s31, s31, 0
	s_cmp_lt_u32 s36, 8
	s_cbranch_scc1 .Lp2_pz8
	global_load_dwordx4 v[68:71], v156, s[30:31]
	s_branch .Lp2_pn8
.Lp2_pz8:
	v_mov_b32_e32 v68, 0
	v_mov_b32_e32 v69, 0
	v_mov_b32_e32 v70, 0
	v_mov_b32_e32 v71, 0
.Lp2_pn8:
	s_sub_u32 s30, s30, 0x400
	s_subb_u32 s31, s31, 0
	s_cmp_lt_u32 s36, 9
	s_cbranch_scc1 .Lp2_pz9
	global_load_dwordx4 v[60:63], v156, s[30:31]
	s_branch .Lp2_pn9
.Lp2_pz9:
	v_mov_b32_e32 v60, 0
	v_mov_b32_e32 v61, 0
	v_mov_b32_e32 v62, 0
	v_mov_b32_e32 v63, 0
.Lp2_pn9:
	s_sub_u32 s30, s30, 0x400
	s_subb_u32 s31, s31, 0
	s_cmp_lt_u32 s36, 10
	s_cbranch_scc1 .Lp2_pz10
	global_load_dwordx4 v[52:55], v156, s[30:31]
	s_branch .Lp2_pn10
.Lp2_pz10:
	v_mov_b32_e32 v52, 0
	v_mov_b32_e32 v53, 0
	v_mov_b32_e32 v54, 0
	v_mov_b32_e32 v55, 0
.Lp2_pn10:
	s_sub_u32 s30, s30, 0x400
	s_subb_u32 s31, s31, 0
	s_cmp_lt_u32 s36, 11
	s_cbranch_scc1 .Lp2_pz11
	global_load_dwordx4 v[44:47], v156, s[30:31]
	s_branch .Lp2_pn11
.Lp2_pz11:
	v_mov_b32_e32 v44, 0
	v_mov_b32_e32 v45, 0
	v_mov_b32_e32 v46, 0
	v_mov_b32_e32 v47, 0
.Lp2_pn11:
	s_sub_u32 s30, s30, 0x400
	s_subb_u32 s31, s31, 0
	s_cmp_lt_u32 s36, 12
	s_cbranch_scc1 .Lp2_pz12
	global_load_dwordx4 v[36:39], v156, s[30:31]
	s_branch .Lp2_pn12
.Lp2_pz12:
	v_mov_b32_e32 v36, 0
	v_mov_b32_e32 v37, 0
	v_mov_b32_e32 v38, 0
	v_mov_b32_e32 v39, 0
.Lp2_pn12:
	s_sub_u32 s30, s30, 0x400
	s_subb_u32 s31, s31, 0
	s_cmp_lt_u32 s36, 13
	s_cbranch_scc1 .Lp2_pz13
	global_load_dwordx4 v[28:31], v156, s[30:31]
	s_branch .Lp2_pn13
.Lp2_pz13:
	v_mov_b32_e32 v28, 0
	v_mov_b32_e32 v29, 0
	v_mov_b32_e32 v30, 0
	v_mov_b32_e32 v31, 0
.Lp2_pn13:
	s_sub_u32 s30, s30, 0x400
	s_subb_u32 s31, s31, 0
	s_cmp_lt_u32 s36, 14
	s_cbranch_scc1 .Lp2_pz14
	global_load_dwordx4 v[20:23], v156, s[30:31]
	s_branch .Lp2_pn14
.Lp2_pz14:
	v_mov_b32_e32 v20, 0
	v_mov_b32_e32 v21, 0
	v_mov_b32_e32 v22, 0
	v_mov_b32_e32 v23, 0
.Lp2_pn14:
	s_sub_u32 s30, s30, 0x400
	s_subb_u32 s31, s31, 0
	s_cmp_lt_u32 s36, 15
	s_cbranch_scc1 .Lp2_pz15
	global_load_dwordx4 v[12:15], v156, s[30:31]
	s_branch .Lp2_pn15
.Lp2_pz15:
	v_mov_b32_e32 v12, 0
	v_mov_b32_e32 v13, 0
	v_mov_b32_e32 v14, 0
	v_mov_b32_e32 v15, 0
.Lp2_pn15:
	global_load_dwordx4 v[134:137], v156, s[16:17]
	global_load_dword v138, v157, s[18:19]
	global_load_dword v139, v157, s[18:19] offset:256
	global_load_dword v140, v157, s[18:19] offset:512
	global_load_dword v141, v157, s[18:19] offset:768
	global_load_dword v142, v157, s[18:19] offset:1024
	global_load_dwordx2 v[144:145], v158, s[18:19]
	global_load_dwordx2 v[146:147], v158, s[18:19] offset:32
	global_load_dwordx4 v[148:151], v159, s[20:21]
	global_load_dwordx4 v[152:155], v159, s[20:21] offset:16
	s_add_u32 s16, s16, 0x400
	s_addc_u32 s17, s17, 0
	s_add_u32 s18, s18, 0x600
	s_addc_u32 s19, s19, 0
	s_add_u32 s20, s20, 0x80
	s_addc_u32 s21, s21, 0
	global_load_dwordx4 v[162:165], v156, s[16:17]
	global_load_dword v166, v157, s[18:19]
	global_load_dword v167, v157, s[18:19] offset:256
	global_load_dword v168, v157, s[18:19] offset:512
	global_load_dword v169, v157, s[18:19] offset:768
	global_load_dword v170, v157, s[18:19] offset:1024
	global_load_dwordx2 v[172:173], v158, s[18:19]
	global_load_dwordx2 v[174:175], v158, s[18:19] offset:32
	global_load_dwordx4 v[176:179], v159, s[20:21]
	global_load_dwordx4 v[180:183], v159, s[20:21] offset:16
	s_add_u32 s16, s16, 0x400
	s_addc_u32 s17, s17, 0
	s_add_u32 s18, s18, 0x600
	s_addc_u32 s19, s19, 0
	s_add_u32 s20, s20, 0x80
	s_addc_u32 s21, s21, 0
	s_waitcnt vmcnt(20)
	v_lshlrev_b32_e32 v126, 16, v130
	v_and_b32_e32 v127, s56, v130
	v_lshlrev_b32_e32 v128, 16, v131
	v_and_b32_e32 v129, s56, v131
	v_lshlrev_b32_e32 v130, 16, v132
	v_and_b32_e32 v131, s56, v132
	v_lshlrev_b32_e32 v132, 16, v133
	v_and_b32_e32 v133, s56, v133
	v_lshlrev_b32_e32 v112, 16, v116
	v_and_b32_e32 v113, s56, v116
	v_lshlrev_b32_e32 v114, 16, v117
	v_and_b32_e32 v115, s56, v117
	v_lshlrev_b32_e32 v116, 16, v118
	v_and_b32_e32 v117, s56, v118
	v_lshlrev_b32_e32 v118, 16, v119
	v_and_b32_e32 v119, s56, v119
	v_lshlrev_b32_e32 v104, 16, v108
	v_and_b32_e32 v105, s56, v108
	v_lshlrev_b32_e32 v106, 16, v109
	v_and_b32_e32 v107, s56, v109
	v_lshlrev_b32_e32 v108, 16, v110
	v_and_b32_e32 v109, s56, v110
	v_lshlrev_b32_e32 v110, 16, v111
	v_and_b32_e32 v111, s56, v111
	v_lshlrev_b32_e32 v96, 16, v100
	v_and_b32_e32 v97, s56, v100
	v_lshlrev_b32_e32 v98, 16, v101
	v_and_b32_e32 v99, s56, v101
	v_lshlrev_b32_e32 v100, 16, v102
	v_and_b32_e32 v101, s56, v102
	v_lshlrev_b32_e32 v102, 16, v103
	v_and_b32_e32 v103, s56, v103
	v_lshlrev_b32_e32 v88, 16, v92
	v_and_b32_e32 v89, s56, v92
	v_lshlrev_b32_e32 v90, 16, v93
	v_and_b32_e32 v91, s56, v93
	v_lshlrev_b32_e32 v92, 16, v94
	v_and_b32_e32 v93, s56, v94
	v_lshlrev_b32_e32 v94, 16, v95
	v_and_b32_e32 v95, s56, v95
	v_lshlrev_b32_e32 v80, 16, v84
	v_and_b32_e32 v81, s56, v84
	v_lshlrev_b32_e32 v82, 16, v85
	v_and_b32_e32 v83, s56, v85
	v_lshlrev_b32_e32 v84, 16, v86
	v_and_b32_e32 v85, s56, v86
	v_lshlrev_b32_e32 v86, 16, v87
	v_and_b32_e32 v87, s56, v87
	v_lshlrev_b32_e32 v72, 16, v76
	v_and_b32_e32 v73, s56, v76
	v_lshlrev_b32_e32 v74, 16, v77
	v_and_b32_e32 v75, s56, v77
	v_lshlrev_b32_e32 v76, 16, v78
	v_and_b32_e32 v77, s56, v78
	v_lshlrev_b32_e32 v78, 16, v79
	v_and_b32_e32 v79, s56, v79
	v_lshlrev_b32_e32 v64, 16, v68
	v_and_b32_e32 v65, s56, v68
	v_lshlrev_b32_e32 v66, 16, v69
	v_and_b32_e32 v67, s56, v69
	v_lshlrev_b32_e32 v68, 16, v70
	v_and_b32_e32 v69, s56, v70
	v_lshlrev_b32_e32 v70, 16, v71
	v_and_b32_e32 v71, s56, v71
	v_lshlrev_b32_e32 v56, 16, v60
	v_and_b32_e32 v57, s56, v60
	v_lshlrev_b32_e32 v58, 16, v61
	v_and_b32_e32 v59, s56, v61
	v_lshlrev_b32_e32 v60, 16, v62
	v_and_b32_e32 v61, s56, v62
	v_lshlrev_b32_e32 v62, 16, v63
	v_and_b32_e32 v63, s56, v63
	v_lshlrev_b32_e32 v48, 16, v52
	v_and_b32_e32 v49, s56, v52
	v_lshlrev_b32_e32 v50, 16, v53
	v_and_b32_e32 v51, s56, v53
	v_lshlrev_b32_e32 v52, 16, v54
	v_and_b32_e32 v53, s56, v54
	v_lshlrev_b32_e32 v54, 16, v55
	v_and_b32_e32 v55, s56, v55
	v_lshlrev_b32_e32 v40, 16, v44
	v_and_b32_e32 v41, s56, v44
	v_lshlrev_b32_e32 v42, 16, v45
	v_and_b32_e32 v43, s56, v45
	v_lshlrev_b32_e32 v44, 16, v46
	v_and_b32_e32 v45, s56, v46
	v_lshlrev_b32_e32 v46, 16, v47
	v_and_b32_e32 v47, s56, v47
	v_lshlrev_b32_e32 v32, 16, v36
	v_and_b32_e32 v33, s56, v36
	v_lshlrev_b32_e32 v34, 16, v37
	v_and_b32_e32 v35, s56, v37
	v_lshlrev_b32_e32 v36, 16, v38
	v_and_b32_e32 v37, s56, v38
	v_lshlrev_b32_e32 v38, 16, v39
	v_and_b32_e32 v39, s56, v39
	v_lshlrev_b32_e32 v24, 16, v28
	v_and_b32_e32 v25, s56, v28
	v_lshlrev_b32_e32 v26, 16, v29
	v_and_b32_e32 v27, s56, v29
	v_lshlrev_b32_e32 v28, 16, v30
	v_and_b32_e32 v29, s56, v30
	v_lshlrev_b32_e32 v30, 16, v31
	v_and_b32_e32 v31, s56, v31
	v_lshlrev_b32_e32 v16, 16, v20
	v_and_b32_e32 v17, s56, v20
	v_lshlrev_b32_e32 v18, 16, v21
	v_and_b32_e32 v19, s56, v21
	v_lshlrev_b32_e32 v20, 16, v22
	v_and_b32_e32 v21, s56, v22
	v_lshlrev_b32_e32 v22, 16, v23
	v_and_b32_e32 v23, s56, v23
	v_lshlrev_b32_e32 v8, 16, v12
	v_and_b32_e32 v9, s56, v12
	v_lshlrev_b32_e32 v10, 16, v13
	v_and_b32_e32 v11, s56, v13
	v_lshlrev_b32_e32 v12, 16, v14
	v_and_b32_e32 v13, s56, v14
	v_lshlrev_b32_e32 v14, 16, v15
	v_and_b32_e32 v15, s56, v15
	s_waitcnt vmcnt(10)
	v_lshlrev_b32_e32 v0, 16, v134
	v_and_b32_e32 v1, s56, v134
	v_lshlrev_b32_e32 v2, 16, v135
	v_and_b32_e32 v3, s56, v135
	v_lshlrev_b32_e32 v4, 16, v136
	v_and_b32_e32 v5, s56, v136
	v_lshlrev_b32_e32 v6, 16, v137
	v_and_b32_e32 v7, s56, v137
	v_cndmask_b32_e64 v234, v144, v146, s[52:53]
	v_cndmask_b32_e64 v235, v145, v147, s[52:53]
	v_cndmask_b32_e64 v232, v146, v144, s[52:53]
	v_cndmask_b32_e64 v233, v147, v145, s[52:53]
	v_lshlrev_b32_e32 v220, 16, v234
	v_and_b32_e32 v221, s56, v234
	v_lshlrev_b32_e32 v222, 16, v235
	v_and_b32_e32 v223, s56, v235
	v_lshlrev_b32_e32 v224, 16, v232
	v_and_b32_e32 v225, s56, v232
	v_lshlrev_b32_e32 v226, 16, v233
	v_and_b32_e32 v227, s56, v233
	v_xor_b32_e32 v234, v185, v149
	v_mul_f32_e32 v224, v224, v234
	v_fmac_f32_e32 v224, v220, v148
	v_xor_b32_e32 v234, v185, v151
	v_mul_f32_e32 v225, v225, v234
	v_fmac_f32_e32 v225, v221, v150
	v_xor_b32_e32 v234, v185, v153
	v_mul_f32_e32 v226, v226, v234
	v_fmac_f32_e32 v226, v222, v152
	v_xor_b32_e32 v234, v185, v155
	v_mul_f32_e32 v227, v227, v234
	v_fmac_f32_e32 v227, v223, v154
	v_cvt_pk_bf16_f32 v238, v224, v225
	v_cvt_pk_bf16_f32 v239, v226, v227
	v_lshlrev_b32_e32 v210, 16, v138
	v_and_b32_e32 v211, s56, v138
	v_lshlrev_b32_e32 v212, 16, v139
	v_and_b32_e32 v213, s56, v139
	v_lshlrev_b32_e32 v214, 16, v140
	v_and_b32_e32 v215, s56, v140
	v_lshlrev_b32_e32 v216, 16, v141
	v_and_b32_e32 v217, s56, v141
	v_lshlrev_b32_e32 v218, 16, v142
	v_and_b32_e32 v219, s56, v142
	global_load_dwordx4 v[134:137], v156, s[16:17]
	global_load_dword v138, v157, s[18:19]
	global_load_dword v139, v157, s[18:19] offset:256
	global_load_dword v140, v157, s[18:19] offset:512
	global_load_dword v141, v157, s[18:19] offset:768
	global_load_dword v142, v157, s[18:19] offset:1024
	global_load_dwordx2 v[144:145], v158, s[18:19]
	global_load_dwordx2 v[146:147], v158, s[18:19] offset:32
	global_load_dwordx4 v[148:151], v159, s[20:21]
	global_load_dwordx4 v[152:155], v159, s[20:21] offset:16
	s_add_u32 s16, s16, 0x400
	s_addc_u32 s17, s17, 0
	s_add_u32 s18, s18, 0x600
	s_addc_u32 s19, s19, 0
	s_add_u32 s20, s20, 0x80
	s_addc_u32 s21, s21, 0
	v_mul_f32_e32 v232, v210, v210
	v_mul_f32_e32 v233, v216, v216
	v_fmac_f32_e32 v232, v211, v211
	v_fmac_f32_e32 v233, v217, v217
	v_fmac_f32_e32 v232, v212, v212
	v_fmac_f32_e32 v233, v218, v218
	v_fmac_f32_e32 v232, v213, v213
	v_fmac_f32_e32 v233, v219, v219
	v_fmac_f32_e32 v232, v214, v214
	v_fmac_f32_e32 v232, v215, v215
	v_add_f32_e32 v202, v0, v126
	v_add_f32_e32 v203, v1, v127
	v_add_f32_e32 v204, v2, v128
	v_add_f32_e32 v205, v3, v129
	v_add_f32_e32 v206, v4, v130
	v_add_f32_e32 v207, v5, v131
	v_add_f32_e32 v208, v6, v132
	v_add_f32_e32 v209, v7, v133
	s_mov_b64 exec, s[46:47]
	v_add_f32_e32 v202, v202, v112
	v_add_f32_e32 v203, v203, v113
	v_add_f32_e32 v204, v204, v114
	v_add_f32_e32 v205, v205, v115
	v_add_f32_e32 v206, v206, v116
	v_add_f32_e32 v207, v207, v117
	v_add_f32_e32 v208, v208, v118
	v_add_f32_e32 v209, v209, v119
	v_add_f32_e32 v202, v202, v104
	v_add_f32_e32 v203, v203, v105
	v_add_f32_e32 v204, v204, v106
	v_add_f32_e32 v205, v205, v107
	v_add_f32_e32 v206, v206, v108
	v_add_f32_e32 v207, v207, v109
	v_add_f32_e32 v208, v208, v110
	v_add_f32_e32 v209, v209, v111
	s_mov_b64 exec, s[48:49]
	v_add_f32_e32 v202, v202, v96
	v_add_f32_e32 v203, v203, v97
	v_add_f32_e32 v204, v204, v98
	v_add_f32_e32 v205, v205, v99
	v_add_f32_e32 v206, v206, v100
	v_add_f32_e32 v207, v207, v101
	v_add_f32_e32 v208, v208, v102
	v_add_f32_e32 v209, v209, v103
	v_add_f32_e32 v202, v202, v88
	v_add_f32_e32 v203, v203, v89
	v_add_f32_e32 v204, v204, v90
	v_add_f32_e32 v205, v205, v91
	v_add_f32_e32 v206, v206, v92
	v_add_f32_e32 v207, v207, v93
	v_add_f32_e32 v208, v208, v94
	v_add_f32_e32 v209, v209, v95
	v_add_f32_e32 v202, v202, v80
	v_add_f32_e32 v203, v203, v81
	v_add_f32_e32 v204, v204, v82
	v_add_f32_e32 v205, v205, v83
	v_add_f32_e32 v206, v206, v84
	v_add_f32_e32 v207, v207, v85
	v_add_f32_e32 v208, v208, v86
	v_add_f32_e32 v209, v209, v87
	v_add_f32_e32 v202, v202, v72
	v_add_f32_e32 v203, v203, v73
	v_add_f32_e32 v204, v204, v74
	v_add_f32_e32 v205, v205, v75
	v_add_f32_e32 v206, v206, v76
	v_add_f32_e32 v207, v207, v77
	v_add_f32_e32 v208, v208, v78
	v_add_f32_e32 v209, v209, v79
	s_mov_b64 exec, s[50:51]
	v_add_f32_e32 v202, v202, v64
	v_add_f32_e32 v203, v203, v65
	v_add_f32_e32 v204, v204, v66
	v_add_f32_e32 v205, v205, v67
	v_add_f32_e32 v206, v206, v68
	v_add_f32_e32 v207, v207, v69
	v_add_f32_e32 v208, v208, v70
	v_add_f32_e32 v209, v209, v71
	v_add_f32_e32 v202, v202, v56
	v_add_f32_e32 v203, v203, v57
	v_add_f32_e32 v204, v204, v58
	v_add_f32_e32 v205, v205, v59
	v_add_f32_e32 v206, v206, v60
	v_add_f32_e32 v207, v207, v61
	v_add_f32_e32 v208, v208, v62
	v_add_f32_e32 v209, v209, v63
	v_add_f32_e32 v202, v202, v48
	v_add_f32_e32 v203, v203, v49
	v_add_f32_e32 v204, v204, v50
	v_add_f32_e32 v205, v205, v51
	v_add_f32_e32 v206, v206, v52
	v_add_f32_e32 v207, v207, v53
	v_add_f32_e32 v208, v208, v54
	v_add_f32_e32 v209, v209, v55
	v_add_f32_e32 v202, v202, v40
	v_add_f32_e32 v203, v203, v41
	v_add_f32_e32 v204, v204, v42
	v_add_f32_e32 v205, v205, v43
	v_add_f32_e32 v206, v206, v44
	v_add_f32_e32 v207, v207, v45
	v_add_f32_e32 v208, v208, v46
	v_add_f32_e32 v209, v209, v47
	v_add_f32_e32 v202, v202, v32
	v_add_f32_e32 v203, v203, v33
	v_add_f32_e32 v204, v204, v34
	v_add_f32_e32 v205, v205, v35
	v_add_f32_e32 v206, v206, v36
	v_add_f32_e32 v207, v207, v37
	v_add_f32_e32 v208, v208, v38
	v_add_f32_e32 v209, v209, v39
	v_add_f32_e32 v202, v202, v24
	v_add_f32_e32 v203, v203, v25
	v_add_f32_e32 v204, v204, v26
	v_add_f32_e32 v205, v205, v27
	v_add_f32_e32 v206, v206, v28
	v_add_f32_e32 v207, v207, v29
	v_add_f32_e32 v208, v208, v30
	v_add_f32_e32 v209, v209, v31
	v_add_f32_e32 v202, v202, v16
	v_add_f32_e32 v203, v203, v17
	v_add_f32_e32 v204, v204, v18
	v_add_f32_e32 v205, v205, v19
	v_add_f32_e32 v206, v206, v20
	v_add_f32_e32 v207, v207, v21
	v_add_f32_e32 v208, v208, v22
	v_add_f32_e32 v209, v209, v23
	v_add_f32_e32 v202, v202, v8
	v_add_f32_e32 v203, v203, v9
	v_add_f32_e32 v204, v204, v10
	v_add_f32_e32 v205, v205, v11
	v_add_f32_e32 v206, v206, v12
	v_add_f32_e32 v207, v207, v13
	v_add_f32_e32 v208, v208, v14
	v_add_f32_e32 v209, v209, v15
	s_mov_b64 exec, -1
	v_fma_f32 v202, v202, v186, -v0
	v_fma_f32 v203, v203, v186, -v1
	v_add_f32_dpp v232, v232, v232 quad_perm:[1,0,3,2] row_mask:0xf bank_mask:0xf
	v_add_f32_dpp v233, v233, v233 quad_perm:[1,0,3,2] row_mask:0xf bank_mask:0xf
	v_fma_f32 v204, v204, v186, -v2
	v_fma_f32 v205, v205, v186, -v3
	v_add_f32_dpp v232, v232, v232 quad_perm:[2,3,0,1] row_mask:0xf bank_mask:0xf
	v_add_f32_dpp v233, v233, v233 quad_perm:[2,3,0,1] row_mask:0xf bank_mask:0xf
	v_fma_f32 v206, v206, v186, -v4
	v_fma_f32 v207, v207, v186, -v5
	v_add_f32_dpp v232, v232, v232 row_half_mirror row_mask:0xf bank_mask:0xf
	v_add_f32_dpp v233, v233, v233 row_half_mirror row_mask:0xf bank_mask:0xf
	v_fma_f32 v208, v208, v186, -v6
	v_fma_f32 v209, v209, v186, -v7
	v_add_f32_dpp v232, v232, v232 row_mirror row_mask:0xf bank_mask:0xf
	v_add_f32_dpp v233, v233, v233 row_mirror row_mask:0xf bank_mask:0xf
	v_cvt_pk_bf16_f32 v228, v202, v203
	v_cvt_pk_bf16_f32 v229, v204, v205
	v_mov_b32_e32 v234, v232
	v_mov_b32_e32 v235, v233
	v_cvt_pk_bf16_f32 v230, v206, v207
	v_cvt_pk_bf16_f32 v231, v208, v209
	v_permlane16_swap_b32_e32 v232, v234
	v_permlane16_swap_b32_e32 v233, v235
	s_nop 0
	v_add_f32_e32 v232, v232, v234
	v_add_f32_e32 v233, v233, v235
	global_store_dwordx4 v156, v[228:231], s[22:23]
	global_store_dwordx2 v184, v[238:239], s[28:29]
	v_mov_b32_e32 v234, v232
	v_mov_b32_e32 v235, v233
	s_nop 1
	v_permlane32_swap_b32_e32 v232, v234
	v_permlane32_swap_b32_e32 v233, v235
	s_nop 0
	v_add_f32_e32 v232, v232, v234
	v_add_f32_e32 v233, v233, v235
	v_fma_f32 v232, v232, s58, v187
	v_fma_f32 v233, v233, s59, v187
	v_rsq_f32_e32 v236, v232
	v_rsq_f32_e32 v237, v233
	s_add_u32 s22, s22, 0x400
	s_addc_u32 s23, s23, 0
	s_add_u32 s28, s28, 0x600
	s_addc_u32 s29, s29, 0
	v_mul_f32_e32 v236, s57, v236
	v_mul_f32_e32 v210, v210, v236
	v_mul_f32_e32 v211, v211, v236
	v_mul_f32_e32 v212, v212, v236
	v_mul_f32_e32 v213, v213, v236
	v_mul_f32_e32 v214, v214, v236
	v_mul_f32_e32 v215, v215, v236
	v_mul_f32_e32 v216, v216, v237
	v_mul_f32_e32 v217, v217, v237
	v_mul_f32_e32 v218, v218, v237
	v_mul_f32_e32 v219, v219, v237
	v_mul_f32_e32 v210, v210, v192
	v_mul_f32_e32 v211, v211, v193
	v_mul_f32_e32 v212, v212, v194
	v_mul_f32_e32 v213, v213, v195
	v_mul_f32_e32 v214, v214, v196
	v_mul_f32_e32 v215, v215, v197
	v_mul_f32_e32 v216, v216, v198
	v_mul_f32_e32 v217, v217, v199
	v_mul_f32_e32 v218, v218, v200
	v_mul_f32_e32 v219, v219, v201
	v_cvt_pk_bf16_f32 v120, v210, v211
	v_cvt_pk_bf16_f32 v121, v212, v213
	v_cvt_pk_bf16_f32 v122, v214, v215
	v_cvt_pk_bf16_f32 v123, v216, v217
	v_cvt_pk_bf16_f32 v125, v218, v219
	global_store_dword v157, v120, s[24:25]
	global_store_dword v157, v121, s[24:25] offset:256
	global_store_dword v157, v122, s[24:25] offset:512
	global_store_dword v157, v123, s[26:27]
	global_store_dword v157, v125, s[26:27] offset:256
	s_add_u32 s24, s24, 0x300
	s_addc_u32 s25, s25, 0
	s_add_u32 s26, s26, 0x200
	s_addc_u32 s27, s27, 0
	s_cmp_eq_u32 s35, 1
	s_cbranch_scc1 .Lp2_next
	s_waitcnt vmcnt(17)
	v_lshlrev_b32_e32 v8, 16, v162
	v_and_b32_e32 v9, s56, v162
	v_lshlrev_b32_e32 v10, 16, v163
	v_and_b32_e32 v11, s56, v163
	v_lshlrev_b32_e32 v12, 16, v164
	v_and_b32_e32 v13, s56, v164
	v_lshlrev_b32_e32 v14, 16, v165
	v_and_b32_e32 v15, s56, v165
	v_cndmask_b32_e64 v234, v172, v174, s[52:53]
	v_cndmask_b32_e64 v235, v173, v175, s[52:53]
	v_cndmask_b32_e64 v232, v174, v172, s[52:53]
	v_cndmask_b32_e64 v233, v175, v173, s[52:53]
	v_lshlrev_b32_e32 v220, 16, v234
	v_and_b32_e32 v221, s56, v234
	v_lshlrev_b32_e32 v222, 16, v235
	v_and_b32_e32 v223, s56, v235
	v_lshlrev_b32_e32 v224, 16, v232
	v_and_b32_e32 v225, s56, v232
	v_lshlrev_b32_e32 v226, 16, v233
	v_and_b32_e32 v227, s56, v233
	v_xor_b32_e32 v234, v185, v177
	v_mul_f32_e32 v224, v224, v234
	v_fmac_f32_e32 v224, v220, v176
	v_xor_b32_e32 v234, v185, v179
	v_mul_f32_e32 v225, v225, v234
	v_fmac_f32_e32 v225, v221, v178
	v_xor_b32_e32 v234, v185, v181
	v_mul_f32_e32 v226, v226, v234
	v_fmac_f32_e32 v226, v222, v180
	v_xor_b32_e32 v234, v185, v183
	v_mul_f32_e32 v227, v227, v234
	v_fmac_f32_e32 v227, v223, v182
	v_cvt_pk_bf16_f32 v238, v224, v225
	v_cvt_pk_bf16_f32 v239, v226, v227
	v_lshlrev_b32_e32 v210, 16, v166
	v_and_b32_e32 v211, s56, v166
	v_lshlrev_b32_e32 v212, 16, v167
	v_and_b32_e32 v213, s56, v167
	v_lshlrev_b32_e32 v214, 16, v168
	v_and_b32_e32 v215, s56, v168
	v_lshlrev_b32_e32 v216, 16, v169
	v_and_b32_e32 v217, s56, v169
	v_lshlrev_b32_e32 v218, 16, v170
	v_and_b32_e32 v219, s56, v170
	global_load_dwordx4 v[162:165], v156, s[16:17]
	global_load_dword v166, v157, s[18:19]
	global_load_dword v167, v157, s[18:19] offset:256
	global_load_dword v168, v157, s[18:19] offset:512
	global_load_dword v169, v157, s[18:19] offset:768
	global_load_dword v170, v157, s[18:19] offset:1024
	global_load_dwordx2 v[172:173], v158, s[18:19]
	global_load_dwordx2 v[174:175], v158, s[18:19] offset:32
	global_load_dwordx4 v[176:179], v159, s[20:21]
	global_load_dwordx4 v[180:183], v159, s[20:21] offset:16
	s_add_u32 s16, s16, 0x400
	s_addc_u32 s17, s17, 0
	s_add_u32 s18, s18, 0x600
	s_addc_u32 s19, s19, 0
	s_add_u32 s20, s20, 0x80
	s_addc_u32 s21, s21, 0
	v_mul_f32_e32 v232, v210, v210
	v_mul_f32_e32 v233, v216, v216
	v_fmac_f32_e32 v232, v211, v211
	v_fmac_f32_e32 v233, v217, v217
	v_fmac_f32_e32 v232, v212, v212
	v_fmac_f32_e32 v233, v218, v218
	v_fmac_f32_e32 v232, v213, v213
	v_fmac_f32_e32 v233, v219, v219
	v_fmac_f32_e32 v232, v214, v214
	v_fmac_f32_e32 v232, v215, v215
	v_add_f32_e32 v202, v8, v0
	v_add_f32_e32 v203, v9, v1
	v_add_f32_e32 v204, v10, v2
	v_add_f32_e32 v205, v11, v3
	v_add_f32_e32 v206, v12, v4
	v_add_f32_e32 v207, v13, v5
	v_add_f32_e32 v208, v14, v6
	v_add_f32_e32 v209, v15, v7
	s_mov_b64 exec, s[46:47]
	v_add_f32_e32 v202, v202, v126
	v_add_f32_e32 v203, v203, v127
	v_add_f32_e32 v204, v204, v128
	v_add_f32_e32 v205, v205, v129
	v_add_f32_e32 v206, v206, v130
	v_add_f32_e32 v207, v207, v131
	v_add_f32_e32 v208, v208, v132
	v_add_f32_e32 v209, v209, v133
	v_add_f32_e32 v202, v202, v112
	v_add_f32_e32 v203, v203, v113
	v_add_f32_e32 v204, v204, v114
	v_add_f32_e32 v205, v205, v115
	v_add_f32_e32 v206, v206, v116
	v_add_f32_e32 v207, v207, v117
	v_add_f32_e32 v208, v208, v118
	v_add_f32_e32 v209, v209, v119
	s_mov_b64 exec, s[48:49]
	v_add_f32_e32 v202, v202, v104
	v_add_f32_e32 v203, v203, v105
	v_add_f32_e32 v204, v204, v106
	v_add_f32_e32 v205, v205, v107
	v_add_f32_e32 v206, v206, v108
	v_add_f32_e32 v207, v207, v109
	v_add_f32_e32 v208, v208, v110
	v_add_f32_e32 v209, v209, v111
	v_add_f32_e32 v202, v202, v96
	v_add_f32_e32 v203, v203, v97
	v_add_f32_e32 v204, v204, v98
	v_add_f32_e32 v205, v205, v99
	v_add_f32_e32 v206, v206, v100
	v_add_f32_e32 v207, v207, v101
	v_add_f32_e32 v208, v208, v102
	v_add_f32_e32 v209, v209, v103
	v_add_f32_e32 v202, v202, v88
	v_add_f32_e32 v203, v203, v89
	v_add_f32_e32 v204, v204, v90
	v_add_f32_e32 v205, v205, v91
	v_add_f32_e32 v206, v206, v92
	v_add_f32_e32 v207, v207, v93
	v_add_f32_e32 v208, v208, v94
	v_add_f32_e32 v209, v209, v95
	v_add_f32_e32 v202, v202, v80
	v_add_f32_e32 v203, v203, v81
	v_add_f32_e32 v204, v204, v82
	v_add_f32_e32 v205, v205, v83
	v_add_f32_e32 v206, v206, v84
	v_add_f32_e32 v207, v207, v85
	v_add_f32_e32 v208, v208, v86
	v_add_f32_e32 v209, v209, v87
	s_mov_b64 exec, s[50:51]
	v_add_f32_e32 v202, v202, v72
	v_add_f32_e32 v203, v203, v73
	v_add_f32_e32 v204, v204, v74
	v_add_f32_e32 v205, v205, v75
	v_add_f32_e32 v206, v206, v76
	v_add_f32_e32 v207, v207, v77
	v_add_f32_e32 v208, v208, v78
	v_add_f32_e32 v209, v209, v79
	v_add_f32_e32 v202, v202, v64
	v_add_f32_e32 v203, v203, v65
	v_add_f32_e32 v204, v204, v66
	v_add_f32_e32 v205, v205, v67
	v_add_f32_e32 v206, v206, v68
	v_add_f32_e32 v207, v207, v69
	v_add_f32_e32 v208, v208, v70
	v_add_f32_e32 v209, v209, v71
	v_add_f32_e32 v202, v202, v56
	v_add_f32_e32 v203, v203, v57
	v_add_f32_e32 v204, v204, v58
	v_add_f32_e32 v205, v205, v59
	v_add_f32_e32 v206, v206, v60
	v_add_f32_e32 v207, v207, v61
	v_add_f32_e32 v208, v208, v62
	v_add_f32_e32 v209, v209, v63
	v_add_f32_e32 v202, v202, v48
	v_add_f32_e32 v203, v203, v49
	v_add_f32_e32 v204, v204, v50
	v_add_f32_e32 v205, v205, v51
	v_add_f32_e32 v206, v206, v52
	v_add_f32_e32 v207, v207, v53
	v_add_f32_e32 v208, v208, v54
	v_add_f32_e32 v209, v209, v55
	v_add_f32_e32 v202, v202, v40
	v_add_f32_e32 v203, v203, v41
	v_add_f32_e32 v204, v204, v42
	v_add_f32_e32 v205, v205, v43
	v_add_f32_e32 v206, v206, v44
	v_add_f32_e32 v207, v207, v45
	v_add_f32_e32 v208, v208, v46
	v_add_f32_e32 v209, v209, v47
	v_add_f32_e32 v202, v202, v32
	v_add_f32_e32 v203, v203, v33
	v_add_f32_e32 v204, v204, v34
	v_add_f32_e32 v205, v205, v35
	v_add_f32_e32 v206, v206, v36
	v_add_f32_e32 v207, v207, v37
	v_add_f32_e32 v208, v208, v38
	v_add_f32_e32 v209, v209, v39
	v_add_f32_e32 v202, v202, v24
	v_add_f32_e32 v203, v203, v25
	v_add_f32_e32 v204, v204, v26
	v_add_f32_e32 v205, v205, v27
	v_add_f32_e32 v206, v206, v28
	v_add_f32_e32 v207, v207, v29
	v_add_f32_e32 v208, v208, v30
	v_add_f32_e32 v209, v209, v31
	v_add_f32_e32 v202, v202, v16
	v_add_f32_e32 v203, v203, v17
	v_add_f32_e32 v204, v204, v18
	v_add_f32_e32 v205, v205, v19
	v_add_f32_e32 v206, v206, v20
	v_add_f32_e32 v207, v207, v21
	v_add_f32_e32 v208, v208, v22
	v_add_f32_e32 v209, v209, v23
	s_mov_b64 exec, -1
	v_fma_f32 v202, v202, v186, -v8
	v_fma_f32 v203, v203, v186, -v9
	v_add_f32_dpp v232, v232, v232 quad_perm:[1,0,3,2] row_mask:0xf bank_mask:0xf
	v_add_f32_dpp v233, v233, v233 quad_perm:[1,0,3,2] row_mask:0xf bank_mask:0xf
	v_fma_f32 v204, v204, v186, -v10
	v_fma_f32 v205, v205, v186, -v11
	v_add_f32_dpp v232, v232, v232 quad_perm:[2,3,0,1] row_mask:0xf bank_mask:0xf
	v_add_f32_dpp v233, v233, v233 quad_perm:[2,3,0,1] row_mask:0xf bank_mask:0xf
	v_fma_f32 v206, v206, v186, -v12
	v_fma_f32 v207, v207, v186, -v13
	v_add_f32_dpp v232, v232, v232 row_half_mirror row_mask:0xf bank_mask:0xf
	v_add_f32_dpp v233, v233, v233 row_half_mirror row_mask:0xf bank_mask:0xf
	v_fma_f32 v208, v208, v186, -v14
	v_fma_f32 v209, v209, v186, -v15
	v_add_f32_dpp v232, v232, v232 row_mirror row_mask:0xf bank_mask:0xf
	v_add_f32_dpp v233, v233, v233 row_mirror row_mask:0xf bank_mask:0xf
	v_cvt_pk_bf16_f32 v228, v202, v203
	v_cvt_pk_bf16_f32 v229, v204, v205
	v_mov_b32_e32 v234, v232
	v_mov_b32_e32 v235, v233
	v_cvt_pk_bf16_f32 v230, v206, v207
	v_cvt_pk_bf16_f32 v231, v208, v209
	v_permlane16_swap_b32_e32 v232, v234
	v_permlane16_swap_b32_e32 v233, v235
	s_nop 0
	v_add_f32_e32 v232, v232, v234
	v_add_f32_e32 v233, v233, v235
	global_store_dwordx4 v156, v[228:231], s[22:23]
	global_store_dwordx2 v184, v[238:239], s[28:29]
	v_mov_b32_e32 v234, v232
	v_mov_b32_e32 v235, v233
	s_nop 1
	v_permlane32_swap_b32_e32 v232, v234
	v_permlane32_swap_b32_e32 v233, v235
	s_nop 0
	v_add_f32_e32 v232, v232, v234
	v_add_f32_e32 v233, v233, v235
	v_fma_f32 v232, v232, s58, v187
	v_fma_f32 v233, v233, s59, v187
	v_rsq_f32_e32 v236, v232
	v_rsq_f32_e32 v237, v233
	s_add_u32 s22, s22, 0x400
	s_addc_u32 s23, s23, 0
	s_add_u32 s28, s28, 0x600
	s_addc_u32 s29, s29, 0
	v_mul_f32_e32 v236, s57, v236
	v_mul_f32_e32 v210, v210, v236
	v_mul_f32_e32 v211, v211, v236
	v_mul_f32_e32 v212, v212, v236
	v_mul_f32_e32 v213, v213, v236
	v_mul_f32_e32 v214, v214, v236
	v_mul_f32_e32 v215, v215, v236
	v_mul_f32_e32 v216, v216, v237
	v_mul_f32_e32 v217, v217, v237
	v_mul_f32_e32 v218, v218, v237
	v_mul_f32_e32 v219, v219, v237
	v_mul_f32_e32 v210, v210, v192
	v_mul_f32_e32 v211, v211, v193
	v_mul_f32_e32 v212, v212, v194
	v_mul_f32_e32 v213, v213, v195
	v_mul_f32_e32 v214, v214, v196
	v_mul_f32_e32 v215, v215, v197
	v_mul_f32_e32 v216, v216, v198
	v_mul_f32_e32 v217, v217, v199
	v_mul_f32_e32 v218, v218, v200
	v_mul_f32_e32 v219, v219, v201
	v_cvt_pk_bf16_f32 v120, v210, v211
	v_cvt_pk_bf16_f32 v121, v212, v213
	v_cvt_pk_bf16_f32 v122, v214, v215
	v_cvt_pk_bf16_f32 v123, v216, v217
	v_cvt_pk_bf16_f32 v125, v218, v219
	global_store_dword v157, v120, s[24:25]
	global_store_dword v157, v121, s[24:25] offset:256
	global_store_dword v157, v122, s[24:25] offset:512
	global_store_dword v157, v123, s[26:27]
	global_store_dword v157, v125, s[26:27] offset:256
	s_add_u32 s24, s24, 0x300
	s_addc_u32 s25, s25, 0
	s_add_u32 s26, s26, 0x200
	s_addc_u32 s27, s27, 0
	s_waitcnt vmcnt(24)
	v_lshlrev_b32_e32 v16, 16, v134
	v_and_b32_e32 v17, s56, v134
	v_lshlrev_b32_e32 v18, 16, v135
	v_and_b32_e32 v19, s56, v135
	v_lshlrev_b32_e32 v20, 16, v136
	v_and_b32_e32 v21, s56, v136
	v_lshlrev_b32_e32 v22, 16, v137
	v_and_b32_e32 v23, s56, v137
	v_cndmask_b32_e64 v234, v144, v146, s[52:53]
	v_cndmask_b32_e64 v235, v145, v147, s[52:53]
	v_cndmask_b32_e64 v232, v146, v144, s[52:53]
	v_cndmask_b32_e64 v233, v147, v145, s[52:53]
	v_lshlrev_b32_e32 v220, 16, v234
	v_and_b32_e32 v221, s56, v234
	v_lshlrev_b32_e32 v222, 16, v235
	v_and_b32_e32 v223, s56, v235
	v_lshlrev_b32_e32 v224, 16, v232
	v_and_b32_e32 v225, s56, v232
	v_lshlrev_b32_e32 v226, 16, v233
	v_and_b32_e32 v227, s56, v233
	v_xor_b32_e32 v234, v185, v149
	v_mul_f32_e32 v224, v224, v234
	v_fmac_f32_e32 v224, v220, v148
	v_xor_b32_e32 v234, v185, v151
	v_mul_f32_e32 v225, v225, v234
	v_fmac_f32_e32 v225, v221, v150
	v_xor_b32_e32 v234, v185, v153
	v_mul_f32_e32 v226, v226, v234
	v_fmac_f32_e32 v226, v222, v152
	v_xor_b32_e32 v234, v185, v155
	v_mul_f32_e32 v227, v227, v234
	v_fmac_f32_e32 v227, v223, v154
	v_cvt_pk_bf16_f32 v238, v224, v225
	v_cvt_pk_bf16_f32 v239, v226, v227
	v_lshlrev_b32_e32 v210, 16, v138
	v_and_b32_e32 v211, s56, v138
	v_lshlrev_b32_e32 v212, 16, v139
	v_and_b32_e32 v213, s56, v139
	v_lshlrev_b32_e32 v214, 16, v140
	v_and_b32_e32 v215, s56, v140
	v_lshlrev_b32_e32 v216, 16, v141
	v_and_b32_e32 v217, s56, v141
	v_lshlrev_b32_e32 v218, 16, v142
	v_and_b32_e32 v219, s56, v142
	global_load_dwordx4 v[134:137], v156, s[16:17]
	global_load_dword v138, v157, s[18:19]
	global_load_dword v139, v157, s[18:19] offset:256
	global_load_dword v140, v157, s[18:19] offset:512
	global_load_dword v141, v157, s[18:19] offset:768
	global_load_dword v142, v157, s[18:19] offset:1024
	global_load_dwordx2 v[144:145], v158, s[18:19]
	global_load_dwordx2 v[146:147], v158, s[18:19] offset:32
	global_load_dwordx4 v[148:151], v159, s[20:21]
	global_load_dwordx4 v[152:155], v159, s[20:21] offset:16
	s_add_u32 s16, s16, 0x400
	s_addc_u32 s17, s17, 0
	s_add_u32 s18, s18, 0x600
	s_addc_u32 s19, s19, 0
	s_add_u32 s20, s20, 0x80
	s_addc_u32 s21, s21, 0
	v_mul_f32_e32 v232, v210, v210
	v_mul_f32_e32 v233, v216, v216
	v_fmac_f32_e32 v232, v211, v211
	v_fmac_f32_e32 v233, v217, v217
	v_fmac_f32_e32 v232, v212, v212
	v_fmac_f32_e32 v233, v218, v218
	v_fmac_f32_e32 v232, v213, v213
	v_fmac_f32_e32 v233, v219, v219
	v_fmac_f32_e32 v232, v214, v214
	v_fmac_f32_e32 v232, v215, v215
	v_add_f32_e32 v202, v16, v8
	v_add_f32_e32 v203, v17, v9
	v_add_f32_e32 v204, v18, v10
	v_add_f32_e32 v205, v19, v11
	v_add_f32_e32 v206, v20, v12
	v_add_f32_e32 v207, v21, v13
	v_add_f32_e32 v208, v22, v14
	v_add_f32_e32 v209, v23, v15
	s_mov_b64 exec, s[46:47]
	v_add_f32_e32 v202, v202, v0
	v_add_f32_e32 v203, v203, v1
	v_add_f32_e32 v204, v204, v2
	v_add_f32_e32 v205, v205, v3
	v_add_f32_e32 v206, v206, v4
	v_add_f32_e32 v207, v207, v5
	v_add_f32_e32 v208, v208, v6
	v_add_f32_e32 v209, v209, v7
	v_add_f32_e32 v202, v202, v126
	v_add_f32_e32 v203, v203, v127
	v_add_f32_e32 v204, v204, v128
	v_add_f32_e32 v205, v205, v129
	v_add_f32_e32 v206, v206, v130
	v_add_f32_e32 v207, v207, v131
	v_add_f32_e32 v208, v208, v132
	v_add_f32_e32 v209, v209, v133
	s_mov_b64 exec, s[48:49]
	v_add_f32_e32 v202, v202, v112
	v_add_f32_e32 v203, v203, v113
	v_add_f32_e32 v204, v204, v114
	v_add_f32_e32 v205, v205, v115
	v_add_f32_e32 v206, v206, v116
	v_add_f32_e32 v207, v207, v117
	v_add_f32_e32 v208, v208, v118
	v_add_f32_e32 v209, v209, v119
	v_add_f32_e32 v202, v202, v104
	v_add_f32_e32 v203, v203, v105
	v_add_f32_e32 v204, v204, v106
	v_add_f32_e32 v205, v205, v107
	v_add_f32_e32 v206, v206, v108
	v_add_f32_e32 v207, v207, v109
	v_add_f32_e32 v208, v208, v110
	v_add_f32_e32 v209, v209, v111
	v_add_f32_e32 v202, v202, v96
	v_add_f32_e32 v203, v203, v97
	v_add_f32_e32 v204, v204, v98
	v_add_f32_e32 v205, v205, v99
	v_add_f32_e32 v206, v206, v100
	v_add_f32_e32 v207, v207, v101
	v_add_f32_e32 v208, v208, v102
	v_add_f32_e32 v209, v209, v103
	v_add_f32_e32 v202, v202, v88
	v_add_f32_e32 v203, v203, v89
	v_add_f32_e32 v204, v204, v90
	v_add_f32_e32 v205, v205, v91
	v_add_f32_e32 v206, v206, v92
	v_add_f32_e32 v207, v207, v93
	v_add_f32_e32 v208, v208, v94
	v_add_f32_e32 v209, v209, v95
	s_mov_b64 exec, s[50:51]
	v_add_f32_e32 v202, v202, v80
	v_add_f32_e32 v203, v203, v81
	v_add_f32_e32 v204, v204, v82
	v_add_f32_e32 v205, v205, v83
	v_add_f32_e32 v206, v206, v84
	v_add_f32_e32 v207, v207, v85
	v_add_f32_e32 v208, v208, v86
	v_add_f32_e32 v209, v209, v87
	v_add_f32_e32 v202, v202, v72
	v_add_f32_e32 v203, v203, v73
	v_add_f32_e32 v204, v204, v74
	v_add_f32_e32 v205, v205, v75
	v_add_f32_e32 v206, v206, v76
	v_add_f32_e32 v207, v207, v77
	v_add_f32_e32 v208, v208, v78
	v_add_f32_e32 v209, v209, v79
	v_add_f32_e32 v202, v202, v64
	v_add_f32_e32 v203, v203, v65
	v_add_f32_e32 v204, v204, v66
	v_add_f32_e32 v205, v205, v67
	v_add_f32_e32 v206, v206, v68
	v_add_f32_e32 v207, v207, v69
	v_add_f32_e32 v208, v208, v70
	v_add_f32_e32 v209, v209, v71
	v_add_f32_e32 v202, v202, v56
	v_add_f32_e32 v203, v203, v57
	v_add_f32_e32 v204, v204, v58
	v_add_f32_e32 v205, v205, v59
	v_add_f32_e32 v206, v206, v60
	v_add_f32_e32 v207, v207, v61
	v_add_f32_e32 v208, v208, v62
	v_add_f32_e32 v209, v209, v63
	v_add_f32_e32 v202, v202, v48
	v_add_f32_e32 v203, v203, v49
	v_add_f32_e32 v204, v204, v50
	v_add_f32_e32 v205, v205, v51
	v_add_f32_e32 v206, v206, v52
	v_add_f32_e32 v207, v207, v53
	v_add_f32_e32 v208, v208, v54
	v_add_f32_e32 v209, v209, v55
	v_add_f32_e32 v202, v202, v40
	v_add_f32_e32 v203, v203, v41
	v_add_f32_e32 v204, v204, v42
	v_add_f32_e32 v205, v205, v43
	v_add_f32_e32 v206, v206, v44
	v_add_f32_e32 v207, v207, v45
	v_add_f32_e32 v208, v208, v46
	v_add_f32_e32 v209, v209, v47
	v_add_f32_e32 v202, v202, v32
	v_add_f32_e32 v203, v203, v33
	v_add_f32_e32 v204, v204, v34
	v_add_f32_e32 v205, v205, v35
	v_add_f32_e32 v206, v206, v36
	v_add_f32_e32 v207, v207, v37
	v_add_f32_e32 v208, v208, v38
	v_add_f32_e32 v209, v209, v39
	v_add_f32_e32 v202, v202, v24
	v_add_f32_e32 v203, v203, v25
	v_add_f32_e32 v204, v204, v26
	v_add_f32_e32 v205, v205, v27
	v_add_f32_e32 v206, v206, v28
	v_add_f32_e32 v207, v207, v29
	v_add_f32_e32 v208, v208, v30
	v_add_f32_e32 v209, v209, v31
	s_mov_b64 exec, -1
	v_fma_f32 v202, v202, v186, -v16
	v_fma_f32 v203, v203, v186, -v17
	v_add_f32_dpp v232, v232, v232 quad_perm:[1,0,3,2] row_mask:0xf bank_mask:0xf
	v_add_f32_dpp v233, v233, v233 quad_perm:[1,0,3,2] row_mask:0xf bank_mask:0xf
	v_fma_f32 v204, v204, v186, -v18
	v_fma_f32 v205, v205, v186, -v19
	v_add_f32_dpp v232, v232, v232 quad_perm:[2,3,0,1] row_mask:0xf bank_mask:0xf
	v_add_f32_dpp v233, v233, v233 quad_perm:[2,3,0,1] row_mask:0xf bank_mask:0xf
	v_fma_f32 v206, v206, v186, -v20
	v_fma_f32 v207, v207, v186, -v21
	v_add_f32_dpp v232, v232, v232 row_half_mirror row_mask:0xf bank_mask:0xf
	v_add_f32_dpp v233, v233, v233 row_half_mirror row_mask:0xf bank_mask:0xf
	v_fma_f32 v208, v208, v186, -v22
	v_fma_f32 v209, v209, v186, -v23
	v_add_f32_dpp v232, v232, v232 row_mirror row_mask:0xf bank_mask:0xf
	v_add_f32_dpp v233, v233, v233 row_mirror row_mask:0xf bank_mask:0xf
	v_cvt_pk_bf16_f32 v228, v202, v203
	v_cvt_pk_bf16_f32 v229, v204, v205
	v_mov_b32_e32 v234, v232
	v_mov_b32_e32 v235, v233
	v_cvt_pk_bf16_f32 v230, v206, v207
	v_cvt_pk_bf16_f32 v231, v208, v209
	v_permlane16_swap_b32_e32 v232, v234
	v_permlane16_swap_b32_e32 v233, v235
	s_nop 0
	v_add_f32_e32 v232, v232, v234
	v_add_f32_e32 v233, v233, v235
	global_store_dwordx4 v156, v[228:231], s[22:23]
	global_store_dwordx2 v184, v[238:239], s[28:29]
	v_mov_b32_e32 v234, v232
	v_mov_b32_e32 v235, v233
	s_nop 1
	v_permlane32_swap_b32_e32 v232, v234
	v_permlane32_swap_b32_e32 v233, v235
	s_nop 0
	v_add_f32_e32 v232, v232, v234
	v_add_f32_e32 v233, v233, v235
	v_fma_f32 v232, v232, s58, v187
	v_fma_f32 v233, v233, s59, v187
	v_rsq_f32_e32 v236, v232
	v_rsq_f32_e32 v237, v233
	s_add_u32 s22, s22, 0x400
	s_addc_u32 s23, s23, 0
	s_add_u32 s28, s28, 0x600
	s_addc_u32 s29, s29, 0
	v_mul_f32_e32 v236, s57, v236
	v_mul_f32_e32 v210, v210, v236
	v_mul_f32_e32 v211, v211, v236
	v_mul_f32_e32 v212, v212, v236
	v_mul_f32_e32 v213, v213, v236
	v_mul_f32_e32 v214, v214, v236
	v_mul_f32_e32 v215, v215, v236
	v_mul_f32_e32 v216, v216, v237
	v_mul_f32_e32 v217, v217, v237
	v_mul_f32_e32 v218, v218, v237
	v_mul_f32_e32 v219, v219, v237
	v_mul_f32_e32 v210, v210, v192
	v_mul_f32_e32 v211, v211, v193
	v_mul_f32_e32 v212, v212, v194
	v_mul_f32_e32 v213, v213, v195
	v_mul_f32_e32 v214, v214, v196
	v_mul_f32_e32 v215, v215, v197
	v_mul_f32_e32 v216, v216, v198
	v_mul_f32_e32 v217, v217, v199
	v_mul_f32_e32 v218, v218, v200
	v_mul_f32_e32 v219, v219, v201
	v_cvt_pk_bf16_f32 v120, v210, v211
	v_cvt_pk_bf16_f32 v121, v212, v213
	v_cvt_pk_bf16_f32 v122, v214, v215
	v_cvt_pk_bf16_f32 v123, v216, v217
	v_cvt_pk_bf16_f32 v125, v218, v219
	global_store_dword v157, v120, s[24:25]
	global_store_dword v157, v121, s[24:25] offset:256
	global_store_dword v157, v122, s[24:25] offset:512
	global_store_dword v157, v123, s[26:27]
	global_store_dword v157, v125, s[26:27] offset:256
	s_add_u32 s24, s24, 0x300
	s_addc_u32 s25, s25, 0
	s_add_u32 s26, s26, 0x200
	s_addc_u32 s27, s27, 0
	s_waitcnt vmcnt(24)
	v_lshlrev_b32_e32 v24, 16, v162
	v_and_b32_e32 v25, s56, v162
	v_lshlrev_b32_e32 v26, 16, v163
	v_and_b32_e32 v27, s56, v163
	v_lshlrev_b32_e32 v28, 16, v164
	v_and_b32_e32 v29, s56, v164
	v_lshlrev_b32_e32 v30, 16, v165
	v_and_b32_e32 v31, s56, v165
	v_cndmask_b32_e64 v234, v172, v174, s[52:53]
	v_cndmask_b32_e64 v235, v173, v175, s[52:53]
	v_cndmask_b32_e64 v232, v174, v172, s[52:53]
	v_cndmask_b32_e64 v233, v175, v173, s[52:53]
	v_lshlrev_b32_e32 v220, 16, v234
	v_and_b32_e32 v221, s56, v234
	v_lshlrev_b32_e32 v222, 16, v235
	v_and_b32_e32 v223, s56, v235
	v_lshlrev_b32_e32 v224, 16, v232
	v_and_b32_e32 v225, s56, v232
	v_lshlrev_b32_e32 v226, 16, v233
	v_and_b32_e32 v227, s56, v233
	v_xor_b32_e32 v234, v185, v177
	v_mul_f32_e32 v224, v224, v234
	v_fmac_f32_e32 v224, v220, v176
	v_xor_b32_e32 v234, v185, v179
	v_mul_f32_e32 v225, v225, v234
	v_fmac_f32_e32 v225, v221, v178
	v_xor_b32_e32 v234, v185, v181
	v_mul_f32_e32 v226, v226, v234
	v_fmac_f32_e32 v226, v222, v180
	v_xor_b32_e32 v234, v185, v183
	v_mul_f32_e32 v227, v227, v234
	v_fmac_f32_e32 v227, v223, v182
	v_cvt_pk_bf16_f32 v238, v224, v225
	v_cvt_pk_bf16_f32 v239, v226, v227
	v_lshlrev_b32_e32 v210, 16, v166
	v_and_b32_e32 v211, s56, v166
	v_lshlrev_b32_e32 v212, 16, v167
	v_and_b32_e32 v213, s56, v167
	v_lshlrev_b32_e32 v214, 16, v168
	v_and_b32_e32 v215, s56, v168
	v_lshlrev_b32_e32 v216, 16, v169
	v_and_b32_e32 v217, s56, v169
	v_lshlrev_b32_e32 v218, 16, v170
	v_and_b32_e32 v219, s56, v170
	global_load_dwordx4 v[162:165], v156, s[16:17]
	global_load_dword v166, v157, s[18:19]
	global_load_dword v167, v157, s[18:19] offset:256
	global_load_dword v168, v157, s[18:19] offset:512
	global_load_dword v169, v157, s[18:19] offset:768
	global_load_dword v170, v157, s[18:19] offset:1024
	global_load_dwordx2 v[172:173], v158, s[18:19]
	global_load_dwordx2 v[174:175], v158, s[18:19] offset:32
	global_load_dwordx4 v[176:179], v159, s[20:21]
	global_load_dwordx4 v[180:183], v159, s[20:21] offset:16
	s_add_u32 s16, s16, 0x400
	s_addc_u32 s17, s17, 0
	s_add_u32 s18, s18, 0x600
	s_addc_u32 s19, s19, 0
	s_add_u32 s20, s20, 0x80
	s_addc_u32 s21, s21, 0
	v_mul_f32_e32 v232, v210, v210
	v_mul_f32_e32 v233, v216, v216
	v_fmac_f32_e32 v232, v211, v211
	v_fmac_f32_e32 v233, v217, v217
	v_fmac_f32_e32 v232, v212, v212
	v_fmac_f32_e32 v233, v218, v218
	v_fmac_f32_e32 v232, v213, v213
	v_fmac_f32_e32 v233, v219, v219
	v_fmac_f32_e32 v232, v214, v214
	v_fmac_f32_e32 v232, v215, v215
	v_add_f32_e32 v202, v24, v16
	v_add_f32_e32 v203, v25, v17
	v_add_f32_e32 v204, v26, v18
	v_add_f32_e32 v205, v27, v19
	v_add_f32_e32 v206, v28, v20
	v_add_f32_e32 v207, v29, v21
	v_add_f32_e32 v208, v30, v22
	v_add_f32_e32 v209, v31, v23
	s_mov_b64 exec, s[46:47]
	v_add_f32_e32 v202, v202, v8
	v_add_f32_e32 v203, v203, v9
	v_add_f32_e32 v204, v204, v10
	v_add_f32_e32 v205, v205, v11
	v_add_f32_e32 v206, v206, v12
	v_add_f32_e32 v207, v207, v13
	v_add_f32_e32 v208, v208, v14
	v_add_f32_e32 v209, v209, v15
	v_add_f32_e32 v202, v202, v0
	v_add_f32_e32 v203, v203, v1
	v_add_f32_e32 v204, v204, v2
	v_add_f32_e32 v205, v205, v3
	v_add_f32_e32 v206, v206, v4
	v_add_f32_e32 v207, v207, v5
	v_add_f32_e32 v208, v208, v6
	v_add_f32_e32 v209, v209, v7
	s_mov_b64 exec, s[48:49]
	v_add_f32_e32 v202, v202, v126
	v_add_f32_e32 v203, v203, v127
	v_add_f32_e32 v204, v204, v128
	v_add_f32_e32 v205, v205, v129
	v_add_f32_e32 v206, v206, v130
	v_add_f32_e32 v207, v207, v131
	v_add_f32_e32 v208, v208, v132
	v_add_f32_e32 v209, v209, v133
	v_add_f32_e32 v202, v202, v112
	v_add_f32_e32 v203, v203, v113
	v_add_f32_e32 v204, v204, v114
	v_add_f32_e32 v205, v205, v115
	v_add_f32_e32 v206, v206, v116
	v_add_f32_e32 v207, v207, v117
	v_add_f32_e32 v208, v208, v118
	v_add_f32_e32 v209, v209, v119
	v_add_f32_e32 v202, v202, v104
	v_add_f32_e32 v203, v203, v105
	v_add_f32_e32 v204, v204, v106
	v_add_f32_e32 v205, v205, v107
	v_add_f32_e32 v206, v206, v108
	v_add_f32_e32 v207, v207, v109
	v_add_f32_e32 v208, v208, v110
	v_add_f32_e32 v209, v209, v111
	v_add_f32_e32 v202, v202, v96
	v_add_f32_e32 v203, v203, v97
	v_add_f32_e32 v204, v204, v98
	v_add_f32_e32 v205, v205, v99
	v_add_f32_e32 v206, v206, v100
	v_add_f32_e32 v207, v207, v101
	v_add_f32_e32 v208, v208, v102
	v_add_f32_e32 v209, v209, v103
	s_mov_b64 exec, s[50:51]
	v_add_f32_e32 v202, v202, v88
	v_add_f32_e32 v203, v203, v89
	v_add_f32_e32 v204, v204, v90
	v_add_f32_e32 v205, v205, v91
	v_add_f32_e32 v206, v206, v92
	v_add_f32_e32 v207, v207, v93
	v_add_f32_e32 v208, v208, v94
	v_add_f32_e32 v209, v209, v95
	v_add_f32_e32 v202, v202, v80
	v_add_f32_e32 v203, v203, v81
	v_add_f32_e32 v204, v204, v82
	v_add_f32_e32 v205, v205, v83
	v_add_f32_e32 v206, v206, v84
	v_add_f32_e32 v207, v207, v85
	v_add_f32_e32 v208, v208, v86
	v_add_f32_e32 v209, v209, v87
	v_add_f32_e32 v202, v202, v72
	v_add_f32_e32 v203, v203, v73
	v_add_f32_e32 v204, v204, v74
	v_add_f32_e32 v205, v205, v75
	v_add_f32_e32 v206, v206, v76
	v_add_f32_e32 v207, v207, v77
	v_add_f32_e32 v208, v208, v78
	v_add_f32_e32 v209, v209, v79
	v_add_f32_e32 v202, v202, v64
	v_add_f32_e32 v203, v203, v65
	v_add_f32_e32 v204, v204, v66
	v_add_f32_e32 v205, v205, v67
	v_add_f32_e32 v206, v206, v68
	v_add_f32_e32 v207, v207, v69
	v_add_f32_e32 v208, v208, v70
	v_add_f32_e32 v209, v209, v71
	v_add_f32_e32 v202, v202, v56
	v_add_f32_e32 v203, v203, v57
	v_add_f32_e32 v204, v204, v58
	v_add_f32_e32 v205, v205, v59
	v_add_f32_e32 v206, v206, v60
	v_add_f32_e32 v207, v207, v61
	v_add_f32_e32 v208, v208, v62
	v_add_f32_e32 v209, v209, v63
	v_add_f32_e32 v202, v202, v48
	v_add_f32_e32 v203, v203, v49
	v_add_f32_e32 v204, v204, v50
	v_add_f32_e32 v205, v205, v51
	v_add_f32_e32 v206, v206, v52
	v_add_f32_e32 v207, v207, v53
	v_add_f32_e32 v208, v208, v54
	v_add_f32_e32 v209, v209, v55
	v_add_f32_e32 v202, v202, v40
	v_add_f32_e32 v203, v203, v41
	v_add_f32_e32 v204, v204, v42
	v_add_f32_e32 v205, v205, v43
	v_add_f32_e32 v206, v206, v44
	v_add_f32_e32 v207, v207, v45
	v_add_f32_e32 v208, v208, v46
	v_add_f32_e32 v209, v209, v47
	v_add_f32_e32 v202, v202, v32
	v_add_f32_e32 v203, v203, v33
	v_add_f32_e32 v204, v204, v34
	v_add_f32_e32 v205, v205, v35
	v_add_f32_e32 v206, v206, v36
	v_add_f32_e32 v207, v207, v37
	v_add_f32_e32 v208, v208, v38
	v_add_f32_e32 v209, v209, v39
	s_mov_b64 exec, -1
	v_fma_f32 v202, v202, v186, -v24
	v_fma_f32 v203, v203, v186, -v25
	v_add_f32_dpp v232, v232, v232 quad_perm:[1,0,3,2] row_mask:0xf bank_mask:0xf
	v_add_f32_dpp v233, v233, v233 quad_perm:[1,0,3,2] row_mask:0xf bank_mask:0xf
	v_fma_f32 v204, v204, v186, -v26
	v_fma_f32 v205, v205, v186, -v27
	v_add_f32_dpp v232, v232, v232 quad_perm:[2,3,0,1] row_mask:0xf bank_mask:0xf
	v_add_f32_dpp v233, v233, v233 quad_perm:[2,3,0,1] row_mask:0xf bank_mask:0xf
	v_fma_f32 v206, v206, v186, -v28
	v_fma_f32 v207, v207, v186, -v29
	v_add_f32_dpp v232, v232, v232 row_half_mirror row_mask:0xf bank_mask:0xf
	v_add_f32_dpp v233, v233, v233 row_half_mirror row_mask:0xf bank_mask:0xf
	v_fma_f32 v208, v208, v186, -v30
	v_fma_f32 v209, v209, v186, -v31
	v_add_f32_dpp v232, v232, v232 row_mirror row_mask:0xf bank_mask:0xf
	v_add_f32_dpp v233, v233, v233 row_mirror row_mask:0xf bank_mask:0xf
	v_cvt_pk_bf16_f32 v228, v202, v203
	v_cvt_pk_bf16_f32 v229, v204, v205
	v_mov_b32_e32 v234, v232
	v_mov_b32_e32 v235, v233
	v_cvt_pk_bf16_f32 v230, v206, v207
	v_cvt_pk_bf16_f32 v231, v208, v209
	v_permlane16_swap_b32_e32 v232, v234
	v_permlane16_swap_b32_e32 v233, v235
	s_nop 0
	v_add_f32_e32 v232, v232, v234
	v_add_f32_e32 v233, v233, v235
	global_store_dwordx4 v156, v[228:231], s[22:23]
	global_store_dwordx2 v184, v[238:239], s[28:29]
	v_mov_b32_e32 v234, v232
	v_mov_b32_e32 v235, v233
	s_nop 1
	v_permlane32_swap_b32_e32 v232, v234
	v_permlane32_swap_b32_e32 v233, v235
	s_nop 0
	v_add_f32_e32 v232, v232, v234
	v_add_f32_e32 v233, v233, v235
	v_fma_f32 v232, v232, s58, v187
	v_fma_f32 v233, v233, s59, v187
	v_rsq_f32_e32 v236, v232
	v_rsq_f32_e32 v237, v233
	s_add_u32 s22, s22, 0x400
	s_addc_u32 s23, s23, 0
	s_add_u32 s28, s28, 0x600
	s_addc_u32 s29, s29, 0
	v_mul_f32_e32 v236, s57, v236
	v_mul_f32_e32 v210, v210, v236
	v_mul_f32_e32 v211, v211, v236
	v_mul_f32_e32 v212, v212, v236
	v_mul_f32_e32 v213, v213, v236
	v_mul_f32_e32 v214, v214, v236
	v_mul_f32_e32 v215, v215, v236
	v_mul_f32_e32 v216, v216, v237
	v_mul_f32_e32 v217, v217, v237
	v_mul_f32_e32 v218, v218, v237
	v_mul_f32_e32 v219, v219, v237
	v_mul_f32_e32 v210, v210, v192
	v_mul_f32_e32 v211, v211, v193
	v_mul_f32_e32 v212, v212, v194
	v_mul_f32_e32 v213, v213, v195
	v_mul_f32_e32 v214, v214, v196
	v_mul_f32_e32 v215, v215, v197
	v_mul_f32_e32 v216, v216, v198
	v_mul_f32_e32 v217, v217, v199
	v_mul_f32_e32 v218, v218, v200
	v_mul_f32_e32 v219, v219, v201
	v_cvt_pk_bf16_f32 v120, v210, v211
	v_cvt_pk_bf16_f32 v121, v212, v213
	v_cvt_pk_bf16_f32 v122, v214, v215
	v_cvt_pk_bf16_f32 v123, v216, v217
	v_cvt_pk_bf16_f32 v125, v218, v219
	global_store_dword v157, v120, s[24:25]
	global_store_dword v157, v121, s[24:25] offset:256
	global_store_dword v157, v122, s[24:25] offset:512
	global_store_dword v157, v123, s[26:27]
	global_store_dword v157, v125, s[26:27] offset:256
	s_add_u32 s24, s24, 0x300
	s_addc_u32 s25, s25, 0
	s_add_u32 s26, s26, 0x200
	s_addc_u32 s27, s27, 0
	s_waitcnt vmcnt(24)
	v_lshlrev_b32_e32 v32, 16, v134
	v_and_b32_e32 v33, s56, v134
	v_lshlrev_b32_e32 v34, 16, v135
	v_and_b32_e32 v35, s56, v135
	v_lshlrev_b32_e32 v36, 16, v136
	v_and_b32_e32 v37, s56, v136
	v_lshlrev_b32_e32 v38, 16, v137
	v_and_b32_e32 v39, s56, v137
	v_cndmask_b32_e64 v234, v144, v146, s[52:53]
	v_cndmask_b32_e64 v235, v145, v147, s[52:53]
	v_cndmask_b32_e64 v232, v146, v144, s[52:53]
	v_cndmask_b32_e64 v233, v147, v145, s[52:53]
	v_lshlrev_b32_e32 v220, 16, v234
	v_and_b32_e32 v221, s56, v234
	v_lshlrev_b32_e32 v222, 16, v235
	v_and_b32_e32 v223, s56, v235
	v_lshlrev_b32_e32 v224, 16, v232
	v_and_b32_e32 v225, s56, v232
	v_lshlrev_b32_e32 v226, 16, v233
	v_and_b32_e32 v227, s56, v233
	v_xor_b32_e32 v234, v185, v149
	v_mul_f32_e32 v224, v224, v234
	v_fmac_f32_e32 v224, v220, v148
	v_xor_b32_e32 v234, v185, v151
	v_mul_f32_e32 v225, v225, v234
	v_fmac_f32_e32 v225, v221, v150
	v_xor_b32_e32 v234, v185, v153
	v_mul_f32_e32 v226, v226, v234
	v_fmac_f32_e32 v226, v222, v152
	v_xor_b32_e32 v234, v185, v155
	v_mul_f32_e32 v227, v227, v234
	v_fmac_f32_e32 v227, v223, v154
	v_cvt_pk_bf16_f32 v238, v224, v225
	v_cvt_pk_bf16_f32 v239, v226, v227
	v_lshlrev_b32_e32 v210, 16, v138
	v_and_b32_e32 v211, s56, v138
	v_lshlrev_b32_e32 v212, 16, v139
	v_and_b32_e32 v213, s56, v139
	v_lshlrev_b32_e32 v214, 16, v140
	v_and_b32_e32 v215, s56, v140
	v_lshlrev_b32_e32 v216, 16, v141
	v_and_b32_e32 v217, s56, v141
	v_lshlrev_b32_e32 v218, 16, v142
	v_and_b32_e32 v219, s56, v142
	global_load_dwordx4 v[134:137], v156, s[16:17]
	global_load_dword v138, v157, s[18:19]
	global_load_dword v139, v157, s[18:19] offset:256
	global_load_dword v140, v157, s[18:19] offset:512
	global_load_dword v141, v157, s[18:19] offset:768
	global_load_dword v142, v157, s[18:19] offset:1024
	global_load_dwordx2 v[144:145], v158, s[18:19]
	global_load_dwordx2 v[146:147], v158, s[18:19] offset:32
	global_load_dwordx4 v[148:151], v159, s[20:21]
	global_load_dwordx4 v[152:155], v159, s[20:21] offset:16
	s_add_u32 s16, s16, 0x400
	s_addc_u32 s17, s17, 0
	s_add_u32 s18, s18, 0x600
	s_addc_u32 s19, s19, 0
	s_add_u32 s20, s20, 0x80
	s_addc_u32 s21, s21, 0
	v_mul_f32_e32 v232, v210, v210
	v_mul_f32_e32 v233, v216, v216
	v_fmac_f32_e32 v232, v211, v211
	v_fmac_f32_e32 v233, v217, v217
	v_fmac_f32_e32 v232, v212, v212
	v_fmac_f32_e32 v233, v218, v218
	v_fmac_f32_e32 v232, v213, v213
	v_fmac_f32_e32 v233, v219, v219
	v_fmac_f32_e32 v232, v214, v214
	v_fmac_f32_e32 v232, v215, v215
	v_add_f32_e32 v202, v32, v24
	v_add_f32_e32 v203, v33, v25
	v_add_f32_e32 v204, v34, v26
	v_add_f32_e32 v205, v35, v27
	v_add_f32_e32 v206, v36, v28
	v_add_f32_e32 v207, v37, v29
	v_add_f32_e32 v208, v38, v30
	v_add_f32_e32 v209, v39, v31
	s_mov_b64 exec, s[46:47]
	v_add_f32_e32 v202, v202, v16
	v_add_f32_e32 v203, v203, v17
	v_add_f32_e32 v204, v204, v18
	v_add_f32_e32 v205, v205, v19
	v_add_f32_e32 v206, v206, v20
	v_add_f32_e32 v207, v207, v21
	v_add_f32_e32 v208, v208, v22
	v_add_f32_e32 v209, v209, v23
	v_add_f32_e32 v202, v202, v8
	v_add_f32_e32 v203, v203, v9
	v_add_f32_e32 v204, v204, v10
	v_add_f32_e32 v205, v205, v11
	v_add_f32_e32 v206, v206, v12
	v_add_f32_e32 v207, v207, v13
	v_add_f32_e32 v208, v208, v14
	v_add_f32_e32 v209, v209, v15
	s_mov_b64 exec, s[48:49]
	v_add_f32_e32 v202, v202, v0
	v_add_f32_e32 v203, v203, v1
	v_add_f32_e32 v204, v204, v2
	v_add_f32_e32 v205, v205, v3
	v_add_f32_e32 v206, v206, v4
	v_add_f32_e32 v207, v207, v5
	v_add_f32_e32 v208, v208, v6
	v_add_f32_e32 v209, v209, v7
	v_add_f32_e32 v202, v202, v126
	v_add_f32_e32 v203, v203, v127
	v_add_f32_e32 v204, v204, v128
	v_add_f32_e32 v205, v205, v129
	v_add_f32_e32 v206, v206, v130
	v_add_f32_e32 v207, v207, v131
	v_add_f32_e32 v208, v208, v132
	v_add_f32_e32 v209, v209, v133
	v_add_f32_e32 v202, v202, v112
	v_add_f32_e32 v203, v203, v113
	v_add_f32_e32 v204, v204, v114
	v_add_f32_e32 v205, v205, v115
	v_add_f32_e32 v206, v206, v116
	v_add_f32_e32 v207, v207, v117
	v_add_f32_e32 v208, v208, v118
	v_add_f32_e32 v209, v209, v119
	v_add_f32_e32 v202, v202, v104
	v_add_f32_e32 v203, v203, v105
	v_add_f32_e32 v204, v204, v106
	v_add_f32_e32 v205, v205, v107
	v_add_f32_e32 v206, v206, v108
	v_add_f32_e32 v207, v207, v109
	v_add_f32_e32 v208, v208, v110
	v_add_f32_e32 v209, v209, v111
	s_mov_b64 exec, s[50:51]
	v_add_f32_e32 v202, v202, v96
	v_add_f32_e32 v203, v203, v97
	v_add_f32_e32 v204, v204, v98
	v_add_f32_e32 v205, v205, v99
	v_add_f32_e32 v206, v206, v100
	v_add_f32_e32 v207, v207, v101
	v_add_f32_e32 v208, v208, v102
	v_add_f32_e32 v209, v209, v103
	v_add_f32_e32 v202, v202, v88
	v_add_f32_e32 v203, v203, v89
	v_add_f32_e32 v204, v204, v90
	v_add_f32_e32 v205, v205, v91
	v_add_f32_e32 v206, v206, v92
	v_add_f32_e32 v207, v207, v93
	v_add_f32_e32 v208, v208, v94
	v_add_f32_e32 v209, v209, v95
	v_add_f32_e32 v202, v202, v80
	v_add_f32_e32 v203, v203, v81
	v_add_f32_e32 v204, v204, v82
	v_add_f32_e32 v205, v205, v83
	v_add_f32_e32 v206, v206, v84
	v_add_f32_e32 v207, v207, v85
	v_add_f32_e32 v208, v208, v86
	v_add_f32_e32 v209, v209, v87
	v_add_f32_e32 v202, v202, v72
	v_add_f32_e32 v203, v203, v73
	v_add_f32_e32 v204, v204, v74
	v_add_f32_e32 v205, v205, v75
	v_add_f32_e32 v206, v206, v76
	v_add_f32_e32 v207, v207, v77
	v_add_f32_e32 v208, v208, v78
	v_add_f32_e32 v209, v209, v79
	v_add_f32_e32 v202, v202, v64
	v_add_f32_e32 v203, v203, v65
	v_add_f32_e32 v204, v204, v66
	v_add_f32_e32 v205, v205, v67
	v_add_f32_e32 v206, v206, v68
	v_add_f32_e32 v207, v207, v69
	v_add_f32_e32 v208, v208, v70
	v_add_f32_e32 v209, v209, v71
	v_add_f32_e32 v202, v202, v56
	v_add_f32_e32 v203, v203, v57
	v_add_f32_e32 v204, v204, v58
	v_add_f32_e32 v205, v205, v59
	v_add_f32_e32 v206, v206, v60
	v_add_f32_e32 v207, v207, v61
	v_add_f32_e32 v208, v208, v62
	v_add_f32_e32 v209, v209, v63
	v_add_f32_e32 v202, v202, v48
	v_add_f32_e32 v203, v203, v49
	v_add_f32_e32 v204, v204, v50
	v_add_f32_e32 v205, v205, v51
	v_add_f32_e32 v206, v206, v52
	v_add_f32_e32 v207, v207, v53
	v_add_f32_e32 v208, v208, v54
	v_add_f32_e32 v209, v209, v55
	v_add_f32_e32 v202, v202, v40
	v_add_f32_e32 v203, v203, v41
	v_add_f32_e32 v204, v204, v42
	v_add_f32_e32 v205, v205, v43
	v_add_f32_e32 v206, v206, v44
	v_add_f32_e32 v207, v207, v45
	v_add_f32_e32 v208, v208, v46
	v_add_f32_e32 v209, v209, v47
	s_mov_b64 exec, -1
	v_fma_f32 v202, v202, v186, -v32
	v_fma_f32 v203, v203, v186, -v33
	v_add_f32_dpp v232, v232, v232 quad_perm:[1,0,3,2] row_mask:0xf bank_mask:0xf
	v_add_f32_dpp v233, v233, v233 quad_perm:[1,0,3,2] row_mask:0xf bank_mask:0xf
	v_fma_f32 v204, v204, v186, -v34
	v_fma_f32 v205, v205, v186, -v35
	v_add_f32_dpp v232, v232, v232 quad_perm:[2,3,0,1] row_mask:0xf bank_mask:0xf
	v_add_f32_dpp v233, v233, v233 quad_perm:[2,3,0,1] row_mask:0xf bank_mask:0xf
	v_fma_f32 v206, v206, v186, -v36
	v_fma_f32 v207, v207, v186, -v37
	v_add_f32_dpp v232, v232, v232 row_half_mirror row_mask:0xf bank_mask:0xf
	v_add_f32_dpp v233, v233, v233 row_half_mirror row_mask:0xf bank_mask:0xf
	v_fma_f32 v208, v208, v186, -v38
	v_fma_f32 v209, v209, v186, -v39
	v_add_f32_dpp v232, v232, v232 row_mirror row_mask:0xf bank_mask:0xf
	v_add_f32_dpp v233, v233, v233 row_mirror row_mask:0xf bank_mask:0xf
	v_cvt_pk_bf16_f32 v228, v202, v203
	v_cvt_pk_bf16_f32 v229, v204, v205
	v_mov_b32_e32 v234, v232
	v_mov_b32_e32 v235, v233
	v_cvt_pk_bf16_f32 v230, v206, v207
	v_cvt_pk_bf16_f32 v231, v208, v209
	v_permlane16_swap_b32_e32 v232, v234
	v_permlane16_swap_b32_e32 v233, v235
	s_nop 0
	v_add_f32_e32 v232, v232, v234
	v_add_f32_e32 v233, v233, v235
	global_store_dwordx4 v156, v[228:231], s[22:23]
	global_store_dwordx2 v184, v[238:239], s[28:29]
	v_mov_b32_e32 v234, v232
	v_mov_b32_e32 v235, v233
	s_nop 1
	v_permlane32_swap_b32_e32 v232, v234
	v_permlane32_swap_b32_e32 v233, v235
	s_nop 0
	v_add_f32_e32 v232, v232, v234
	v_add_f32_e32 v233, v233, v235
	v_fma_f32 v232, v232, s58, v187
	v_fma_f32 v233, v233, s59, v187
	v_rsq_f32_e32 v236, v232
	v_rsq_f32_e32 v237, v233
	s_add_u32 s22, s22, 0x400
	s_addc_u32 s23, s23, 0
	s_add_u32 s28, s28, 0x600
	s_addc_u32 s29, s29, 0
	v_mul_f32_e32 v236, s57, v236
	v_mul_f32_e32 v210, v210, v236
	v_mul_f32_e32 v211, v211, v236
	v_mul_f32_e32 v212, v212, v236
	v_mul_f32_e32 v213, v213, v236
	v_mul_f32_e32 v214, v214, v236
	v_mul_f32_e32 v215, v215, v236
	v_mul_f32_e32 v216, v216, v237
	v_mul_f32_e32 v217, v217, v237
	v_mul_f32_e32 v218, v218, v237
	v_mul_f32_e32 v219, v219, v237
	v_mul_f32_e32 v210, v210, v192
	v_mul_f32_e32 v211, v211, v193
	v_mul_f32_e32 v212, v212, v194
	v_mul_f32_e32 v213, v213, v195
	v_mul_f32_e32 v214, v214, v196
	v_mul_f32_e32 v215, v215, v197
	v_mul_f32_e32 v216, v216, v198
	v_mul_f32_e32 v217, v217, v199
	v_mul_f32_e32 v218, v218, v200
	v_mul_f32_e32 v219, v219, v201
	v_cvt_pk_bf16_f32 v120, v210, v211
	v_cvt_pk_bf16_f32 v121, v212, v213
	v_cvt_pk_bf16_f32 v122, v214, v215
	v_cvt_pk_bf16_f32 v123, v216, v217
	v_cvt_pk_bf16_f32 v125, v218, v219
	global_store_dword v157, v120, s[24:25]
	global_store_dword v157, v121, s[24:25] offset:256
	global_store_dword v157, v122, s[24:25] offset:512
	global_store_dword v157, v123, s[26:27]
	global_store_dword v157, v125, s[26:27] offset:256
	s_add_u32 s24, s24, 0x300
	s_addc_u32 s25, s25, 0
	s_add_u32 s26, s26, 0x200
	s_addc_u32 s27, s27, 0
	s_waitcnt vmcnt(24)
	v_lshlrev_b32_e32 v40, 16, v162
	v_and_b32_e32 v41, s56, v162
	v_lshlrev_b32_e32 v42, 16, v163
	v_and_b32_e32 v43, s56, v163
	v_lshlrev_b32_e32 v44, 16, v164
	v_and_b32_e32 v45, s56, v164
	v_lshlrev_b32_e32 v46, 16, v165
	v_and_b32_e32 v47, s56, v165
	v_cndmask_b32_e64 v234, v172, v174, s[52:53]
	v_cndmask_b32_e64 v235, v173, v175, s[52:53]
	v_cndmask_b32_e64 v232, v174, v172, s[52:53]
	v_cndmask_b32_e64 v233, v175, v173, s[52:53]
	v_lshlrev_b32_e32 v220, 16, v234
	v_and_b32_e32 v221, s56, v234
	v_lshlrev_b32_e32 v222, 16, v235
	v_and_b32_e32 v223, s56, v235
	v_lshlrev_b32_e32 v224, 16, v232
	v_and_b32_e32 v225, s56, v232
	v_lshlrev_b32_e32 v226, 16, v233
	v_and_b32_e32 v227, s56, v233
	v_xor_b32_e32 v234, v185, v177
	v_mul_f32_e32 v224, v224, v234
	v_fmac_f32_e32 v224, v220, v176
	v_xor_b32_e32 v234, v185, v179
	v_mul_f32_e32 v225, v225, v234
	v_fmac_f32_e32 v225, v221, v178
	v_xor_b32_e32 v234, v185, v181
	v_mul_f32_e32 v226, v226, v234
	v_fmac_f32_e32 v226, v222, v180
	v_xor_b32_e32 v234, v185, v183
	v_mul_f32_e32 v227, v227, v234
	v_fmac_f32_e32 v227, v223, v182
	v_cvt_pk_bf16_f32 v238, v224, v225
	v_cvt_pk_bf16_f32 v239, v226, v227
	v_lshlrev_b32_e32 v210, 16, v166
	v_and_b32_e32 v211, s56, v166
	v_lshlrev_b32_e32 v212, 16, v167
	v_and_b32_e32 v213, s56, v167
	v_lshlrev_b32_e32 v214, 16, v168
	v_and_b32_e32 v215, s56, v168
	v_lshlrev_b32_e32 v216, 16, v169
	v_and_b32_e32 v217, s56, v169
	v_lshlrev_b32_e32 v218, 16, v170
	v_and_b32_e32 v219, s56, v170
	global_load_dwordx4 v[162:165], v156, s[16:17]
	global_load_dword v166, v157, s[18:19]
	global_load_dword v167, v157, s[18:19] offset:256
	global_load_dword v168, v157, s[18:19] offset:512
	global_load_dword v169, v157, s[18:19] offset:768
	global_load_dword v170, v157, s[18:19] offset:1024
	global_load_dwordx2 v[172:173], v158, s[18:19]
	global_load_dwordx2 v[174:175], v158, s[18:19] offset:32
	global_load_dwordx4 v[176:179], v159, s[20:21]
	global_load_dwordx4 v[180:183], v159, s[20:21] offset:16
	s_add_u32 s16, s16, 0x400
	s_addc_u32 s17, s17, 0
	s_add_u32 s18, s18, 0x600
	s_addc_u32 s19, s19, 0
	s_add_u32 s20, s20, 0x80
	s_addc_u32 s21, s21, 0
	v_mul_f32_e32 v232, v210, v210
	v_mul_f32_e32 v233, v216, v216
	v_fmac_f32_e32 v232, v211, v211
	v_fmac_f32_e32 v233, v217, v217
	v_fmac_f32_e32 v232, v212, v212
	v_fmac_f32_e32 v233, v218, v218
	v_fmac_f32_e32 v232, v213, v213
	v_fmac_f32_e32 v233, v219, v219
	v_fmac_f32_e32 v232, v214, v214
	v_fmac_f32_e32 v232, v215, v215
	v_add_f32_e32 v202, v40, v32
	v_add_f32_e32 v203, v41, v33
	v_add_f32_e32 v204, v42, v34
	v_add_f32_e32 v205, v43, v35
	v_add_f32_e32 v206, v44, v36
	v_add_f32_e32 v207, v45, v37
	v_add_f32_e32 v208, v46, v38
	v_add_f32_e32 v209, v47, v39
	s_mov_b64 exec, s[46:47]
	v_add_f32_e32 v202, v202, v24
	v_add_f32_e32 v203, v203, v25
	v_add_f32_e32 v204, v204, v26
	v_add_f32_e32 v205, v205, v27
	v_add_f32_e32 v206, v206, v28
	v_add_f32_e32 v207, v207, v29
	v_add_f32_e32 v208, v208, v30
	v_add_f32_e32 v209, v209, v31
	v_add_f32_e32 v202, v202, v16
	v_add_f32_e32 v203, v203, v17
	v_add_f32_e32 v204, v204, v18
	v_add_f32_e32 v205, v205, v19
	v_add_f32_e32 v206, v206, v20
	v_add_f32_e32 v207, v207, v21
	v_add_f32_e32 v208, v208, v22
	v_add_f32_e32 v209, v209, v23
	s_mov_b64 exec, s[48:49]
	v_add_f32_e32 v202, v202, v8
	v_add_f32_e32 v203, v203, v9
	v_add_f32_e32 v204, v204, v10
	v_add_f32_e32 v205, v205, v11
	v_add_f32_e32 v206, v206, v12
	v_add_f32_e32 v207, v207, v13
	v_add_f32_e32 v208, v208, v14
	v_add_f32_e32 v209, v209, v15
	v_add_f32_e32 v202, v202, v0
	v_add_f32_e32 v203, v203, v1
	v_add_f32_e32 v204, v204, v2
	v_add_f32_e32 v205, v205, v3
	v_add_f32_e32 v206, v206, v4
	v_add_f32_e32 v207, v207, v5
	v_add_f32_e32 v208, v208, v6
	v_add_f32_e32 v209, v209, v7
	v_add_f32_e32 v202, v202, v126
	v_add_f32_e32 v203, v203, v127
	v_add_f32_e32 v204, v204, v128
	v_add_f32_e32 v205, v205, v129
	v_add_f32_e32 v206, v206, v130
	v_add_f32_e32 v207, v207, v131
	v_add_f32_e32 v208, v208, v132
	v_add_f32_e32 v209, v209, v133
	v_add_f32_e32 v202, v202, v112
	v_add_f32_e32 v203, v203, v113
	v_add_f32_e32 v204, v204, v114
	v_add_f32_e32 v205, v205, v115
	v_add_f32_e32 v206, v206, v116
	v_add_f32_e32 v207, v207, v117
	v_add_f32_e32 v208, v208, v118
	v_add_f32_e32 v209, v209, v119
	s_mov_b64 exec, s[50:51]
	v_add_f32_e32 v202, v202, v104
	v_add_f32_e32 v203, v203, v105
	v_add_f32_e32 v204, v204, v106
	v_add_f32_e32 v205, v205, v107
	v_add_f32_e32 v206, v206, v108
	v_add_f32_e32 v207, v207, v109
	v_add_f32_e32 v208, v208, v110
	v_add_f32_e32 v209, v209, v111
	v_add_f32_e32 v202, v202, v96
	v_add_f32_e32 v203, v203, v97
	v_add_f32_e32 v204, v204, v98
	v_add_f32_e32 v205, v205, v99
	v_add_f32_e32 v206, v206, v100
	v_add_f32_e32 v207, v207, v101
	v_add_f32_e32 v208, v208, v102
	v_add_f32_e32 v209, v209, v103
	v_add_f32_e32 v202, v202, v88
	v_add_f32_e32 v203, v203, v89
	v_add_f32_e32 v204, v204, v90
	v_add_f32_e32 v205, v205, v91
	v_add_f32_e32 v206, v206, v92
	v_add_f32_e32 v207, v207, v93
	v_add_f32_e32 v208, v208, v94
	v_add_f32_e32 v209, v209, v95
	v_add_f32_e32 v202, v202, v80
	v_add_f32_e32 v203, v203, v81
	v_add_f32_e32 v204, v204, v82
	v_add_f32_e32 v205, v205, v83
	v_add_f32_e32 v206, v206, v84
	v_add_f32_e32 v207, v207, v85
	v_add_f32_e32 v208, v208, v86
	v_add_f32_e32 v209, v209, v87
	v_add_f32_e32 v202, v202, v72
	v_add_f32_e32 v203, v203, v73
	v_add_f32_e32 v204, v204, v74
	v_add_f32_e32 v205, v205, v75
	v_add_f32_e32 v206, v206, v76
	v_add_f32_e32 v207, v207, v77
	v_add_f32_e32 v208, v208, v78
	v_add_f32_e32 v209, v209, v79
	v_add_f32_e32 v202, v202, v64
	v_add_f32_e32 v203, v203, v65
	v_add_f32_e32 v204, v204, v66
	v_add_f32_e32 v205, v205, v67
	v_add_f32_e32 v206, v206, v68
	v_add_f32_e32 v207, v207, v69
	v_add_f32_e32 v208, v208, v70
	v_add_f32_e32 v209, v209, v71
	v_add_f32_e32 v202, v202, v56
	v_add_f32_e32 v203, v203, v57
	v_add_f32_e32 v204, v204, v58
	v_add_f32_e32 v205, v205, v59
	v_add_f32_e32 v206, v206, v60
	v_add_f32_e32 v207, v207, v61
	v_add_f32_e32 v208, v208, v62
	v_add_f32_e32 v209, v209, v63
	v_add_f32_e32 v202, v202, v48
	v_add_f32_e32 v203, v203, v49
	v_add_f32_e32 v204, v204, v50
	v_add_f32_e32 v205, v205, v51
	v_add_f32_e32 v206, v206, v52
	v_add_f32_e32 v207, v207, v53
	v_add_f32_e32 v208, v208, v54
	v_add_f32_e32 v209, v209, v55
	s_mov_b64 exec, -1
	v_fma_f32 v202, v202, v186, -v40
	v_fma_f32 v203, v203, v186, -v41
	v_add_f32_dpp v232, v232, v232 quad_perm:[1,0,3,2] row_mask:0xf bank_mask:0xf
	v_add_f32_dpp v233, v233, v233 quad_perm:[1,0,3,2] row_mask:0xf bank_mask:0xf
	v_fma_f32 v204, v204, v186, -v42
	v_fma_f32 v205, v205, v186, -v43
	v_add_f32_dpp v232, v232, v232 quad_perm:[2,3,0,1] row_mask:0xf bank_mask:0xf
	v_add_f32_dpp v233, v233, v233 quad_perm:[2,3,0,1] row_mask:0xf bank_mask:0xf
	v_fma_f32 v206, v206, v186, -v44
	v_fma_f32 v207, v207, v186, -v45
	v_add_f32_dpp v232, v232, v232 row_half_mirror row_mask:0xf bank_mask:0xf
	v_add_f32_dpp v233, v233, v233 row_half_mirror row_mask:0xf bank_mask:0xf
	v_fma_f32 v208, v208, v186, -v46
	v_fma_f32 v209, v209, v186, -v47
	v_add_f32_dpp v232, v232, v232 row_mirror row_mask:0xf bank_mask:0xf
	v_add_f32_dpp v233, v233, v233 row_mirror row_mask:0xf bank_mask:0xf
	v_cvt_pk_bf16_f32 v228, v202, v203
	v_cvt_pk_bf16_f32 v229, v204, v205
	v_mov_b32_e32 v234, v232
	v_mov_b32_e32 v235, v233
	v_cvt_pk_bf16_f32 v230, v206, v207
	v_cvt_pk_bf16_f32 v231, v208, v209
	v_permlane16_swap_b32_e32 v232, v234
	v_permlane16_swap_b32_e32 v233, v235
	s_nop 0
	v_add_f32_e32 v232, v232, v234
	v_add_f32_e32 v233, v233, v235
	global_store_dwordx4 v156, v[228:231], s[22:23]
	global_store_dwordx2 v184, v[238:239], s[28:29]
	v_mov_b32_e32 v234, v232
	v_mov_b32_e32 v235, v233
	s_nop 1
	v_permlane32_swap_b32_e32 v232, v234
	v_permlane32_swap_b32_e32 v233, v235
	s_nop 0
	v_add_f32_e32 v232, v232, v234
	v_add_f32_e32 v233, v233, v235
	v_fma_f32 v232, v232, s58, v187
	v_fma_f32 v233, v233, s59, v187
	v_rsq_f32_e32 v236, v232
	v_rsq_f32_e32 v237, v233
	s_add_u32 s22, s22, 0x400
	s_addc_u32 s23, s23, 0
	s_add_u32 s28, s28, 0x600
	s_addc_u32 s29, s29, 0
	v_mul_f32_e32 v236, s57, v236
	v_mul_f32_e32 v210, v210, v236
	v_mul_f32_e32 v211, v211, v236
	v_mul_f32_e32 v212, v212, v236
	v_mul_f32_e32 v213, v213, v236
	v_mul_f32_e32 v214, v214, v236
	v_mul_f32_e32 v215, v215, v236
	v_mul_f32_e32 v216, v216, v237
	v_mul_f32_e32 v217, v217, v237
	v_mul_f32_e32 v218, v218, v237
	v_mul_f32_e32 v219, v219, v237
	v_mul_f32_e32 v210, v210, v192
	v_mul_f32_e32 v211, v211, v193
	v_mul_f32_e32 v212, v212, v194
	v_mul_f32_e32 v213, v213, v195
	v_mul_f32_e32 v214, v214, v196
	v_mul_f32_e32 v215, v215, v197
	v_mul_f32_e32 v216, v216, v198
	v_mul_f32_e32 v217, v217, v199
	v_mul_f32_e32 v218, v218, v200
	v_mul_f32_e32 v219, v219, v201
	v_cvt_pk_bf16_f32 v120, v210, v211
	v_cvt_pk_bf16_f32 v121, v212, v213
	v_cvt_pk_bf16_f32 v122, v214, v215
	v_cvt_pk_bf16_f32 v123, v216, v217
	v_cvt_pk_bf16_f32 v125, v218, v219
	global_store_dword v157, v120, s[24:25]
	global_store_dword v157, v121, s[24:25] offset:256
	global_store_dword v157, v122, s[24:25] offset:512
	global_store_dword v157, v123, s[26:27]
	global_store_dword v157, v125, s[26:27] offset:256
	s_add_u32 s24, s24, 0x300
	s_addc_u32 s25, s25, 0
	s_add_u32 s26, s26, 0x200
	s_addc_u32 s27, s27, 0
	s_waitcnt vmcnt(24)
	v_lshlrev_b32_e32 v48, 16, v134
	v_and_b32_e32 v49, s56, v134
	v_lshlrev_b32_e32 v50, 16, v135
	v_and_b32_e32 v51, s56, v135
	v_lshlrev_b32_e32 v52, 16, v136
	v_and_b32_e32 v53, s56, v136
	v_lshlrev_b32_e32 v54, 16, v137
	v_and_b32_e32 v55, s56, v137
	v_cndmask_b32_e64 v234, v144, v146, s[52:53]
	v_cndmask_b32_e64 v235, v145, v147, s[52:53]
	v_cndmask_b32_e64 v232, v146, v144, s[52:53]
	v_cndmask_b32_e64 v233, v147, v145, s[52:53]
	v_lshlrev_b32_e32 v220, 16, v234
	v_and_b32_e32 v221, s56, v234
	v_lshlrev_b32_e32 v222, 16, v235
	v_and_b32_e32 v223, s56, v235
	v_lshlrev_b32_e32 v224, 16, v232
	v_and_b32_e32 v225, s56, v232
	v_lshlrev_b32_e32 v226, 16, v233
	v_and_b32_e32 v227, s56, v233
	v_xor_b32_e32 v234, v185, v149
	v_mul_f32_e32 v224, v224, v234
	v_fmac_f32_e32 v224, v220, v148
	v_xor_b32_e32 v234, v185, v151
	v_mul_f32_e32 v225, v225, v234
	v_fmac_f32_e32 v225, v221, v150
	v_xor_b32_e32 v234, v185, v153
	v_mul_f32_e32 v226, v226, v234
	v_fmac_f32_e32 v226, v222, v152
	v_xor_b32_e32 v234, v185, v155
	v_mul_f32_e32 v227, v227, v234
	v_fmac_f32_e32 v227, v223, v154
	v_cvt_pk_bf16_f32 v238, v224, v225
	v_cvt_pk_bf16_f32 v239, v226, v227
	v_lshlrev_b32_e32 v210, 16, v138
	v_and_b32_e32 v211, s56, v138
	v_lshlrev_b32_e32 v212, 16, v139
	v_and_b32_e32 v213, s56, v139
	v_lshlrev_b32_e32 v214, 16, v140
	v_and_b32_e32 v215, s56, v140
	v_lshlrev_b32_e32 v216, 16, v141
	v_and_b32_e32 v217, s56, v141
	v_lshlrev_b32_e32 v218, 16, v142
	v_and_b32_e32 v219, s56, v142
	global_load_dwordx4 v[134:137], v156, s[16:17]
	global_load_dword v138, v157, s[18:19]
	global_load_dword v139, v157, s[18:19] offset:256
	global_load_dword v140, v157, s[18:19] offset:512
	global_load_dword v141, v157, s[18:19] offset:768
	global_load_dword v142, v157, s[18:19] offset:1024
	global_load_dwordx2 v[144:145], v158, s[18:19]
	global_load_dwordx2 v[146:147], v158, s[18:19] offset:32
	global_load_dwordx4 v[148:151], v159, s[20:21]
	global_load_dwordx4 v[152:155], v159, s[20:21] offset:16
	s_add_u32 s16, s16, 0x400
	s_addc_u32 s17, s17, 0
	s_add_u32 s18, s18, 0x600
	s_addc_u32 s19, s19, 0
	s_add_u32 s20, s20, 0x80
	s_addc_u32 s21, s21, 0
	v_mul_f32_e32 v232, v210, v210
	v_mul_f32_e32 v233, v216, v216
	v_fmac_f32_e32 v232, v211, v211
	v_fmac_f32_e32 v233, v217, v217
	v_fmac_f32_e32 v232, v212, v212
	v_fmac_f32_e32 v233, v218, v218
	v_fmac_f32_e32 v232, v213, v213
	v_fmac_f32_e32 v233, v219, v219
	v_fmac_f32_e32 v232, v214, v214
	v_fmac_f32_e32 v232, v215, v215
	v_add_f32_e32 v202, v48, v40
	v_add_f32_e32 v203, v49, v41
	v_add_f32_e32 v204, v50, v42
	v_add_f32_e32 v205, v51, v43
	v_add_f32_e32 v206, v52, v44
	v_add_f32_e32 v207, v53, v45
	v_add_f32_e32 v208, v54, v46
	v_add_f32_e32 v209, v55, v47
	s_mov_b64 exec, s[46:47]
	v_add_f32_e32 v202, v202, v32
	v_add_f32_e32 v203, v203, v33
	v_add_f32_e32 v204, v204, v34
	v_add_f32_e32 v205, v205, v35
	v_add_f32_e32 v206, v206, v36
	v_add_f32_e32 v207, v207, v37
	v_add_f32_e32 v208, v208, v38
	v_add_f32_e32 v209, v209, v39
	v_add_f32_e32 v202, v202, v24
	v_add_f32_e32 v203, v203, v25
	v_add_f32_e32 v204, v204, v26
	v_add_f32_e32 v205, v205, v27
	v_add_f32_e32 v206, v206, v28
	v_add_f32_e32 v207, v207, v29
	v_add_f32_e32 v208, v208, v30
	v_add_f32_e32 v209, v209, v31
	s_mov_b64 exec, s[48:49]
	v_add_f32_e32 v202, v202, v16
	v_add_f32_e32 v203, v203, v17
	v_add_f32_e32 v204, v204, v18
	v_add_f32_e32 v205, v205, v19
	v_add_f32_e32 v206, v206, v20
	v_add_f32_e32 v207, v207, v21
	v_add_f32_e32 v208, v208, v22
	v_add_f32_e32 v209, v209, v23
	v_add_f32_e32 v202, v202, v8
	v_add_f32_e32 v203, v203, v9
	v_add_f32_e32 v204, v204, v10
	v_add_f32_e32 v205, v205, v11
	v_add_f32_e32 v206, v206, v12
	v_add_f32_e32 v207, v207, v13
	v_add_f32_e32 v208, v208, v14
	v_add_f32_e32 v209, v209, v15
	v_add_f32_e32 v202, v202, v0
	v_add_f32_e32 v203, v203, v1
	v_add_f32_e32 v204, v204, v2
	v_add_f32_e32 v205, v205, v3
	v_add_f32_e32 v206, v206, v4
	v_add_f32_e32 v207, v207, v5
	v_add_f32_e32 v208, v208, v6
	v_add_f32_e32 v209, v209, v7
	v_add_f32_e32 v202, v202, v126
	v_add_f32_e32 v203, v203, v127
	v_add_f32_e32 v204, v204, v128
	v_add_f32_e32 v205, v205, v129
	v_add_f32_e32 v206, v206, v130
	v_add_f32_e32 v207, v207, v131
	v_add_f32_e32 v208, v208, v132
	v_add_f32_e32 v209, v209, v133
	s_mov_b64 exec, s[50:51]
	v_add_f32_e32 v202, v202, v112
	v_add_f32_e32 v203, v203, v113
	v_add_f32_e32 v204, v204, v114
	v_add_f32_e32 v205, v205, v115
	v_add_f32_e32 v206, v206, v116
	v_add_f32_e32 v207, v207, v117
	v_add_f32_e32 v208, v208, v118
	v_add_f32_e32 v209, v209, v119
	v_add_f32_e32 v202, v202, v104
	v_add_f32_e32 v203, v203, v105
	v_add_f32_e32 v204, v204, v106
	v_add_f32_e32 v205, v205, v107
	v_add_f32_e32 v206, v206, v108
	v_add_f32_e32 v207, v207, v109
	v_add_f32_e32 v208, v208, v110
	v_add_f32_e32 v209, v209, v111
	v_add_f32_e32 v202, v202, v96
	v_add_f32_e32 v203, v203, v97
	v_add_f32_e32 v204, v204, v98
	v_add_f32_e32 v205, v205, v99
	v_add_f32_e32 v206, v206, v100
	v_add_f32_e32 v207, v207, v101
	v_add_f32_e32 v208, v208, v102
	v_add_f32_e32 v209, v209, v103
	v_add_f32_e32 v202, v202, v88
	v_add_f32_e32 v203, v203, v89
	v_add_f32_e32 v204, v204, v90
	v_add_f32_e32 v205, v205, v91
	v_add_f32_e32 v206, v206, v92
	v_add_f32_e32 v207, v207, v93
	v_add_f32_e32 v208, v208, v94
	v_add_f32_e32 v209, v209, v95
	v_add_f32_e32 v202, v202, v80
	v_add_f32_e32 v203, v203, v81
	v_add_f32_e32 v204, v204, v82
	v_add_f32_e32 v205, v205, v83
	v_add_f32_e32 v206, v206, v84
	v_add_f32_e32 v207, v207, v85
	v_add_f32_e32 v208, v208, v86
	v_add_f32_e32 v209, v209, v87
	v_add_f32_e32 v202, v202, v72
	v_add_f32_e32 v203, v203, v73
	v_add_f32_e32 v204, v204, v74
	v_add_f32_e32 v205, v205, v75
	v_add_f32_e32 v206, v206, v76
	v_add_f32_e32 v207, v207, v77
	v_add_f32_e32 v208, v208, v78
	v_add_f32_e32 v209, v209, v79
	v_add_f32_e32 v202, v202, v64
	v_add_f32_e32 v203, v203, v65
	v_add_f32_e32 v204, v204, v66
	v_add_f32_e32 v205, v205, v67
	v_add_f32_e32 v206, v206, v68
	v_add_f32_e32 v207, v207, v69
	v_add_f32_e32 v208, v208, v70
	v_add_f32_e32 v209, v209, v71
	v_add_f32_e32 v202, v202, v56
	v_add_f32_e32 v203, v203, v57
	v_add_f32_e32 v204, v204, v58
	v_add_f32_e32 v205, v205, v59
	v_add_f32_e32 v206, v206, v60
	v_add_f32_e32 v207, v207, v61
	v_add_f32_e32 v208, v208, v62
	v_add_f32_e32 v209, v209, v63
	s_mov_b64 exec, -1
	v_fma_f32 v202, v202, v186, -v48
	v_fma_f32 v203, v203, v186, -v49
	v_add_f32_dpp v232, v232, v232 quad_perm:[1,0,3,2] row_mask:0xf bank_mask:0xf
	v_add_f32_dpp v233, v233, v233 quad_perm:[1,0,3,2] row_mask:0xf bank_mask:0xf
	v_fma_f32 v204, v204, v186, -v50
	v_fma_f32 v205, v205, v186, -v51
	v_add_f32_dpp v232, v232, v232 quad_perm:[2,3,0,1] row_mask:0xf bank_mask:0xf
	v_add_f32_dpp v233, v233, v233 quad_perm:[2,3,0,1] row_mask:0xf bank_mask:0xf
	v_fma_f32 v206, v206, v186, -v52
	v_fma_f32 v207, v207, v186, -v53
	v_add_f32_dpp v232, v232, v232 row_half_mirror row_mask:0xf bank_mask:0xf
	v_add_f32_dpp v233, v233, v233 row_half_mirror row_mask:0xf bank_mask:0xf
	v_fma_f32 v208, v208, v186, -v54
	v_fma_f32 v209, v209, v186, -v55
	v_add_f32_dpp v232, v232, v232 row_mirror row_mask:0xf bank_mask:0xf
	v_add_f32_dpp v233, v233, v233 row_mirror row_mask:0xf bank_mask:0xf
	v_cvt_pk_bf16_f32 v228, v202, v203
	v_cvt_pk_bf16_f32 v229, v204, v205
	v_mov_b32_e32 v234, v232
	v_mov_b32_e32 v235, v233
	v_cvt_pk_bf16_f32 v230, v206, v207
	v_cvt_pk_bf16_f32 v231, v208, v209
	v_permlane16_swap_b32_e32 v232, v234
	v_permlane16_swap_b32_e32 v233, v235
	s_nop 0
	v_add_f32_e32 v232, v232, v234
	v_add_f32_e32 v233, v233, v235
	global_store_dwordx4 v156, v[228:231], s[22:23]
	global_store_dwordx2 v184, v[238:239], s[28:29]
	v_mov_b32_e32 v234, v232
	v_mov_b32_e32 v235, v233
	s_nop 1
	v_permlane32_swap_b32_e32 v232, v234
	v_permlane32_swap_b32_e32 v233, v235
	s_nop 0
	v_add_f32_e32 v232, v232, v234
	v_add_f32_e32 v233, v233, v235
	v_fma_f32 v232, v232, s58, v187
	v_fma_f32 v233, v233, s59, v187
	v_rsq_f32_e32 v236, v232
	v_rsq_f32_e32 v237, v233
	s_add_u32 s22, s22, 0x400
	s_addc_u32 s23, s23, 0
	s_add_u32 s28, s28, 0x600
	s_addc_u32 s29, s29, 0
	v_mul_f32_e32 v236, s57, v236
	v_mul_f32_e32 v210, v210, v236
	v_mul_f32_e32 v211, v211, v236
	v_mul_f32_e32 v212, v212, v236
	v_mul_f32_e32 v213, v213, v236
	v_mul_f32_e32 v214, v214, v236
	v_mul_f32_e32 v215, v215, v236
	v_mul_f32_e32 v216, v216, v237
	v_mul_f32_e32 v217, v217, v237
	v_mul_f32_e32 v218, v218, v237
	v_mul_f32_e32 v219, v219, v237
	v_mul_f32_e32 v210, v210, v192
	v_mul_f32_e32 v211, v211, v193
	v_mul_f32_e32 v212, v212, v194
	v_mul_f32_e32 v213, v213, v195
	v_mul_f32_e32 v214, v214, v196
	v_mul_f32_e32 v215, v215, v197
	v_mul_f32_e32 v216, v216, v198
	v_mul_f32_e32 v217, v217, v199
	v_mul_f32_e32 v218, v218, v200
	v_mul_f32_e32 v219, v219, v201
	v_cvt_pk_bf16_f32 v120, v210, v211
	v_cvt_pk_bf16_f32 v121, v212, v213
	v_cvt_pk_bf16_f32 v122, v214, v215
	v_cvt_pk_bf16_f32 v123, v216, v217
	v_cvt_pk_bf16_f32 v125, v218, v219
	global_store_dword v157, v120, s[24:25]
	global_store_dword v157, v121, s[24:25] offset:256
	global_store_dword v157, v122, s[24:25] offset:512
	global_store_dword v157, v123, s[26:27]
	global_store_dword v157, v125, s[26:27] offset:256
	s_add_u32 s24, s24, 0x300
	s_addc_u32 s25, s25, 0
	s_add_u32 s26, s26, 0x200
	s_addc_u32 s27, s27, 0
	s_waitcnt vmcnt(24)
	v_lshlrev_b32_e32 v56, 16, v162
	v_and_b32_e32 v57, s56, v162
	v_lshlrev_b32_e32 v58, 16, v163
	v_and_b32_e32 v59, s56, v163
	v_lshlrev_b32_e32 v60, 16, v164
	v_and_b32_e32 v61, s56, v164
	v_lshlrev_b32_e32 v62, 16, v165
	v_and_b32_e32 v63, s56, v165
	v_cndmask_b32_e64 v234, v172, v174, s[52:53]
	v_cndmask_b32_e64 v235, v173, v175, s[52:53]
	v_cndmask_b32_e64 v232, v174, v172, s[52:53]
	v_cndmask_b32_e64 v233, v175, v173, s[52:53]
	v_lshlrev_b32_e32 v220, 16, v234
	v_and_b32_e32 v221, s56, v234
	v_lshlrev_b32_e32 v222, 16, v235
	v_and_b32_e32 v223, s56, v235
	v_lshlrev_b32_e32 v224, 16, v232
	v_and_b32_e32 v225, s56, v232
	v_lshlrev_b32_e32 v226, 16, v233
	v_and_b32_e32 v227, s56, v233
	v_xor_b32_e32 v234, v185, v177
	v_mul_f32_e32 v224, v224, v234
	v_fmac_f32_e32 v224, v220, v176
	v_xor_b32_e32 v234, v185, v179
	v_mul_f32_e32 v225, v225, v234
	v_fmac_f32_e32 v225, v221, v178
	v_xor_b32_e32 v234, v185, v181
	v_mul_f32_e32 v226, v226, v234
	v_fmac_f32_e32 v226, v222, v180
	v_xor_b32_e32 v234, v185, v183
	v_mul_f32_e32 v227, v227, v234
	v_fmac_f32_e32 v227, v223, v182
	v_cvt_pk_bf16_f32 v238, v224, v225
	v_cvt_pk_bf16_f32 v239, v226, v227
	v_lshlrev_b32_e32 v210, 16, v166
	v_and_b32_e32 v211, s56, v166
	v_lshlrev_b32_e32 v212, 16, v167
	v_and_b32_e32 v213, s56, v167
	v_lshlrev_b32_e32 v214, 16, v168
	v_and_b32_e32 v215, s56, v168
	v_lshlrev_b32_e32 v216, 16, v169
	v_and_b32_e32 v217, s56, v169
	v_lshlrev_b32_e32 v218, 16, v170
	v_and_b32_e32 v219, s56, v170
	global_load_dwordx4 v[162:165], v156, s[16:17]
	global_load_dword v166, v157, s[18:19]
	global_load_dword v167, v157, s[18:19] offset:256
	global_load_dword v168, v157, s[18:19] offset:512
	global_load_dword v169, v157, s[18:19] offset:768
	global_load_dword v170, v157, s[18:19] offset:1024
	global_load_dwordx2 v[172:173], v158, s[18:19]
	global_load_dwordx2 v[174:175], v158, s[18:19] offset:32
	global_load_dwordx4 v[176:179], v159, s[20:21]
	global_load_dwordx4 v[180:183], v159, s[20:21] offset:16
	s_add_u32 s16, s16, 0x400
	s_addc_u32 s17, s17, 0
	s_add_u32 s18, s18, 0x600
	s_addc_u32 s19, s19, 0
	s_add_u32 s20, s20, 0x80
	s_addc_u32 s21, s21, 0
	v_mul_f32_e32 v232, v210, v210
	v_mul_f32_e32 v233, v216, v216
	v_fmac_f32_e32 v232, v211, v211
	v_fmac_f32_e32 v233, v217, v217
	v_fmac_f32_e32 v232, v212, v212
	v_fmac_f32_e32 v233, v218, v218
	v_fmac_f32_e32 v232, v213, v213
	v_fmac_f32_e32 v233, v219, v219
	v_fmac_f32_e32 v232, v214, v214
	v_fmac_f32_e32 v232, v215, v215
	v_add_f32_e32 v202, v56, v48
	v_add_f32_e32 v203, v57, v49
	v_add_f32_e32 v204, v58, v50
	v_add_f32_e32 v205, v59, v51
	v_add_f32_e32 v206, v60, v52
	v_add_f32_e32 v207, v61, v53
	v_add_f32_e32 v208, v62, v54
	v_add_f32_e32 v209, v63, v55
	s_mov_b64 exec, s[46:47]
	v_add_f32_e32 v202, v202, v40
	v_add_f32_e32 v203, v203, v41
	v_add_f32_e32 v204, v204, v42
	v_add_f32_e32 v205, v205, v43
	v_add_f32_e32 v206, v206, v44
	v_add_f32_e32 v207, v207, v45
	v_add_f32_e32 v208, v208, v46
	v_add_f32_e32 v209, v209, v47
	v_add_f32_e32 v202, v202, v32
	v_add_f32_e32 v203, v203, v33
	v_add_f32_e32 v204, v204, v34
	v_add_f32_e32 v205, v205, v35
	v_add_f32_e32 v206, v206, v36
	v_add_f32_e32 v207, v207, v37
	v_add_f32_e32 v208, v208, v38
	v_add_f32_e32 v209, v209, v39
	s_mov_b64 exec, s[48:49]
	v_add_f32_e32 v202, v202, v24
	v_add_f32_e32 v203, v203, v25
	v_add_f32_e32 v204, v204, v26
	v_add_f32_e32 v205, v205, v27
	v_add_f32_e32 v206, v206, v28
	v_add_f32_e32 v207, v207, v29
	v_add_f32_e32 v208, v208, v30
	v_add_f32_e32 v209, v209, v31
	v_add_f32_e32 v202, v202, v16
	v_add_f32_e32 v203, v203, v17
	v_add_f32_e32 v204, v204, v18
	v_add_f32_e32 v205, v205, v19
	v_add_f32_e32 v206, v206, v20
	v_add_f32_e32 v207, v207, v21
	v_add_f32_e32 v208, v208, v22
	v_add_f32_e32 v209, v209, v23
	v_add_f32_e32 v202, v202, v8
	v_add_f32_e32 v203, v203, v9
	v_add_f32_e32 v204, v204, v10
	v_add_f32_e32 v205, v205, v11
	v_add_f32_e32 v206, v206, v12
	v_add_f32_e32 v207, v207, v13
	v_add_f32_e32 v208, v208, v14
	v_add_f32_e32 v209, v209, v15
	v_add_f32_e32 v202, v202, v0
	v_add_f32_e32 v203, v203, v1
	v_add_f32_e32 v204, v204, v2
	v_add_f32_e32 v205, v205, v3
	v_add_f32_e32 v206, v206, v4
	v_add_f32_e32 v207, v207, v5
	v_add_f32_e32 v208, v208, v6
	v_add_f32_e32 v209, v209, v7
	s_mov_b64 exec, s[50:51]
	v_add_f32_e32 v202, v202, v126
	v_add_f32_e32 v203, v203, v127
	v_add_f32_e32 v204, v204, v128
	v_add_f32_e32 v205, v205, v129
	v_add_f32_e32 v206, v206, v130
	v_add_f32_e32 v207, v207, v131
	v_add_f32_e32 v208, v208, v132
	v_add_f32_e32 v209, v209, v133
	v_add_f32_e32 v202, v202, v112
	v_add_f32_e32 v203, v203, v113
	v_add_f32_e32 v204, v204, v114
	v_add_f32_e32 v205, v205, v115
	v_add_f32_e32 v206, v206, v116
	v_add_f32_e32 v207, v207, v117
	v_add_f32_e32 v208, v208, v118
	v_add_f32_e32 v209, v209, v119
	v_add_f32_e32 v202, v202, v104
	v_add_f32_e32 v203, v203, v105
	v_add_f32_e32 v204, v204, v106
	v_add_f32_e32 v205, v205, v107
	v_add_f32_e32 v206, v206, v108
	v_add_f32_e32 v207, v207, v109
	v_add_f32_e32 v208, v208, v110
	v_add_f32_e32 v209, v209, v111
	v_add_f32_e32 v202, v202, v96
	v_add_f32_e32 v203, v203, v97
	v_add_f32_e32 v204, v204, v98
	v_add_f32_e32 v205, v205, v99
	v_add_f32_e32 v206, v206, v100
	v_add_f32_e32 v207, v207, v101
	v_add_f32_e32 v208, v208, v102
	v_add_f32_e32 v209, v209, v103
	v_add_f32_e32 v202, v202, v88
	v_add_f32_e32 v203, v203, v89
	v_add_f32_e32 v204, v204, v90
	v_add_f32_e32 v205, v205, v91
	v_add_f32_e32 v206, v206, v92
	v_add_f32_e32 v207, v207, v93
	v_add_f32_e32 v208, v208, v94
	v_add_f32_e32 v209, v209, v95
	v_add_f32_e32 v202, v202, v80
	v_add_f32_e32 v203, v203, v81
	v_add_f32_e32 v204, v204, v82
	v_add_f32_e32 v205, v205, v83
	v_add_f32_e32 v206, v206, v84
	v_add_f32_e32 v207, v207, v85
	v_add_f32_e32 v208, v208, v86
	v_add_f32_e32 v209, v209, v87
	v_add_f32_e32 v202, v202, v72
	v_add_f32_e32 v203, v203, v73
	v_add_f32_e32 v204, v204, v74
	v_add_f32_e32 v205, v205, v75
	v_add_f32_e32 v206, v206, v76
	v_add_f32_e32 v207, v207, v77
	v_add_f32_e32 v208, v208, v78
	v_add_f32_e32 v209, v209, v79
	v_add_f32_e32 v202, v202, v64
	v_add_f32_e32 v203, v203, v65
	v_add_f32_e32 v204, v204, v66
	v_add_f32_e32 v205, v205, v67
	v_add_f32_e32 v206, v206, v68
	v_add_f32_e32 v207, v207, v69
	v_add_f32_e32 v208, v208, v70
	v_add_f32_e32 v209, v209, v71
	s_mov_b64 exec, -1
	v_fma_f32 v202, v202, v186, -v56
	v_fma_f32 v203, v203, v186, -v57
	v_add_f32_dpp v232, v232, v232 quad_perm:[1,0,3,2] row_mask:0xf bank_mask:0xf
	v_add_f32_dpp v233, v233, v233 quad_perm:[1,0,3,2] row_mask:0xf bank_mask:0xf
	v_fma_f32 v204, v204, v186, -v58
	v_fma_f32 v205, v205, v186, -v59
	v_add_f32_dpp v232, v232, v232 quad_perm:[2,3,0,1] row_mask:0xf bank_mask:0xf
	v_add_f32_dpp v233, v233, v233 quad_perm:[2,3,0,1] row_mask:0xf bank_mask:0xf
	v_fma_f32 v206, v206, v186, -v60
	v_fma_f32 v207, v207, v186, -v61
	v_add_f32_dpp v232, v232, v232 row_half_mirror row_mask:0xf bank_mask:0xf
	v_add_f32_dpp v233, v233, v233 row_half_mirror row_mask:0xf bank_mask:0xf
	v_fma_f32 v208, v208, v186, -v62
	v_fma_f32 v209, v209, v186, -v63
	v_add_f32_dpp v232, v232, v232 row_mirror row_mask:0xf bank_mask:0xf
	v_add_f32_dpp v233, v233, v233 row_mirror row_mask:0xf bank_mask:0xf
	v_cvt_pk_bf16_f32 v228, v202, v203
	v_cvt_pk_bf16_f32 v229, v204, v205
	v_mov_b32_e32 v234, v232
	v_mov_b32_e32 v235, v233
	v_cvt_pk_bf16_f32 v230, v206, v207
	v_cvt_pk_bf16_f32 v231, v208, v209
	v_permlane16_swap_b32_e32 v232, v234
	v_permlane16_swap_b32_e32 v233, v235
	s_nop 0
	v_add_f32_e32 v232, v232, v234
	v_add_f32_e32 v233, v233, v235
	global_store_dwordx4 v156, v[228:231], s[22:23]
	global_store_dwordx2 v184, v[238:239], s[28:29]
	v_mov_b32_e32 v234, v232
	v_mov_b32_e32 v235, v233
	s_nop 1
	v_permlane32_swap_b32_e32 v232, v234
	v_permlane32_swap_b32_e32 v233, v235
	s_nop 0
	v_add_f32_e32 v232, v232, v234
	v_add_f32_e32 v233, v233, v235
	v_fma_f32 v232, v232, s58, v187
	v_fma_f32 v233, v233, s59, v187
	v_rsq_f32_e32 v236, v232
	v_rsq_f32_e32 v237, v233
	s_add_u32 s22, s22, 0x400
	s_addc_u32 s23, s23, 0
	s_add_u32 s28, s28, 0x600
	s_addc_u32 s29, s29, 0
	v_mul_f32_e32 v236, s57, v236
	v_mul_f32_e32 v210, v210, v236
	v_mul_f32_e32 v211, v211, v236
	v_mul_f32_e32 v212, v212, v236
	v_mul_f32_e32 v213, v213, v236
	v_mul_f32_e32 v214, v214, v236
	v_mul_f32_e32 v215, v215, v236
	v_mul_f32_e32 v216, v216, v237
	v_mul_f32_e32 v217, v217, v237
	v_mul_f32_e32 v218, v218, v237
	v_mul_f32_e32 v219, v219, v237
	v_mul_f32_e32 v210, v210, v192
	v_mul_f32_e32 v211, v211, v193
	v_mul_f32_e32 v212, v212, v194
	v_mul_f32_e32 v213, v213, v195
	v_mul_f32_e32 v214, v214, v196
	v_mul_f32_e32 v215, v215, v197
	v_mul_f32_e32 v216, v216, v198
	v_mul_f32_e32 v217, v217, v199
	v_mul_f32_e32 v218, v218, v200
	v_mul_f32_e32 v219, v219, v201
	v_cvt_pk_bf16_f32 v120, v210, v211
	v_cvt_pk_bf16_f32 v121, v212, v213
	v_cvt_pk_bf16_f32 v122, v214, v215
	v_cvt_pk_bf16_f32 v123, v216, v217
	v_cvt_pk_bf16_f32 v125, v218, v219
	global_store_dword v157, v120, s[24:25]
	global_store_dword v157, v121, s[24:25] offset:256
	global_store_dword v157, v122, s[24:25] offset:512
	global_store_dword v157, v123, s[26:27]
	global_store_dword v157, v125, s[26:27] offset:256
	s_add_u32 s24, s24, 0x300
	s_addc_u32 s25, s25, 0
	s_add_u32 s26, s26, 0x200
	s_addc_u32 s27, s27, 0
	s_waitcnt vmcnt(24)
	v_lshlrev_b32_e32 v64, 16, v134
	v_and_b32_e32 v65, s56, v134
	v_lshlrev_b32_e32 v66, 16, v135
	v_and_b32_e32 v67, s56, v135
	v_lshlrev_b32_e32 v68, 16, v136
	v_and_b32_e32 v69, s56, v136
	v_lshlrev_b32_e32 v70, 16, v137
	v_and_b32_e32 v71, s56, v137
	v_cndmask_b32_e64 v234, v144, v146, s[52:53]
	v_cndmask_b32_e64 v235, v145, v147, s[52:53]
	v_cndmask_b32_e64 v232, v146, v144, s[52:53]
	v_cndmask_b32_e64 v233, v147, v145, s[52:53]
	v_lshlrev_b32_e32 v220, 16, v234
	v_and_b32_e32 v221, s56, v234
	v_lshlrev_b32_e32 v222, 16, v235
	v_and_b32_e32 v223, s56, v235
	v_lshlrev_b32_e32 v224, 16, v232
	v_and_b32_e32 v225, s56, v232
	v_lshlrev_b32_e32 v226, 16, v233
	v_and_b32_e32 v227, s56, v233
	v_xor_b32_e32 v234, v185, v149
	v_mul_f32_e32 v224, v224, v234
	v_fmac_f32_e32 v224, v220, v148
	v_xor_b32_e32 v234, v185, v151
	v_mul_f32_e32 v225, v225, v234
	v_fmac_f32_e32 v225, v221, v150
	v_xor_b32_e32 v234, v185, v153
	v_mul_f32_e32 v226, v226, v234
	v_fmac_f32_e32 v226, v222, v152
	v_xor_b32_e32 v234, v185, v155
	v_mul_f32_e32 v227, v227, v234
	v_fmac_f32_e32 v227, v223, v154
	v_cvt_pk_bf16_f32 v238, v224, v225
	v_cvt_pk_bf16_f32 v239, v226, v227
	v_lshlrev_b32_e32 v210, 16, v138
	v_and_b32_e32 v211, s56, v138
	v_lshlrev_b32_e32 v212, 16, v139
	v_and_b32_e32 v213, s56, v139
	v_lshlrev_b32_e32 v214, 16, v140
	v_and_b32_e32 v215, s56, v140
	v_lshlrev_b32_e32 v216, 16, v141
	v_and_b32_e32 v217, s56, v141
	v_lshlrev_b32_e32 v218, 16, v142
	v_and_b32_e32 v219, s56, v142
	global_load_dwordx4 v[134:137], v156, s[16:17]
	global_load_dword v138, v157, s[18:19]
	global_load_dword v139, v157, s[18:19] offset:256
	global_load_dword v140, v157, s[18:19] offset:512
	global_load_dword v141, v157, s[18:19] offset:768
	global_load_dword v142, v157, s[18:19] offset:1024
	global_load_dwordx2 v[144:145], v158, s[18:19]
	global_load_dwordx2 v[146:147], v158, s[18:19] offset:32
	global_load_dwordx4 v[148:151], v159, s[20:21]
	global_load_dwordx4 v[152:155], v159, s[20:21] offset:16
	s_add_u32 s16, s16, 0x400
	s_addc_u32 s17, s17, 0
	s_add_u32 s18, s18, 0x600
	s_addc_u32 s19, s19, 0
	s_add_u32 s20, s20, 0x80
	s_addc_u32 s21, s21, 0
	v_mul_f32_e32 v232, v210, v210
	v_mul_f32_e32 v233, v216, v216
	v_fmac_f32_e32 v232, v211, v211
	v_fmac_f32_e32 v233, v217, v217
	v_fmac_f32_e32 v232, v212, v212
	v_fmac_f32_e32 v233, v218, v218
	v_fmac_f32_e32 v232, v213, v213
	v_fmac_f32_e32 v233, v219, v219
	v_fmac_f32_e32 v232, v214, v214
	v_fmac_f32_e32 v232, v215, v215
	v_add_f32_e32 v202, v64, v56
	v_add_f32_e32 v203, v65, v57
	v_add_f32_e32 v204, v66, v58
	v_add_f32_e32 v205, v67, v59
	v_add_f32_e32 v206, v68, v60
	v_add_f32_e32 v207, v69, v61
	v_add_f32_e32 v208, v70, v62
	v_add_f32_e32 v209, v71, v63
	s_mov_b64 exec, s[46:47]
	v_add_f32_e32 v202, v202, v48
	v_add_f32_e32 v203, v203, v49
	v_add_f32_e32 v204, v204, v50
	v_add_f32_e32 v205, v205, v51
	v_add_f32_e32 v206, v206, v52
	v_add_f32_e32 v207, v207, v53
	v_add_f32_e32 v208, v208, v54
	v_add_f32_e32 v209, v209, v55
	v_add_f32_e32 v202, v202, v40
	v_add_f32_e32 v203, v203, v41
	v_add_f32_e32 v204, v204, v42
	v_add_f32_e32 v205, v205, v43
	v_add_f32_e32 v206, v206, v44
	v_add_f32_e32 v207, v207, v45
	v_add_f32_e32 v208, v208, v46
	v_add_f32_e32 v209, v209, v47
	s_mov_b64 exec, s[48:49]
	v_add_f32_e32 v202, v202, v32
	v_add_f32_e32 v203, v203, v33
	v_add_f32_e32 v204, v204, v34
	v_add_f32_e32 v205, v205, v35
	v_add_f32_e32 v206, v206, v36
	v_add_f32_e32 v207, v207, v37
	v_add_f32_e32 v208, v208, v38
	v_add_f32_e32 v209, v209, v39
	v_add_f32_e32 v202, v202, v24
	v_add_f32_e32 v203, v203, v25
	v_add_f32_e32 v204, v204, v26
	v_add_f32_e32 v205, v205, v27
	v_add_f32_e32 v206, v206, v28
	v_add_f32_e32 v207, v207, v29
	v_add_f32_e32 v208, v208, v30
	v_add_f32_e32 v209, v209, v31
	v_add_f32_e32 v202, v202, v16
	v_add_f32_e32 v203, v203, v17
	v_add_f32_e32 v204, v204, v18
	v_add_f32_e32 v205, v205, v19
	v_add_f32_e32 v206, v206, v20
	v_add_f32_e32 v207, v207, v21
	v_add_f32_e32 v208, v208, v22
	v_add_f32_e32 v209, v209, v23
	v_add_f32_e32 v202, v202, v8
	v_add_f32_e32 v203, v203, v9
	v_add_f32_e32 v204, v204, v10
	v_add_f32_e32 v205, v205, v11
	v_add_f32_e32 v206, v206, v12
	v_add_f32_e32 v207, v207, v13
	v_add_f32_e32 v208, v208, v14
	v_add_f32_e32 v209, v209, v15
	s_mov_b64 exec, s[50:51]
	v_add_f32_e32 v202, v202, v0
	v_add_f32_e32 v203, v203, v1
	v_add_f32_e32 v204, v204, v2
	v_add_f32_e32 v205, v205, v3
	v_add_f32_e32 v206, v206, v4
	v_add_f32_e32 v207, v207, v5
	v_add_f32_e32 v208, v208, v6
	v_add_f32_e32 v209, v209, v7
	v_add_f32_e32 v202, v202, v126
	v_add_f32_e32 v203, v203, v127
	v_add_f32_e32 v204, v204, v128
	v_add_f32_e32 v205, v205, v129
	v_add_f32_e32 v206, v206, v130
	v_add_f32_e32 v207, v207, v131
	v_add_f32_e32 v208, v208, v132
	v_add_f32_e32 v209, v209, v133
	v_add_f32_e32 v202, v202, v112
	v_add_f32_e32 v203, v203, v113
	v_add_f32_e32 v204, v204, v114
	v_add_f32_e32 v205, v205, v115
	v_add_f32_e32 v206, v206, v116
	v_add_f32_e32 v207, v207, v117
	v_add_f32_e32 v208, v208, v118
	v_add_f32_e32 v209, v209, v119
	v_add_f32_e32 v202, v202, v104
	v_add_f32_e32 v203, v203, v105
	v_add_f32_e32 v204, v204, v106
	v_add_f32_e32 v205, v205, v107
	v_add_f32_e32 v206, v206, v108
	v_add_f32_e32 v207, v207, v109
	v_add_f32_e32 v208, v208, v110
	v_add_f32_e32 v209, v209, v111
	v_add_f32_e32 v202, v202, v96
	v_add_f32_e32 v203, v203, v97
	v_add_f32_e32 v204, v204, v98
	v_add_f32_e32 v205, v205, v99
	v_add_f32_e32 v206, v206, v100
	v_add_f32_e32 v207, v207, v101
	v_add_f32_e32 v208, v208, v102
	v_add_f32_e32 v209, v209, v103
	v_add_f32_e32 v202, v202, v88
	v_add_f32_e32 v203, v203, v89
	v_add_f32_e32 v204, v204, v90
	v_add_f32_e32 v205, v205, v91
	v_add_f32_e32 v206, v206, v92
	v_add_f32_e32 v207, v207, v93
	v_add_f32_e32 v208, v208, v94
	v_add_f32_e32 v209, v209, v95
	v_add_f32_e32 v202, v202, v80
	v_add_f32_e32 v203, v203, v81
	v_add_f32_e32 v204, v204, v82
	v_add_f32_e32 v205, v205, v83
	v_add_f32_e32 v206, v206, v84
	v_add_f32_e32 v207, v207, v85
	v_add_f32_e32 v208, v208, v86
	v_add_f32_e32 v209, v209, v87
	v_add_f32_e32 v202, v202, v72
	v_add_f32_e32 v203, v203, v73
	v_add_f32_e32 v204, v204, v74
	v_add_f32_e32 v205, v205, v75
	v_add_f32_e32 v206, v206, v76
	v_add_f32_e32 v207, v207, v77
	v_add_f32_e32 v208, v208, v78
	v_add_f32_e32 v209, v209, v79
	s_mov_b64 exec, -1
	v_fma_f32 v202, v202, v186, -v64
	v_fma_f32 v203, v203, v186, -v65
	v_add_f32_dpp v232, v232, v232 quad_perm:[1,0,3,2] row_mask:0xf bank_mask:0xf
	v_add_f32_dpp v233, v233, v233 quad_perm:[1,0,3,2] row_mask:0xf bank_mask:0xf
	v_fma_f32 v204, v204, v186, -v66
	v_fma_f32 v205, v205, v186, -v67
	v_add_f32_dpp v232, v232, v232 quad_perm:[2,3,0,1] row_mask:0xf bank_mask:0xf
	v_add_f32_dpp v233, v233, v233 quad_perm:[2,3,0,1] row_mask:0xf bank_mask:0xf
	v_fma_f32 v206, v206, v186, -v68
	v_fma_f32 v207, v207, v186, -v69
	v_add_f32_dpp v232, v232, v232 row_half_mirror row_mask:0xf bank_mask:0xf
	v_add_f32_dpp v233, v233, v233 row_half_mirror row_mask:0xf bank_mask:0xf
	v_fma_f32 v208, v208, v186, -v70
	v_fma_f32 v209, v209, v186, -v71
	v_add_f32_dpp v232, v232, v232 row_mirror row_mask:0xf bank_mask:0xf
	v_add_f32_dpp v233, v233, v233 row_mirror row_mask:0xf bank_mask:0xf
	v_cvt_pk_bf16_f32 v228, v202, v203
	v_cvt_pk_bf16_f32 v229, v204, v205
	v_mov_b32_e32 v234, v232
	v_mov_b32_e32 v235, v233
	v_cvt_pk_bf16_f32 v230, v206, v207
	v_cvt_pk_bf16_f32 v231, v208, v209
	v_permlane16_swap_b32_e32 v232, v234
	v_permlane16_swap_b32_e32 v233, v235
	s_nop 0
	v_add_f32_e32 v232, v232, v234
	v_add_f32_e32 v233, v233, v235
	global_store_dwordx4 v156, v[228:231], s[22:23]
	global_store_dwordx2 v184, v[238:239], s[28:29]
	v_mov_b32_e32 v234, v232
	v_mov_b32_e32 v235, v233
	s_nop 1
	v_permlane32_swap_b32_e32 v232, v234
	v_permlane32_swap_b32_e32 v233, v235
	s_nop 0
	v_add_f32_e32 v232, v232, v234
	v_add_f32_e32 v233, v233, v235
	v_fma_f32 v232, v232, s58, v187
	v_fma_f32 v233, v233, s59, v187
	v_rsq_f32_e32 v236, v232
	v_rsq_f32_e32 v237, v233
	s_add_u32 s22, s22, 0x400
	s_addc_u32 s23, s23, 0
	s_add_u32 s28, s28, 0x600
	s_addc_u32 s29, s29, 0
	v_mul_f32_e32 v236, s57, v236
	v_mul_f32_e32 v210, v210, v236
	v_mul_f32_e32 v211, v211, v236
	v_mul_f32_e32 v212, v212, v236
	v_mul_f32_e32 v213, v213, v236
	v_mul_f32_e32 v214, v214, v236
	v_mul_f32_e32 v215, v215, v236
	v_mul_f32_e32 v216, v216, v237
	v_mul_f32_e32 v217, v217, v237
	v_mul_f32_e32 v218, v218, v237
	v_mul_f32_e32 v219, v219, v237
	v_mul_f32_e32 v210, v210, v192
	v_mul_f32_e32 v211, v211, v193
	v_mul_f32_e32 v212, v212, v194
	v_mul_f32_e32 v213, v213, v195
	v_mul_f32_e32 v214, v214, v196
	v_mul_f32_e32 v215, v215, v197
	v_mul_f32_e32 v216, v216, v198
	v_mul_f32_e32 v217, v217, v199
	v_mul_f32_e32 v218, v218, v200
	v_mul_f32_e32 v219, v219, v201
	v_cvt_pk_bf16_f32 v120, v210, v211
	v_cvt_pk_bf16_f32 v121, v212, v213
	v_cvt_pk_bf16_f32 v122, v214, v215
	v_cvt_pk_bf16_f32 v123, v216, v217
	v_cvt_pk_bf16_f32 v125, v218, v219
	global_store_dword v157, v120, s[24:25]
	global_store_dword v157, v121, s[24:25] offset:256
	global_store_dword v157, v122, s[24:25] offset:512
	global_store_dword v157, v123, s[26:27]
	global_store_dword v157, v125, s[26:27] offset:256
	s_add_u32 s24, s24, 0x300
	s_addc_u32 s25, s25, 0
	s_add_u32 s26, s26, 0x200
	s_addc_u32 s27, s27, 0
	s_waitcnt vmcnt(24)
	v_lshlrev_b32_e32 v72, 16, v162
	v_and_b32_e32 v73, s56, v162
	v_lshlrev_b32_e32 v74, 16, v163
	v_and_b32_e32 v75, s56, v163
	v_lshlrev_b32_e32 v76, 16, v164
	v_and_b32_e32 v77, s56, v164
	v_lshlrev_b32_e32 v78, 16, v165
	v_and_b32_e32 v79, s56, v165
	v_cndmask_b32_e64 v234, v172, v174, s[52:53]
	v_cndmask_b32_e64 v235, v173, v175, s[52:53]
	v_cndmask_b32_e64 v232, v174, v172, s[52:53]
	v_cndmask_b32_e64 v233, v175, v173, s[52:53]
	v_lshlrev_b32_e32 v220, 16, v234
	v_and_b32_e32 v221, s56, v234
	v_lshlrev_b32_e32 v222, 16, v235
	v_and_b32_e32 v223, s56, v235
	v_lshlrev_b32_e32 v224, 16, v232
	v_and_b32_e32 v225, s56, v232
	v_lshlrev_b32_e32 v226, 16, v233
	v_and_b32_e32 v227, s56, v233
	v_xor_b32_e32 v234, v185, v177
	v_mul_f32_e32 v224, v224, v234
	v_fmac_f32_e32 v224, v220, v176
	v_xor_b32_e32 v234, v185, v179
	v_mul_f32_e32 v225, v225, v234
	v_fmac_f32_e32 v225, v221, v178
	v_xor_b32_e32 v234, v185, v181
	v_mul_f32_e32 v226, v226, v234
	v_fmac_f32_e32 v226, v222, v180
	v_xor_b32_e32 v234, v185, v183
	v_mul_f32_e32 v227, v227, v234
	v_fmac_f32_e32 v227, v223, v182
	v_cvt_pk_bf16_f32 v238, v224, v225
	v_cvt_pk_bf16_f32 v239, v226, v227
	v_lshlrev_b32_e32 v210, 16, v166
	v_and_b32_e32 v211, s56, v166
	v_lshlrev_b32_e32 v212, 16, v167
	v_and_b32_e32 v213, s56, v167
	v_lshlrev_b32_e32 v214, 16, v168
	v_and_b32_e32 v215, s56, v168
	v_lshlrev_b32_e32 v216, 16, v169
	v_and_b32_e32 v217, s56, v169
	v_lshlrev_b32_e32 v218, 16, v170
	v_and_b32_e32 v219, s56, v170
	global_load_dwordx4 v[162:165], v156, s[16:17]
	global_load_dword v166, v157, s[18:19]
	global_load_dword v167, v157, s[18:19] offset:256
	global_load_dword v168, v157, s[18:19] offset:512
	global_load_dword v169, v157, s[18:19] offset:768
	global_load_dword v170, v157, s[18:19] offset:1024
	global_load_dwordx2 v[172:173], v158, s[18:19]
	global_load_dwordx2 v[174:175], v158, s[18:19] offset:32
	global_load_dwordx4 v[176:179], v159, s[20:21]
	global_load_dwordx4 v[180:183], v159, s[20:21] offset:16
	s_add_u32 s16, s16, 0x400
	s_addc_u32 s17, s17, 0
	s_add_u32 s18, s18, 0x600
	s_addc_u32 s19, s19, 0
	s_add_u32 s20, s20, 0x80
	s_addc_u32 s21, s21, 0
	v_mul_f32_e32 v232, v210, v210
	v_mul_f32_e32 v233, v216, v216
	v_fmac_f32_e32 v232, v211, v211
	v_fmac_f32_e32 v233, v217, v217
	v_fmac_f32_e32 v232, v212, v212
	v_fmac_f32_e32 v233, v218, v218
	v_fmac_f32_e32 v232, v213, v213
	v_fmac_f32_e32 v233, v219, v219
	v_fmac_f32_e32 v232, v214, v214
	v_fmac_f32_e32 v232, v215, v215
	v_add_f32_e32 v202, v72, v64
	v_add_f32_e32 v203, v73, v65
	v_add_f32_e32 v204, v74, v66
	v_add_f32_e32 v205, v75, v67
	v_add_f32_e32 v206, v76, v68
	v_add_f32_e32 v207, v77, v69
	v_add_f32_e32 v208, v78, v70
	v_add_f32_e32 v209, v79, v71
	s_mov_b64 exec, s[46:47]
	v_add_f32_e32 v202, v202, v56
	v_add_f32_e32 v203, v203, v57
	v_add_f32_e32 v204, v204, v58
	v_add_f32_e32 v205, v205, v59
	v_add_f32_e32 v206, v206, v60
	v_add_f32_e32 v207, v207, v61
	v_add_f32_e32 v208, v208, v62
	v_add_f32_e32 v209, v209, v63
	v_add_f32_e32 v202, v202, v48
	v_add_f32_e32 v203, v203, v49
	v_add_f32_e32 v204, v204, v50
	v_add_f32_e32 v205, v205, v51
	v_add_f32_e32 v206, v206, v52
	v_add_f32_e32 v207, v207, v53
	v_add_f32_e32 v208, v208, v54
	v_add_f32_e32 v209, v209, v55
	s_mov_b64 exec, s[48:49]
	v_add_f32_e32 v202, v202, v40
	v_add_f32_e32 v203, v203, v41
	v_add_f32_e32 v204, v204, v42
	v_add_f32_e32 v205, v205, v43
	v_add_f32_e32 v206, v206, v44
	v_add_f32_e32 v207, v207, v45
	v_add_f32_e32 v208, v208, v46
	v_add_f32_e32 v209, v209, v47
	v_add_f32_e32 v202, v202, v32
	v_add_f32_e32 v203, v203, v33
	v_add_f32_e32 v204, v204, v34
	v_add_f32_e32 v205, v205, v35
	v_add_f32_e32 v206, v206, v36
	v_add_f32_e32 v207, v207, v37
	v_add_f32_e32 v208, v208, v38
	v_add_f32_e32 v209, v209, v39
	v_add_f32_e32 v202, v202, v24
	v_add_f32_e32 v203, v203, v25
	v_add_f32_e32 v204, v204, v26
	v_add_f32_e32 v205, v205, v27
	v_add_f32_e32 v206, v206, v28
	v_add_f32_e32 v207, v207, v29
	v_add_f32_e32 v208, v208, v30
	v_add_f32_e32 v209, v209, v31
	v_add_f32_e32 v202, v202, v16
	v_add_f32_e32 v203, v203, v17
	v_add_f32_e32 v204, v204, v18
	v_add_f32_e32 v205, v205, v19
	v_add_f32_e32 v206, v206, v20
	v_add_f32_e32 v207, v207, v21
	v_add_f32_e32 v208, v208, v22
	v_add_f32_e32 v209, v209, v23
	s_mov_b64 exec, s[50:51]
	v_add_f32_e32 v202, v202, v8
	v_add_f32_e32 v203, v203, v9
	v_add_f32_e32 v204, v204, v10
	v_add_f32_e32 v205, v205, v11
	v_add_f32_e32 v206, v206, v12
	v_add_f32_e32 v207, v207, v13
	v_add_f32_e32 v208, v208, v14
	v_add_f32_e32 v209, v209, v15
	v_add_f32_e32 v202, v202, v0
	v_add_f32_e32 v203, v203, v1
	v_add_f32_e32 v204, v204, v2
	v_add_f32_e32 v205, v205, v3
	v_add_f32_e32 v206, v206, v4
	v_add_f32_e32 v207, v207, v5
	v_add_f32_e32 v208, v208, v6
	v_add_f32_e32 v209, v209, v7
	v_add_f32_e32 v202, v202, v126
	v_add_f32_e32 v203, v203, v127
	v_add_f32_e32 v204, v204, v128
	v_add_f32_e32 v205, v205, v129
	v_add_f32_e32 v206, v206, v130
	v_add_f32_e32 v207, v207, v131
	v_add_f32_e32 v208, v208, v132
	v_add_f32_e32 v209, v209, v133
	v_add_f32_e32 v202, v202, v112
	v_add_f32_e32 v203, v203, v113
	v_add_f32_e32 v204, v204, v114
	v_add_f32_e32 v205, v205, v115
	v_add_f32_e32 v206, v206, v116
	v_add_f32_e32 v207, v207, v117
	v_add_f32_e32 v208, v208, v118
	v_add_f32_e32 v209, v209, v119
	v_add_f32_e32 v202, v202, v104
	v_add_f32_e32 v203, v203, v105
	v_add_f32_e32 v204, v204, v106
	v_add_f32_e32 v205, v205, v107
	v_add_f32_e32 v206, v206, v108
	v_add_f32_e32 v207, v207, v109
	v_add_f32_e32 v208, v208, v110
	v_add_f32_e32 v209, v209, v111
	v_add_f32_e32 v202, v202, v96
	v_add_f32_e32 v203, v203, v97
	v_add_f32_e32 v204, v204, v98
	v_add_f32_e32 v205, v205, v99
	v_add_f32_e32 v206, v206, v100
	v_add_f32_e32 v207, v207, v101
	v_add_f32_e32 v208, v208, v102
	v_add_f32_e32 v209, v209, v103
	v_add_f32_e32 v202, v202, v88
	v_add_f32_e32 v203, v203, v89
	v_add_f32_e32 v204, v204, v90
	v_add_f32_e32 v205, v205, v91
	v_add_f32_e32 v206, v206, v92
	v_add_f32_e32 v207, v207, v93
	v_add_f32_e32 v208, v208, v94
	v_add_f32_e32 v209, v209, v95
	v_add_f32_e32 v202, v202, v80
	v_add_f32_e32 v203, v203, v81
	v_add_f32_e32 v204, v204, v82
	v_add_f32_e32 v205, v205, v83
	v_add_f32_e32 v206, v206, v84
	v_add_f32_e32 v207, v207, v85
	v_add_f32_e32 v208, v208, v86
	v_add_f32_e32 v209, v209, v87
	s_mov_b64 exec, -1
	v_fma_f32 v202, v202, v186, -v72
	v_fma_f32 v203, v203, v186, -v73
	v_add_f32_dpp v232, v232, v232 quad_perm:[1,0,3,2] row_mask:0xf bank_mask:0xf
	v_add_f32_dpp v233, v233, v233 quad_perm:[1,0,3,2] row_mask:0xf bank_mask:0xf
	v_fma_f32 v204, v204, v186, -v74
	v_fma_f32 v205, v205, v186, -v75
	v_add_f32_dpp v232, v232, v232 quad_perm:[2,3,0,1] row_mask:0xf bank_mask:0xf
	v_add_f32_dpp v233, v233, v233 quad_perm:[2,3,0,1] row_mask:0xf bank_mask:0xf
	v_fma_f32 v206, v206, v186, -v76
	v_fma_f32 v207, v207, v186, -v77
	v_add_f32_dpp v232, v232, v232 row_half_mirror row_mask:0xf bank_mask:0xf
	v_add_f32_dpp v233, v233, v233 row_half_mirror row_mask:0xf bank_mask:0xf
	v_fma_f32 v208, v208, v186, -v78
	v_fma_f32 v209, v209, v186, -v79
	v_add_f32_dpp v232, v232, v232 row_mirror row_mask:0xf bank_mask:0xf
	v_add_f32_dpp v233, v233, v233 row_mirror row_mask:0xf bank_mask:0xf
	v_cvt_pk_bf16_f32 v228, v202, v203
	v_cvt_pk_bf16_f32 v229, v204, v205
	v_mov_b32_e32 v234, v232
	v_mov_b32_e32 v235, v233
	v_cvt_pk_bf16_f32 v230, v206, v207
	v_cvt_pk_bf16_f32 v231, v208, v209
	v_permlane16_swap_b32_e32 v232, v234
	v_permlane16_swap_b32_e32 v233, v235
	s_nop 0
	v_add_f32_e32 v232, v232, v234
	v_add_f32_e32 v233, v233, v235
	global_store_dwordx4 v156, v[228:231], s[22:23]
	global_store_dwordx2 v184, v[238:239], s[28:29]
	v_mov_b32_e32 v234, v232
	v_mov_b32_e32 v235, v233
	s_nop 1
	v_permlane32_swap_b32_e32 v232, v234
	v_permlane32_swap_b32_e32 v233, v235
	s_nop 0
	v_add_f32_e32 v232, v232, v234
	v_add_f32_e32 v233, v233, v235
	v_fma_f32 v232, v232, s58, v187
	v_fma_f32 v233, v233, s59, v187
	v_rsq_f32_e32 v236, v232
	v_rsq_f32_e32 v237, v233
	s_add_u32 s22, s22, 0x400
	s_addc_u32 s23, s23, 0
	s_add_u32 s28, s28, 0x600
	s_addc_u32 s29, s29, 0
	v_mul_f32_e32 v236, s57, v236
	v_mul_f32_e32 v210, v210, v236
	v_mul_f32_e32 v211, v211, v236
	v_mul_f32_e32 v212, v212, v236
	v_mul_f32_e32 v213, v213, v236
	v_mul_f32_e32 v214, v214, v236
	v_mul_f32_e32 v215, v215, v236
	v_mul_f32_e32 v216, v216, v237
	v_mul_f32_e32 v217, v217, v237
	v_mul_f32_e32 v218, v218, v237
	v_mul_f32_e32 v219, v219, v237
	v_mul_f32_e32 v210, v210, v192
	v_mul_f32_e32 v211, v211, v193
	v_mul_f32_e32 v212, v212, v194
	v_mul_f32_e32 v213, v213, v195
	v_mul_f32_e32 v214, v214, v196
	v_mul_f32_e32 v215, v215, v197
	v_mul_f32_e32 v216, v216, v198
	v_mul_f32_e32 v217, v217, v199
	v_mul_f32_e32 v218, v218, v200
	v_mul_f32_e32 v219, v219, v201
	v_cvt_pk_bf16_f32 v120, v210, v211
	v_cvt_pk_bf16_f32 v121, v212, v213
	v_cvt_pk_bf16_f32 v122, v214, v215
	v_cvt_pk_bf16_f32 v123, v216, v217
	v_cvt_pk_bf16_f32 v125, v218, v219
	global_store_dword v157, v120, s[24:25]
	global_store_dword v157, v121, s[24:25] offset:256
	global_store_dword v157, v122, s[24:25] offset:512
	global_store_dword v157, v123, s[26:27]
	global_store_dword v157, v125, s[26:27] offset:256
	s_add_u32 s24, s24, 0x300
	s_addc_u32 s25, s25, 0
	s_add_u32 s26, s26, 0x200
	s_addc_u32 s27, s27, 0
	s_waitcnt vmcnt(24)
	v_lshlrev_b32_e32 v80, 16, v134
	v_and_b32_e32 v81, s56, v134
	v_lshlrev_b32_e32 v82, 16, v135
	v_and_b32_e32 v83, s56, v135
	v_lshlrev_b32_e32 v84, 16, v136
	v_and_b32_e32 v85, s56, v136
	v_lshlrev_b32_e32 v86, 16, v137
	v_and_b32_e32 v87, s56, v137
	v_cndmask_b32_e64 v234, v144, v146, s[52:53]
	v_cndmask_b32_e64 v235, v145, v147, s[52:53]
	v_cndmask_b32_e64 v232, v146, v144, s[52:53]
	v_cndmask_b32_e64 v233, v147, v145, s[52:53]
	v_lshlrev_b32_e32 v220, 16, v234
	v_and_b32_e32 v221, s56, v234
	v_lshlrev_b32_e32 v222, 16, v235
	v_and_b32_e32 v223, s56, v235
	v_lshlrev_b32_e32 v224, 16, v232
	v_and_b32_e32 v225, s56, v232
	v_lshlrev_b32_e32 v226, 16, v233
	v_and_b32_e32 v227, s56, v233
	v_xor_b32_e32 v234, v185, v149
	v_mul_f32_e32 v224, v224, v234
	v_fmac_f32_e32 v224, v220, v148
	v_xor_b32_e32 v234, v185, v151
	v_mul_f32_e32 v225, v225, v234
	v_fmac_f32_e32 v225, v221, v150
	v_xor_b32_e32 v234, v185, v153
	v_mul_f32_e32 v226, v226, v234
	v_fmac_f32_e32 v226, v222, v152
	v_xor_b32_e32 v234, v185, v155
	v_mul_f32_e32 v227, v227, v234
	v_fmac_f32_e32 v227, v223, v154
	v_cvt_pk_bf16_f32 v238, v224, v225
	v_cvt_pk_bf16_f32 v239, v226, v227
	v_lshlrev_b32_e32 v210, 16, v138
	v_and_b32_e32 v211, s56, v138
	v_lshlrev_b32_e32 v212, 16, v139
	v_and_b32_e32 v213, s56, v139
	v_lshlrev_b32_e32 v214, 16, v140
	v_and_b32_e32 v215, s56, v140
	v_lshlrev_b32_e32 v216, 16, v141
	v_and_b32_e32 v217, s56, v141
	v_lshlrev_b32_e32 v218, 16, v142
	v_and_b32_e32 v219, s56, v142
	global_load_dwordx4 v[134:137], v156, s[16:17]
	global_load_dword v138, v157, s[18:19]
	global_load_dword v139, v157, s[18:19] offset:256
	global_load_dword v140, v157, s[18:19] offset:512
	global_load_dword v141, v157, s[18:19] offset:768
	global_load_dword v142, v157, s[18:19] offset:1024
	global_load_dwordx2 v[144:145], v158, s[18:19]
	global_load_dwordx2 v[146:147], v158, s[18:19] offset:32
	global_load_dwordx4 v[148:151], v159, s[20:21]
	global_load_dwordx4 v[152:155], v159, s[20:21] offset:16
	s_add_u32 s16, s16, 0x400
	s_addc_u32 s17, s17, 0
	s_add_u32 s18, s18, 0x600
	s_addc_u32 s19, s19, 0
	s_add_u32 s20, s20, 0x80
	s_addc_u32 s21, s21, 0
	v_mul_f32_e32 v232, v210, v210
	v_mul_f32_e32 v233, v216, v216
	v_fmac_f32_e32 v232, v211, v211
	v_fmac_f32_e32 v233, v217, v217
	v_fmac_f32_e32 v232, v212, v212
	v_fmac_f32_e32 v233, v218, v218
	v_fmac_f32_e32 v232, v213, v213
	v_fmac_f32_e32 v233, v219, v219
	v_fmac_f32_e32 v232, v214, v214
	v_fmac_f32_e32 v232, v215, v215
	v_add_f32_e32 v202, v80, v72
	v_add_f32_e32 v203, v81, v73
	v_add_f32_e32 v204, v82, v74
	v_add_f32_e32 v205, v83, v75
	v_add_f32_e32 v206, v84, v76
	v_add_f32_e32 v207, v85, v77
	v_add_f32_e32 v208, v86, v78
	v_add_f32_e32 v209, v87, v79
	s_mov_b64 exec, s[46:47]
	v_add_f32_e32 v202, v202, v64
	v_add_f32_e32 v203, v203, v65
	v_add_f32_e32 v204, v204, v66
	v_add_f32_e32 v205, v205, v67
	v_add_f32_e32 v206, v206, v68
	v_add_f32_e32 v207, v207, v69
	v_add_f32_e32 v208, v208, v70
	v_add_f32_e32 v209, v209, v71
	v_add_f32_e32 v202, v202, v56
	v_add_f32_e32 v203, v203, v57
	v_add_f32_e32 v204, v204, v58
	v_add_f32_e32 v205, v205, v59
	v_add_f32_e32 v206, v206, v60
	v_add_f32_e32 v207, v207, v61
	v_add_f32_e32 v208, v208, v62
	v_add_f32_e32 v209, v209, v63
	s_mov_b64 exec, s[48:49]
	v_add_f32_e32 v202, v202, v48
	v_add_f32_e32 v203, v203, v49
	v_add_f32_e32 v204, v204, v50
	v_add_f32_e32 v205, v205, v51
	v_add_f32_e32 v206, v206, v52
	v_add_f32_e32 v207, v207, v53
	v_add_f32_e32 v208, v208, v54
	v_add_f32_e32 v209, v209, v55
	v_add_f32_e32 v202, v202, v40
	v_add_f32_e32 v203, v203, v41
	v_add_f32_e32 v204, v204, v42
	v_add_f32_e32 v205, v205, v43
	v_add_f32_e32 v206, v206, v44
	v_add_f32_e32 v207, v207, v45
	v_add_f32_e32 v208, v208, v46
	v_add_f32_e32 v209, v209, v47
	v_add_f32_e32 v202, v202, v32
	v_add_f32_e32 v203, v203, v33
	v_add_f32_e32 v204, v204, v34
	v_add_f32_e32 v205, v205, v35
	v_add_f32_e32 v206, v206, v36
	v_add_f32_e32 v207, v207, v37
	v_add_f32_e32 v208, v208, v38
	v_add_f32_e32 v209, v209, v39
	v_add_f32_e32 v202, v202, v24
	v_add_f32_e32 v203, v203, v25
	v_add_f32_e32 v204, v204, v26
	v_add_f32_e32 v205, v205, v27
	v_add_f32_e32 v206, v206, v28
	v_add_f32_e32 v207, v207, v29
	v_add_f32_e32 v208, v208, v30
	v_add_f32_e32 v209, v209, v31
	s_mov_b64 exec, s[50:51]
	v_add_f32_e32 v202, v202, v16
	v_add_f32_e32 v203, v203, v17
	v_add_f32_e32 v204, v204, v18
	v_add_f32_e32 v205, v205, v19
	v_add_f32_e32 v206, v206, v20
	v_add_f32_e32 v207, v207, v21
	v_add_f32_e32 v208, v208, v22
	v_add_f32_e32 v209, v209, v23
	v_add_f32_e32 v202, v202, v8
	v_add_f32_e32 v203, v203, v9
	v_add_f32_e32 v204, v204, v10
	v_add_f32_e32 v205, v205, v11
	v_add_f32_e32 v206, v206, v12
	v_add_f32_e32 v207, v207, v13
	v_add_f32_e32 v208, v208, v14
	v_add_f32_e32 v209, v209, v15
	v_add_f32_e32 v202, v202, v0
	v_add_f32_e32 v203, v203, v1
	v_add_f32_e32 v204, v204, v2
	v_add_f32_e32 v205, v205, v3
	v_add_f32_e32 v206, v206, v4
	v_add_f32_e32 v207, v207, v5
	v_add_f32_e32 v208, v208, v6
	v_add_f32_e32 v209, v209, v7
	v_add_f32_e32 v202, v202, v126
	v_add_f32_e32 v203, v203, v127
	v_add_f32_e32 v204, v204, v128
	v_add_f32_e32 v205, v205, v129
	v_add_f32_e32 v206, v206, v130
	v_add_f32_e32 v207, v207, v131
	v_add_f32_e32 v208, v208, v132
	v_add_f32_e32 v209, v209, v133
	v_add_f32_e32 v202, v202, v112
	v_add_f32_e32 v203, v203, v113
	v_add_f32_e32 v204, v204, v114
	v_add_f32_e32 v205, v205, v115
	v_add_f32_e32 v206, v206, v116
	v_add_f32_e32 v207, v207, v117
	v_add_f32_e32 v208, v208, v118
	v_add_f32_e32 v209, v209, v119
	v_add_f32_e32 v202, v202, v104
	v_add_f32_e32 v203, v203, v105
	v_add_f32_e32 v204, v204, v106
	v_add_f32_e32 v205, v205, v107
	v_add_f32_e32 v206, v206, v108
	v_add_f32_e32 v207, v207, v109
	v_add_f32_e32 v208, v208, v110
	v_add_f32_e32 v209, v209, v111
	v_add_f32_e32 v202, v202, v96
	v_add_f32_e32 v203, v203, v97
	v_add_f32_e32 v204, v204, v98
	v_add_f32_e32 v205, v205, v99
	v_add_f32_e32 v206, v206, v100
	v_add_f32_e32 v207, v207, v101
	v_add_f32_e32 v208, v208, v102
	v_add_f32_e32 v209, v209, v103
	v_add_f32_e32 v202, v202, v88
	v_add_f32_e32 v203, v203, v89
	v_add_f32_e32 v204, v204, v90
	v_add_f32_e32 v205, v205, v91
	v_add_f32_e32 v206, v206, v92
	v_add_f32_e32 v207, v207, v93
	v_add_f32_e32 v208, v208, v94
	v_add_f32_e32 v209, v209, v95
	s_mov_b64 exec, -1
	v_fma_f32 v202, v202, v186, -v80
	v_fma_f32 v203, v203, v186, -v81
	v_add_f32_dpp v232, v232, v232 quad_perm:[1,0,3,2] row_mask:0xf bank_mask:0xf
	v_add_f32_dpp v233, v233, v233 quad_perm:[1,0,3,2] row_mask:0xf bank_mask:0xf
	v_fma_f32 v204, v204, v186, -v82
	v_fma_f32 v205, v205, v186, -v83
	v_add_f32_dpp v232, v232, v232 quad_perm:[2,3,0,1] row_mask:0xf bank_mask:0xf
	v_add_f32_dpp v233, v233, v233 quad_perm:[2,3,0,1] row_mask:0xf bank_mask:0xf
	v_fma_f32 v206, v206, v186, -v84
	v_fma_f32 v207, v207, v186, -v85
	v_add_f32_dpp v232, v232, v232 row_half_mirror row_mask:0xf bank_mask:0xf
	v_add_f32_dpp v233, v233, v233 row_half_mirror row_mask:0xf bank_mask:0xf
	v_fma_f32 v208, v208, v186, -v86
	v_fma_f32 v209, v209, v186, -v87
	v_add_f32_dpp v232, v232, v232 row_mirror row_mask:0xf bank_mask:0xf
	v_add_f32_dpp v233, v233, v233 row_mirror row_mask:0xf bank_mask:0xf
	v_cvt_pk_bf16_f32 v228, v202, v203
	v_cvt_pk_bf16_f32 v229, v204, v205
	v_mov_b32_e32 v234, v232
	v_mov_b32_e32 v235, v233
	v_cvt_pk_bf16_f32 v230, v206, v207
	v_cvt_pk_bf16_f32 v231, v208, v209
	v_permlane16_swap_b32_e32 v232, v234
	v_permlane16_swap_b32_e32 v233, v235
	s_nop 0
	v_add_f32_e32 v232, v232, v234
	v_add_f32_e32 v233, v233, v235
	global_store_dwordx4 v156, v[228:231], s[22:23]
	global_store_dwordx2 v184, v[238:239], s[28:29]
	v_mov_b32_e32 v234, v232
	v_mov_b32_e32 v235, v233
	s_nop 1
	v_permlane32_swap_b32_e32 v232, v234
	v_permlane32_swap_b32_e32 v233, v235
	s_nop 0
	v_add_f32_e32 v232, v232, v234
	v_add_f32_e32 v233, v233, v235
	v_fma_f32 v232, v232, s58, v187
	v_fma_f32 v233, v233, s59, v187
	v_rsq_f32_e32 v236, v232
	v_rsq_f32_e32 v237, v233
	s_add_u32 s22, s22, 0x400
	s_addc_u32 s23, s23, 0
	s_add_u32 s28, s28, 0x600
	s_addc_u32 s29, s29, 0
	v_mul_f32_e32 v236, s57, v236
	v_mul_f32_e32 v210, v210, v236
	v_mul_f32_e32 v211, v211, v236
	v_mul_f32_e32 v212, v212, v236
	v_mul_f32_e32 v213, v213, v236
	v_mul_f32_e32 v214, v214, v236
	v_mul_f32_e32 v215, v215, v236
	v_mul_f32_e32 v216, v216, v237
	v_mul_f32_e32 v217, v217, v237
	v_mul_f32_e32 v218, v218, v237
	v_mul_f32_e32 v219, v219, v237
	v_mul_f32_e32 v210, v210, v192
	v_mul_f32_e32 v211, v211, v193
	v_mul_f32_e32 v212, v212, v194
	v_mul_f32_e32 v213, v213, v195
	v_mul_f32_e32 v214, v214, v196
	v_mul_f32_e32 v215, v215, v197
	v_mul_f32_e32 v216, v216, v198
	v_mul_f32_e32 v217, v217, v199
	v_mul_f32_e32 v218, v218, v200
	v_mul_f32_e32 v219, v219, v201
	v_cvt_pk_bf16_f32 v120, v210, v211
	v_cvt_pk_bf16_f32 v121, v212, v213
	v_cvt_pk_bf16_f32 v122, v214, v215
	v_cvt_pk_bf16_f32 v123, v216, v217
	v_cvt_pk_bf16_f32 v125, v218, v219
	global_store_dword v157, v120, s[24:25]
	global_store_dword v157, v121, s[24:25] offset:256
	global_store_dword v157, v122, s[24:25] offset:512
	global_store_dword v157, v123, s[26:27]
	global_store_dword v157, v125, s[26:27] offset:256
	s_add_u32 s24, s24, 0x300
	s_addc_u32 s25, s25, 0
	s_add_u32 s26, s26, 0x200
	s_addc_u32 s27, s27, 0
	s_waitcnt vmcnt(24)
	v_lshlrev_b32_e32 v88, 16, v162
	v_and_b32_e32 v89, s56, v162
	v_lshlrev_b32_e32 v90, 16, v163
	v_and_b32_e32 v91, s56, v163
	v_lshlrev_b32_e32 v92, 16, v164
	v_and_b32_e32 v93, s56, v164
	v_lshlrev_b32_e32 v94, 16, v165
	v_and_b32_e32 v95, s56, v165
	v_cndmask_b32_e64 v234, v172, v174, s[52:53]
	v_cndmask_b32_e64 v235, v173, v175, s[52:53]
	v_cndmask_b32_e64 v232, v174, v172, s[52:53]
	v_cndmask_b32_e64 v233, v175, v173, s[52:53]
	v_lshlrev_b32_e32 v220, 16, v234
	v_and_b32_e32 v221, s56, v234
	v_lshlrev_b32_e32 v222, 16, v235
	v_and_b32_e32 v223, s56, v235
	v_lshlrev_b32_e32 v224, 16, v232
	v_and_b32_e32 v225, s56, v232
	v_lshlrev_b32_e32 v226, 16, v233
	v_and_b32_e32 v227, s56, v233
	v_xor_b32_e32 v234, v185, v177
	v_mul_f32_e32 v224, v224, v234
	v_fmac_f32_e32 v224, v220, v176
	v_xor_b32_e32 v234, v185, v179
	v_mul_f32_e32 v225, v225, v234
	v_fmac_f32_e32 v225, v221, v178
	v_xor_b32_e32 v234, v185, v181
	v_mul_f32_e32 v226, v226, v234
	v_fmac_f32_e32 v226, v222, v180
	v_xor_b32_e32 v234, v185, v183
	v_mul_f32_e32 v227, v227, v234
	v_fmac_f32_e32 v227, v223, v182
	v_cvt_pk_bf16_f32 v238, v224, v225
	v_cvt_pk_bf16_f32 v239, v226, v227
	v_lshlrev_b32_e32 v210, 16, v166
	v_and_b32_e32 v211, s56, v166
	v_lshlrev_b32_e32 v212, 16, v167
	v_and_b32_e32 v213, s56, v167
	v_lshlrev_b32_e32 v214, 16, v168
	v_and_b32_e32 v215, s56, v168
	v_lshlrev_b32_e32 v216, 16, v169
	v_and_b32_e32 v217, s56, v169
	v_lshlrev_b32_e32 v218, 16, v170
	v_and_b32_e32 v219, s56, v170
	global_load_dwordx4 v[162:165], v156, s[16:17]
	global_load_dword v166, v157, s[18:19]
	global_load_dword v167, v157, s[18:19] offset:256
	global_load_dword v168, v157, s[18:19] offset:512
	global_load_dword v169, v157, s[18:19] offset:768
	global_load_dword v170, v157, s[18:19] offset:1024
	global_load_dwordx2 v[172:173], v158, s[18:19]
	global_load_dwordx2 v[174:175], v158, s[18:19] offset:32
	global_load_dwordx4 v[176:179], v159, s[20:21]
	global_load_dwordx4 v[180:183], v159, s[20:21] offset:16
	s_add_u32 s16, s16, 0x400
	s_addc_u32 s17, s17, 0
	s_add_u32 s18, s18, 0x600
	s_addc_u32 s19, s19, 0
	s_add_u32 s20, s20, 0x80
	s_addc_u32 s21, s21, 0
	v_mul_f32_e32 v232, v210, v210
	v_mul_f32_e32 v233, v216, v216
	v_fmac_f32_e32 v232, v211, v211
	v_fmac_f32_e32 v233, v217, v217
	v_fmac_f32_e32 v232, v212, v212
	v_fmac_f32_e32 v233, v218, v218
	v_fmac_f32_e32 v232, v213, v213
	v_fmac_f32_e32 v233, v219, v219
	v_fmac_f32_e32 v232, v214, v214
	v_fmac_f32_e32 v232, v215, v215
	v_add_f32_e32 v202, v88, v80
	v_add_f32_e32 v203, v89, v81
	v_add_f32_e32 v204, v90, v82
	v_add_f32_e32 v205, v91, v83
	v_add_f32_e32 v206, v92, v84
	v_add_f32_e32 v207, v93, v85
	v_add_f32_e32 v208, v94, v86
	v_add_f32_e32 v209, v95, v87
	s_mov_b64 exec, s[46:47]
	v_add_f32_e32 v202, v202, v72
	v_add_f32_e32 v203, v203, v73
	v_add_f32_e32 v204, v204, v74
	v_add_f32_e32 v205, v205, v75
	v_add_f32_e32 v206, v206, v76
	v_add_f32_e32 v207, v207, v77
	v_add_f32_e32 v208, v208, v78
	v_add_f32_e32 v209, v209, v79
	v_add_f32_e32 v202, v202, v64
	v_add_f32_e32 v203, v203, v65
	v_add_f32_e32 v204, v204, v66
	v_add_f32_e32 v205, v205, v67
	v_add_f32_e32 v206, v206, v68
	v_add_f32_e32 v207, v207, v69
	v_add_f32_e32 v208, v208, v70
	v_add_f32_e32 v209, v209, v71
	s_mov_b64 exec, s[48:49]
	v_add_f32_e32 v202, v202, v56
	v_add_f32_e32 v203, v203, v57
	v_add_f32_e32 v204, v204, v58
	v_add_f32_e32 v205, v205, v59
	v_add_f32_e32 v206, v206, v60
	v_add_f32_e32 v207, v207, v61
	v_add_f32_e32 v208, v208, v62
	v_add_f32_e32 v209, v209, v63
	v_add_f32_e32 v202, v202, v48
	v_add_f32_e32 v203, v203, v49
	v_add_f32_e32 v204, v204, v50
	v_add_f32_e32 v205, v205, v51
	v_add_f32_e32 v206, v206, v52
	v_add_f32_e32 v207, v207, v53
	v_add_f32_e32 v208, v208, v54
	v_add_f32_e32 v209, v209, v55
	v_add_f32_e32 v202, v202, v40
	v_add_f32_e32 v203, v203, v41
	v_add_f32_e32 v204, v204, v42
	v_add_f32_e32 v205, v205, v43
	v_add_f32_e32 v206, v206, v44
	v_add_f32_e32 v207, v207, v45
	v_add_f32_e32 v208, v208, v46
	v_add_f32_e32 v209, v209, v47
	v_add_f32_e32 v202, v202, v32
	v_add_f32_e32 v203, v203, v33
	v_add_f32_e32 v204, v204, v34
	v_add_f32_e32 v205, v205, v35
	v_add_f32_e32 v206, v206, v36
	v_add_f32_e32 v207, v207, v37
	v_add_f32_e32 v208, v208, v38
	v_add_f32_e32 v209, v209, v39
	s_mov_b64 exec, s[50:51]
	v_add_f32_e32 v202, v202, v24
	v_add_f32_e32 v203, v203, v25
	v_add_f32_e32 v204, v204, v26
	v_add_f32_e32 v205, v205, v27
	v_add_f32_e32 v206, v206, v28
	v_add_f32_e32 v207, v207, v29
	v_add_f32_e32 v208, v208, v30
	v_add_f32_e32 v209, v209, v31
	v_add_f32_e32 v202, v202, v16
	v_add_f32_e32 v203, v203, v17
	v_add_f32_e32 v204, v204, v18
	v_add_f32_e32 v205, v205, v19
	v_add_f32_e32 v206, v206, v20
	v_add_f32_e32 v207, v207, v21
	v_add_f32_e32 v208, v208, v22
	v_add_f32_e32 v209, v209, v23
	v_add_f32_e32 v202, v202, v8
	v_add_f32_e32 v203, v203, v9
	v_add_f32_e32 v204, v204, v10
	v_add_f32_e32 v205, v205, v11
	v_add_f32_e32 v206, v206, v12
	v_add_f32_e32 v207, v207, v13
	v_add_f32_e32 v208, v208, v14
	v_add_f32_e32 v209, v209, v15
	v_add_f32_e32 v202, v202, v0
	v_add_f32_e32 v203, v203, v1
	v_add_f32_e32 v204, v204, v2
	v_add_f32_e32 v205, v205, v3
	v_add_f32_e32 v206, v206, v4
	v_add_f32_e32 v207, v207, v5
	v_add_f32_e32 v208, v208, v6
	v_add_f32_e32 v209, v209, v7
	v_add_f32_e32 v202, v202, v126
	v_add_f32_e32 v203, v203, v127
	v_add_f32_e32 v204, v204, v128
	v_add_f32_e32 v205, v205, v129
	v_add_f32_e32 v206, v206, v130
	v_add_f32_e32 v207, v207, v131
	v_add_f32_e32 v208, v208, v132
	v_add_f32_e32 v209, v209, v133
	v_add_f32_e32 v202, v202, v112
	v_add_f32_e32 v203, v203, v113
	v_add_f32_e32 v204, v204, v114
	v_add_f32_e32 v205, v205, v115
	v_add_f32_e32 v206, v206, v116
	v_add_f32_e32 v207, v207, v117
	v_add_f32_e32 v208, v208, v118
	v_add_f32_e32 v209, v209, v119
	v_add_f32_e32 v202, v202, v104
	v_add_f32_e32 v203, v203, v105
	v_add_f32_e32 v204, v204, v106
	v_add_f32_e32 v205, v205, v107
	v_add_f32_e32 v206, v206, v108
	v_add_f32_e32 v207, v207, v109
	v_add_f32_e32 v208, v208, v110
	v_add_f32_e32 v209, v209, v111
	v_add_f32_e32 v202, v202, v96
	v_add_f32_e32 v203, v203, v97
	v_add_f32_e32 v204, v204, v98
	v_add_f32_e32 v205, v205, v99
	v_add_f32_e32 v206, v206, v100
	v_add_f32_e32 v207, v207, v101
	v_add_f32_e32 v208, v208, v102
	v_add_f32_e32 v209, v209, v103
	s_mov_b64 exec, -1
	v_fma_f32 v202, v202, v186, -v88
	v_fma_f32 v203, v203, v186, -v89
	v_add_f32_dpp v232, v232, v232 quad_perm:[1,0,3,2] row_mask:0xf bank_mask:0xf
	v_add_f32_dpp v233, v233, v233 quad_perm:[1,0,3,2] row_mask:0xf bank_mask:0xf
	v_fma_f32 v204, v204, v186, -v90
	v_fma_f32 v205, v205, v186, -v91
	v_add_f32_dpp v232, v232, v232 quad_perm:[2,3,0,1] row_mask:0xf bank_mask:0xf
	v_add_f32_dpp v233, v233, v233 quad_perm:[2,3,0,1] row_mask:0xf bank_mask:0xf
	v_fma_f32 v206, v206, v186, -v92
	v_fma_f32 v207, v207, v186, -v93
	v_add_f32_dpp v232, v232, v232 row_half_mirror row_mask:0xf bank_mask:0xf
	v_add_f32_dpp v233, v233, v233 row_half_mirror row_mask:0xf bank_mask:0xf
	v_fma_f32 v208, v208, v186, -v94
	v_fma_f32 v209, v209, v186, -v95
	v_add_f32_dpp v232, v232, v232 row_mirror row_mask:0xf bank_mask:0xf
	v_add_f32_dpp v233, v233, v233 row_mirror row_mask:0xf bank_mask:0xf
	v_cvt_pk_bf16_f32 v228, v202, v203
	v_cvt_pk_bf16_f32 v229, v204, v205
	v_mov_b32_e32 v234, v232
	v_mov_b32_e32 v235, v233
	v_cvt_pk_bf16_f32 v230, v206, v207
	v_cvt_pk_bf16_f32 v231, v208, v209
	v_permlane16_swap_b32_e32 v232, v234
	v_permlane16_swap_b32_e32 v233, v235
	s_nop 0
	v_add_f32_e32 v232, v232, v234
	v_add_f32_e32 v233, v233, v235
	global_store_dwordx4 v156, v[228:231], s[22:23]
	global_store_dwordx2 v184, v[238:239], s[28:29]
	v_mov_b32_e32 v234, v232
	v_mov_b32_e32 v235, v233
	s_nop 1
	v_permlane32_swap_b32_e32 v232, v234
	v_permlane32_swap_b32_e32 v233, v235
	s_nop 0
	v_add_f32_e32 v232, v232, v234
	v_add_f32_e32 v233, v233, v235
	v_fma_f32 v232, v232, s58, v187
	v_fma_f32 v233, v233, s59, v187
	v_rsq_f32_e32 v236, v232
	v_rsq_f32_e32 v237, v233
	s_add_u32 s22, s22, 0x400
	s_addc_u32 s23, s23, 0
	s_add_u32 s28, s28, 0x600
	s_addc_u32 s29, s29, 0
	v_mul_f32_e32 v236, s57, v236
	v_mul_f32_e32 v210, v210, v236
	v_mul_f32_e32 v211, v211, v236
	v_mul_f32_e32 v212, v212, v236
	v_mul_f32_e32 v213, v213, v236
	v_mul_f32_e32 v214, v214, v236
	v_mul_f32_e32 v215, v215, v236
	v_mul_f32_e32 v216, v216, v237
	v_mul_f32_e32 v217, v217, v237
	v_mul_f32_e32 v218, v218, v237
	v_mul_f32_e32 v219, v219, v237
	v_mul_f32_e32 v210, v210, v192
	v_mul_f32_e32 v211, v211, v193
	v_mul_f32_e32 v212, v212, v194
	v_mul_f32_e32 v213, v213, v195
	v_mul_f32_e32 v214, v214, v196
	v_mul_f32_e32 v215, v215, v197
	v_mul_f32_e32 v216, v216, v198
	v_mul_f32_e32 v217, v217, v199
	v_mul_f32_e32 v218, v218, v200
	v_mul_f32_e32 v219, v219, v201
	v_cvt_pk_bf16_f32 v120, v210, v211
	v_cvt_pk_bf16_f32 v121, v212, v213
	v_cvt_pk_bf16_f32 v122, v214, v215
	v_cvt_pk_bf16_f32 v123, v216, v217
	v_cvt_pk_bf16_f32 v125, v218, v219
	global_store_dword v157, v120, s[24:25]
	global_store_dword v157, v121, s[24:25] offset:256
	global_store_dword v157, v122, s[24:25] offset:512
	global_store_dword v157, v123, s[26:27]
	global_store_dword v157, v125, s[26:27] offset:256
	s_add_u32 s24, s24, 0x300
	s_addc_u32 s25, s25, 0
	s_add_u32 s26, s26, 0x200
	s_addc_u32 s27, s27, 0
	s_waitcnt vmcnt(24)
	v_lshlrev_b32_e32 v96, 16, v134
	v_and_b32_e32 v97, s56, v134
	v_lshlrev_b32_e32 v98, 16, v135
	v_and_b32_e32 v99, s56, v135
	v_lshlrev_b32_e32 v100, 16, v136
	v_and_b32_e32 v101, s56, v136
	v_lshlrev_b32_e32 v102, 16, v137
	v_and_b32_e32 v103, s56, v137
	v_cndmask_b32_e64 v234, v144, v146, s[52:53]
	v_cndmask_b32_e64 v235, v145, v147, s[52:53]
	v_cndmask_b32_e64 v232, v146, v144, s[52:53]
	v_cndmask_b32_e64 v233, v147, v145, s[52:53]
	v_lshlrev_b32_e32 v220, 16, v234
	v_and_b32_e32 v221, s56, v234
	v_lshlrev_b32_e32 v222, 16, v235
	v_and_b32_e32 v223, s56, v235
	v_lshlrev_b32_e32 v224, 16, v232
	v_and_b32_e32 v225, s56, v232
	v_lshlrev_b32_e32 v226, 16, v233
	v_and_b32_e32 v227, s56, v233
	v_xor_b32_e32 v234, v185, v149
	v_mul_f32_e32 v224, v224, v234
	v_fmac_f32_e32 v224, v220, v148
	v_xor_b32_e32 v234, v185, v151
	v_mul_f32_e32 v225, v225, v234
	v_fmac_f32_e32 v225, v221, v150
	v_xor_b32_e32 v234, v185, v153
	v_mul_f32_e32 v226, v226, v234
	v_fmac_f32_e32 v226, v222, v152
	v_xor_b32_e32 v234, v185, v155
	v_mul_f32_e32 v227, v227, v234
	v_fmac_f32_e32 v227, v223, v154
	v_cvt_pk_bf16_f32 v238, v224, v225
	v_cvt_pk_bf16_f32 v239, v226, v227
	v_lshlrev_b32_e32 v210, 16, v138
	v_and_b32_e32 v211, s56, v138
	v_lshlrev_b32_e32 v212, 16, v139
	v_and_b32_e32 v213, s56, v139
	v_lshlrev_b32_e32 v214, 16, v140
	v_and_b32_e32 v215, s56, v140
	v_lshlrev_b32_e32 v216, 16, v141
	v_and_b32_e32 v217, s56, v141
	v_lshlrev_b32_e32 v218, 16, v142
	v_and_b32_e32 v219, s56, v142
	global_load_dwordx4 v[134:137], v156, s[16:17]
	global_load_dword v138, v157, s[18:19]
	global_load_dword v139, v157, s[18:19] offset:256
	global_load_dword v140, v157, s[18:19] offset:512
	global_load_dword v141, v157, s[18:19] offset:768
	global_load_dword v142, v157, s[18:19] offset:1024
	global_load_dwordx2 v[144:145], v158, s[18:19]
	global_load_dwordx2 v[146:147], v158, s[18:19] offset:32
	global_load_dwordx4 v[148:151], v159, s[20:21]
	global_load_dwordx4 v[152:155], v159, s[20:21] offset:16
	s_add_u32 s16, s16, 0x400
	s_addc_u32 s17, s17, 0
	s_add_u32 s18, s18, 0x600
	s_addc_u32 s19, s19, 0
	s_add_u32 s20, s20, 0x80
	s_addc_u32 s21, s21, 0
	v_mul_f32_e32 v232, v210, v210
	v_mul_f32_e32 v233, v216, v216
	v_fmac_f32_e32 v232, v211, v211
	v_fmac_f32_e32 v233, v217, v217
	v_fmac_f32_e32 v232, v212, v212
	v_fmac_f32_e32 v233, v218, v218
	v_fmac_f32_e32 v232, v213, v213
	v_fmac_f32_e32 v233, v219, v219
	v_fmac_f32_e32 v232, v214, v214
	v_fmac_f32_e32 v232, v215, v215
	v_add_f32_e32 v202, v96, v88
	v_add_f32_e32 v203, v97, v89
	v_add_f32_e32 v204, v98, v90
	v_add_f32_e32 v205, v99, v91
	v_add_f32_e32 v206, v100, v92
	v_add_f32_e32 v207, v101, v93
	v_add_f32_e32 v208, v102, v94
	v_add_f32_e32 v209, v103, v95
	s_mov_b64 exec, s[46:47]
	v_add_f32_e32 v202, v202, v80
	v_add_f32_e32 v203, v203, v81
	v_add_f32_e32 v204, v204, v82
	v_add_f32_e32 v205, v205, v83
	v_add_f32_e32 v206, v206, v84
	v_add_f32_e32 v207, v207, v85
	v_add_f32_e32 v208, v208, v86
	v_add_f32_e32 v209, v209, v87
	v_add_f32_e32 v202, v202, v72
	v_add_f32_e32 v203, v203, v73
	v_add_f32_e32 v204, v204, v74
	v_add_f32_e32 v205, v205, v75
	v_add_f32_e32 v206, v206, v76
	v_add_f32_e32 v207, v207, v77
	v_add_f32_e32 v208, v208, v78
	v_add_f32_e32 v209, v209, v79
	s_mov_b64 exec, s[48:49]
	v_add_f32_e32 v202, v202, v64
	v_add_f32_e32 v203, v203, v65
	v_add_f32_e32 v204, v204, v66
	v_add_f32_e32 v205, v205, v67
	v_add_f32_e32 v206, v206, v68
	v_add_f32_e32 v207, v207, v69
	v_add_f32_e32 v208, v208, v70
	v_add_f32_e32 v209, v209, v71
	v_add_f32_e32 v202, v202, v56
	v_add_f32_e32 v203, v203, v57
	v_add_f32_e32 v204, v204, v58
	v_add_f32_e32 v205, v205, v59
	v_add_f32_e32 v206, v206, v60
	v_add_f32_e32 v207, v207, v61
	v_add_f32_e32 v208, v208, v62
	v_add_f32_e32 v209, v209, v63
	v_add_f32_e32 v202, v202, v48
	v_add_f32_e32 v203, v203, v49
	v_add_f32_e32 v204, v204, v50
	v_add_f32_e32 v205, v205, v51
	v_add_f32_e32 v206, v206, v52
	v_add_f32_e32 v207, v207, v53
	v_add_f32_e32 v208, v208, v54
	v_add_f32_e32 v209, v209, v55
	v_add_f32_e32 v202, v202, v40
	v_add_f32_e32 v203, v203, v41
	v_add_f32_e32 v204, v204, v42
	v_add_f32_e32 v205, v205, v43
	v_add_f32_e32 v206, v206, v44
	v_add_f32_e32 v207, v207, v45
	v_add_f32_e32 v208, v208, v46
	v_add_f32_e32 v209, v209, v47
	s_mov_b64 exec, s[50:51]
	v_add_f32_e32 v202, v202, v32
	v_add_f32_e32 v203, v203, v33
	v_add_f32_e32 v204, v204, v34
	v_add_f32_e32 v205, v205, v35
	v_add_f32_e32 v206, v206, v36
	v_add_f32_e32 v207, v207, v37
	v_add_f32_e32 v208, v208, v38
	v_add_f32_e32 v209, v209, v39
	v_add_f32_e32 v202, v202, v24
	v_add_f32_e32 v203, v203, v25
	v_add_f32_e32 v204, v204, v26
	v_add_f32_e32 v205, v205, v27
	v_add_f32_e32 v206, v206, v28
	v_add_f32_e32 v207, v207, v29
	v_add_f32_e32 v208, v208, v30
	v_add_f32_e32 v209, v209, v31
	v_add_f32_e32 v202, v202, v16
	v_add_f32_e32 v203, v203, v17
	v_add_f32_e32 v204, v204, v18
	v_add_f32_e32 v205, v205, v19
	v_add_f32_e32 v206, v206, v20
	v_add_f32_e32 v207, v207, v21
	v_add_f32_e32 v208, v208, v22
	v_add_f32_e32 v209, v209, v23
	v_add_f32_e32 v202, v202, v8
	v_add_f32_e32 v203, v203, v9
	v_add_f32_e32 v204, v204, v10
	v_add_f32_e32 v205, v205, v11
	v_add_f32_e32 v206, v206, v12
	v_add_f32_e32 v207, v207, v13
	v_add_f32_e32 v208, v208, v14
	v_add_f32_e32 v209, v209, v15
	v_add_f32_e32 v202, v202, v0
	v_add_f32_e32 v203, v203, v1
	v_add_f32_e32 v204, v204, v2
	v_add_f32_e32 v205, v205, v3
	v_add_f32_e32 v206, v206, v4
	v_add_f32_e32 v207, v207, v5
	v_add_f32_e32 v208, v208, v6
	v_add_f32_e32 v209, v209, v7
	v_add_f32_e32 v202, v202, v126
	v_add_f32_e32 v203, v203, v127
	v_add_f32_e32 v204, v204, v128
	v_add_f32_e32 v205, v205, v129
	v_add_f32_e32 v206, v206, v130
	v_add_f32_e32 v207, v207, v131
	v_add_f32_e32 v208, v208, v132
	v_add_f32_e32 v209, v209, v133
	v_add_f32_e32 v202, v202, v112
	v_add_f32_e32 v203, v203, v113
	v_add_f32_e32 v204, v204, v114
	v_add_f32_e32 v205, v205, v115
	v_add_f32_e32 v206, v206, v116
	v_add_f32_e32 v207, v207, v117
	v_add_f32_e32 v208, v208, v118
	v_add_f32_e32 v209, v209, v119
	v_add_f32_e32 v202, v202, v104
	v_add_f32_e32 v203, v203, v105
	v_add_f32_e32 v204, v204, v106
	v_add_f32_e32 v205, v205, v107
	v_add_f32_e32 v206, v206, v108
	v_add_f32_e32 v207, v207, v109
	v_add_f32_e32 v208, v208, v110
	v_add_f32_e32 v209, v209, v111
	s_mov_b64 exec, -1
	v_fma_f32 v202, v202, v186, -v96
	v_fma_f32 v203, v203, v186, -v97
	v_add_f32_dpp v232, v232, v232 quad_perm:[1,0,3,2] row_mask:0xf bank_mask:0xf
	v_add_f32_dpp v233, v233, v233 quad_perm:[1,0,3,2] row_mask:0xf bank_mask:0xf
	v_fma_f32 v204, v204, v186, -v98
	v_fma_f32 v205, v205, v186, -v99
	v_add_f32_dpp v232, v232, v232 quad_perm:[2,3,0,1] row_mask:0xf bank_mask:0xf
	v_add_f32_dpp v233, v233, v233 quad_perm:[2,3,0,1] row_mask:0xf bank_mask:0xf
	v_fma_f32 v206, v206, v186, -v100
	v_fma_f32 v207, v207, v186, -v101
	v_add_f32_dpp v232, v232, v232 row_half_mirror row_mask:0xf bank_mask:0xf
	v_add_f32_dpp v233, v233, v233 row_half_mirror row_mask:0xf bank_mask:0xf
	v_fma_f32 v208, v208, v186, -v102
	v_fma_f32 v209, v209, v186, -v103
	v_add_f32_dpp v232, v232, v232 row_mirror row_mask:0xf bank_mask:0xf
	v_add_f32_dpp v233, v233, v233 row_mirror row_mask:0xf bank_mask:0xf
	v_cvt_pk_bf16_f32 v228, v202, v203
	v_cvt_pk_bf16_f32 v229, v204, v205
	v_mov_b32_e32 v234, v232
	v_mov_b32_e32 v235, v233
	v_cvt_pk_bf16_f32 v230, v206, v207
	v_cvt_pk_bf16_f32 v231, v208, v209
	v_permlane16_swap_b32_e32 v232, v234
	v_permlane16_swap_b32_e32 v233, v235
	s_nop 0
	v_add_f32_e32 v232, v232, v234
	v_add_f32_e32 v233, v233, v235
	global_store_dwordx4 v156, v[228:231], s[22:23]
	global_store_dwordx2 v184, v[238:239], s[28:29]
	v_mov_b32_e32 v234, v232
	v_mov_b32_e32 v235, v233
	s_nop 1
	v_permlane32_swap_b32_e32 v232, v234
	v_permlane32_swap_b32_e32 v233, v235
	s_nop 0
	v_add_f32_e32 v232, v232, v234
	v_add_f32_e32 v233, v233, v235
	v_fma_f32 v232, v232, s58, v187
	v_fma_f32 v233, v233, s59, v187
	v_rsq_f32_e32 v236, v232
	v_rsq_f32_e32 v237, v233
	s_add_u32 s22, s22, 0x400
	s_addc_u32 s23, s23, 0
	s_add_u32 s28, s28, 0x600
	s_addc_u32 s29, s29, 0
	v_mul_f32_e32 v236, s57, v236
	v_mul_f32_e32 v210, v210, v236
	v_mul_f32_e32 v211, v211, v236
	v_mul_f32_e32 v212, v212, v236
	v_mul_f32_e32 v213, v213, v236
	v_mul_f32_e32 v214, v214, v236
	v_mul_f32_e32 v215, v215, v236
	v_mul_f32_e32 v216, v216, v237
	v_mul_f32_e32 v217, v217, v237
	v_mul_f32_e32 v218, v218, v237
	v_mul_f32_e32 v219, v219, v237
	v_mul_f32_e32 v210, v210, v192
	v_mul_f32_e32 v211, v211, v193
	v_mul_f32_e32 v212, v212, v194
	v_mul_f32_e32 v213, v213, v195
	v_mul_f32_e32 v214, v214, v196
	v_mul_f32_e32 v215, v215, v197
	v_mul_f32_e32 v216, v216, v198
	v_mul_f32_e32 v217, v217, v199
	v_mul_f32_e32 v218, v218, v200
	v_mul_f32_e32 v219, v219, v201
	v_cvt_pk_bf16_f32 v120, v210, v211
	v_cvt_pk_bf16_f32 v121, v212, v213
	v_cvt_pk_bf16_f32 v122, v214, v215
	v_cvt_pk_bf16_f32 v123, v216, v217
	v_cvt_pk_bf16_f32 v125, v218, v219
	global_store_dword v157, v120, s[24:25]
	global_store_dword v157, v121, s[24:25] offset:256
	global_store_dword v157, v122, s[24:25] offset:512
	global_store_dword v157, v123, s[26:27]
	global_store_dword v157, v125, s[26:27] offset:256
	s_add_u32 s24, s24, 0x300
	s_addc_u32 s25, s25, 0
	s_add_u32 s26, s26, 0x200
	s_addc_u32 s27, s27, 0
	s_waitcnt vmcnt(24)
	v_lshlrev_b32_e32 v104, 16, v162
	v_and_b32_e32 v105, s56, v162
	v_lshlrev_b32_e32 v106, 16, v163
	v_and_b32_e32 v107, s56, v163
	v_lshlrev_b32_e32 v108, 16, v164
	v_and_b32_e32 v109, s56, v164
	v_lshlrev_b32_e32 v110, 16, v165
	v_and_b32_e32 v111, s56, v165
	v_cndmask_b32_e64 v234, v172, v174, s[52:53]
	v_cndmask_b32_e64 v235, v173, v175, s[52:53]
	v_cndmask_b32_e64 v232, v174, v172, s[52:53]
	v_cndmask_b32_e64 v233, v175, v173, s[52:53]
	v_lshlrev_b32_e32 v220, 16, v234
	v_and_b32_e32 v221, s56, v234
	v_lshlrev_b32_e32 v222, 16, v235
	v_and_b32_e32 v223, s56, v235
	v_lshlrev_b32_e32 v224, 16, v232
	v_and_b32_e32 v225, s56, v232
	v_lshlrev_b32_e32 v226, 16, v233
	v_and_b32_e32 v227, s56, v233
	v_xor_b32_e32 v234, v185, v177
	v_mul_f32_e32 v224, v224, v234
	v_fmac_f32_e32 v224, v220, v176
	v_xor_b32_e32 v234, v185, v179
	v_mul_f32_e32 v225, v225, v234
	v_fmac_f32_e32 v225, v221, v178
	v_xor_b32_e32 v234, v185, v181
	v_mul_f32_e32 v226, v226, v234
	v_fmac_f32_e32 v226, v222, v180
	v_xor_b32_e32 v234, v185, v183
	v_mul_f32_e32 v227, v227, v234
	v_fmac_f32_e32 v227, v223, v182
	v_cvt_pk_bf16_f32 v238, v224, v225
	v_cvt_pk_bf16_f32 v239, v226, v227
	v_lshlrev_b32_e32 v210, 16, v166
	v_and_b32_e32 v211, s56, v166
	v_lshlrev_b32_e32 v212, 16, v167
	v_and_b32_e32 v213, s56, v167
	v_lshlrev_b32_e32 v214, 16, v168
	v_and_b32_e32 v215, s56, v168
	v_lshlrev_b32_e32 v216, 16, v169
	v_and_b32_e32 v217, s56, v169
	v_lshlrev_b32_e32 v218, 16, v170
	v_and_b32_e32 v219, s56, v170
	global_load_dwordx4 v[162:165], v156, s[16:17]
	global_load_dword v166, v157, s[18:19]
	global_load_dword v167, v157, s[18:19] offset:256
	global_load_dword v168, v157, s[18:19] offset:512
	global_load_dword v169, v157, s[18:19] offset:768
	global_load_dword v170, v157, s[18:19] offset:1024
	global_load_dwordx2 v[172:173], v158, s[18:19]
	global_load_dwordx2 v[174:175], v158, s[18:19] offset:32
	global_load_dwordx4 v[176:179], v159, s[20:21]
	global_load_dwordx4 v[180:183], v159, s[20:21] offset:16
	s_add_u32 s16, s16, 0x400
	s_addc_u32 s17, s17, 0
	s_add_u32 s18, s18, 0x600
	s_addc_u32 s19, s19, 0
	s_add_u32 s20, s20, 0x80
	s_addc_u32 s21, s21, 0
	v_mul_f32_e32 v232, v210, v210
	v_mul_f32_e32 v233, v216, v216
	v_fmac_f32_e32 v232, v211, v211
	v_fmac_f32_e32 v233, v217, v217
	v_fmac_f32_e32 v232, v212, v212
	v_fmac_f32_e32 v233, v218, v218
	v_fmac_f32_e32 v232, v213, v213
	v_fmac_f32_e32 v233, v219, v219
	v_fmac_f32_e32 v232, v214, v214
	v_fmac_f32_e32 v232, v215, v215
	v_add_f32_e32 v202, v104, v96
	v_add_f32_e32 v203, v105, v97
	v_add_f32_e32 v204, v106, v98
	v_add_f32_e32 v205, v107, v99
	v_add_f32_e32 v206, v108, v100
	v_add_f32_e32 v207, v109, v101
	v_add_f32_e32 v208, v110, v102
	v_add_f32_e32 v209, v111, v103
	s_mov_b64 exec, s[46:47]
	v_add_f32_e32 v202, v202, v88
	v_add_f32_e32 v203, v203, v89
	v_add_f32_e32 v204, v204, v90
	v_add_f32_e32 v205, v205, v91
	v_add_f32_e32 v206, v206, v92
	v_add_f32_e32 v207, v207, v93
	v_add_f32_e32 v208, v208, v94
	v_add_f32_e32 v209, v209, v95
	v_add_f32_e32 v202, v202, v80
	v_add_f32_e32 v203, v203, v81
	v_add_f32_e32 v204, v204, v82
	v_add_f32_e32 v205, v205, v83
	v_add_f32_e32 v206, v206, v84
	v_add_f32_e32 v207, v207, v85
	v_add_f32_e32 v208, v208, v86
	v_add_f32_e32 v209, v209, v87
	s_mov_b64 exec, s[48:49]
	v_add_f32_e32 v202, v202, v72
	v_add_f32_e32 v203, v203, v73
	v_add_f32_e32 v204, v204, v74
	v_add_f32_e32 v205, v205, v75
	v_add_f32_e32 v206, v206, v76
	v_add_f32_e32 v207, v207, v77
	v_add_f32_e32 v208, v208, v78
	v_add_f32_e32 v209, v209, v79
	v_add_f32_e32 v202, v202, v64
	v_add_f32_e32 v203, v203, v65
	v_add_f32_e32 v204, v204, v66
	v_add_f32_e32 v205, v205, v67
	v_add_f32_e32 v206, v206, v68
	v_add_f32_e32 v207, v207, v69
	v_add_f32_e32 v208, v208, v70
	v_add_f32_e32 v209, v209, v71
	v_add_f32_e32 v202, v202, v56
	v_add_f32_e32 v203, v203, v57
	v_add_f32_e32 v204, v204, v58
	v_add_f32_e32 v205, v205, v59
	v_add_f32_e32 v206, v206, v60
	v_add_f32_e32 v207, v207, v61
	v_add_f32_e32 v208, v208, v62
	v_add_f32_e32 v209, v209, v63
	v_add_f32_e32 v202, v202, v48
	v_add_f32_e32 v203, v203, v49
	v_add_f32_e32 v204, v204, v50
	v_add_f32_e32 v205, v205, v51
	v_add_f32_e32 v206, v206, v52
	v_add_f32_e32 v207, v207, v53
	v_add_f32_e32 v208, v208, v54
	v_add_f32_e32 v209, v209, v55
	s_mov_b64 exec, s[50:51]
	v_add_f32_e32 v202, v202, v40
	v_add_f32_e32 v203, v203, v41
	v_add_f32_e32 v204, v204, v42
	v_add_f32_e32 v205, v205, v43
	v_add_f32_e32 v206, v206, v44
	v_add_f32_e32 v207, v207, v45
	v_add_f32_e32 v208, v208, v46
	v_add_f32_e32 v209, v209, v47
	v_add_f32_e32 v202, v202, v32
	v_add_f32_e32 v203, v203, v33
	v_add_f32_e32 v204, v204, v34
	v_add_f32_e32 v205, v205, v35
	v_add_f32_e32 v206, v206, v36
	v_add_f32_e32 v207, v207, v37
	v_add_f32_e32 v208, v208, v38
	v_add_f32_e32 v209, v209, v39
	v_add_f32_e32 v202, v202, v24
	v_add_f32_e32 v203, v203, v25
	v_add_f32_e32 v204, v204, v26
	v_add_f32_e32 v205, v205, v27
	v_add_f32_e32 v206, v206, v28
	v_add_f32_e32 v207, v207, v29
	v_add_f32_e32 v208, v208, v30
	v_add_f32_e32 v209, v209, v31
	v_add_f32_e32 v202, v202, v16
	v_add_f32_e32 v203, v203, v17
	v_add_f32_e32 v204, v204, v18
	v_add_f32_e32 v205, v205, v19
	v_add_f32_e32 v206, v206, v20
	v_add_f32_e32 v207, v207, v21
	v_add_f32_e32 v208, v208, v22
	v_add_f32_e32 v209, v209, v23
	v_add_f32_e32 v202, v202, v8
	v_add_f32_e32 v203, v203, v9
	v_add_f32_e32 v204, v204, v10
	v_add_f32_e32 v205, v205, v11
	v_add_f32_e32 v206, v206, v12
	v_add_f32_e32 v207, v207, v13
	v_add_f32_e32 v208, v208, v14
	v_add_f32_e32 v209, v209, v15
	v_add_f32_e32 v202, v202, v0
	v_add_f32_e32 v203, v203, v1
	v_add_f32_e32 v204, v204, v2
	v_add_f32_e32 v205, v205, v3
	v_add_f32_e32 v206, v206, v4
	v_add_f32_e32 v207, v207, v5
	v_add_f32_e32 v208, v208, v6
	v_add_f32_e32 v209, v209, v7
	v_add_f32_e32 v202, v202, v126
	v_add_f32_e32 v203, v203, v127
	v_add_f32_e32 v204, v204, v128
	v_add_f32_e32 v205, v205, v129
	v_add_f32_e32 v206, v206, v130
	v_add_f32_e32 v207, v207, v131
	v_add_f32_e32 v208, v208, v132
	v_add_f32_e32 v209, v209, v133
	v_add_f32_e32 v202, v202, v112
	v_add_f32_e32 v203, v203, v113
	v_add_f32_e32 v204, v204, v114
	v_add_f32_e32 v205, v205, v115
	v_add_f32_e32 v206, v206, v116
	v_add_f32_e32 v207, v207, v117
	v_add_f32_e32 v208, v208, v118
	v_add_f32_e32 v209, v209, v119
	s_mov_b64 exec, -1
	v_fma_f32 v202, v202, v186, -v104
	v_fma_f32 v203, v203, v186, -v105
	v_add_f32_dpp v232, v232, v232 quad_perm:[1,0,3,2] row_mask:0xf bank_mask:0xf
	v_add_f32_dpp v233, v233, v233 quad_perm:[1,0,3,2] row_mask:0xf bank_mask:0xf
	v_fma_f32 v204, v204, v186, -v106
	v_fma_f32 v205, v205, v186, -v107
	v_add_f32_dpp v232, v232, v232 quad_perm:[2,3,0,1] row_mask:0xf bank_mask:0xf
	v_add_f32_dpp v233, v233, v233 quad_perm:[2,3,0,1] row_mask:0xf bank_mask:0xf
	v_fma_f32 v206, v206, v186, -v108
	v_fma_f32 v207, v207, v186, -v109
	v_add_f32_dpp v232, v232, v232 row_half_mirror row_mask:0xf bank_mask:0xf
	v_add_f32_dpp v233, v233, v233 row_half_mirror row_mask:0xf bank_mask:0xf
	v_fma_f32 v208, v208, v186, -v110
	v_fma_f32 v209, v209, v186, -v111
	v_add_f32_dpp v232, v232, v232 row_mirror row_mask:0xf bank_mask:0xf
	v_add_f32_dpp v233, v233, v233 row_mirror row_mask:0xf bank_mask:0xf
	v_cvt_pk_bf16_f32 v228, v202, v203
	v_cvt_pk_bf16_f32 v229, v204, v205
	v_mov_b32_e32 v234, v232
	v_mov_b32_e32 v235, v233
	v_cvt_pk_bf16_f32 v230, v206, v207
	v_cvt_pk_bf16_f32 v231, v208, v209
	v_permlane16_swap_b32_e32 v232, v234
	v_permlane16_swap_b32_e32 v233, v235
	s_nop 0
	v_add_f32_e32 v232, v232, v234
	v_add_f32_e32 v233, v233, v235
	global_store_dwordx4 v156, v[228:231], s[22:23]
	global_store_dwordx2 v184, v[238:239], s[28:29]
	v_mov_b32_e32 v234, v232
	v_mov_b32_e32 v235, v233
	s_nop 1
	v_permlane32_swap_b32_e32 v232, v234
	v_permlane32_swap_b32_e32 v233, v235
	s_nop 0
	v_add_f32_e32 v232, v232, v234
	v_add_f32_e32 v233, v233, v235
	v_fma_f32 v232, v232, s58, v187
	v_fma_f32 v233, v233, s59, v187
	v_rsq_f32_e32 v236, v232
	v_rsq_f32_e32 v237, v233
	s_add_u32 s22, s22, 0x400
	s_addc_u32 s23, s23, 0
	s_add_u32 s28, s28, 0x600
	s_addc_u32 s29, s29, 0
	v_mul_f32_e32 v236, s57, v236
	v_mul_f32_e32 v210, v210, v236
	v_mul_f32_e32 v211, v211, v236
	v_mul_f32_e32 v212, v212, v236
	v_mul_f32_e32 v213, v213, v236
	v_mul_f32_e32 v214, v214, v236
	v_mul_f32_e32 v215, v215, v236
	v_mul_f32_e32 v216, v216, v237
	v_mul_f32_e32 v217, v217, v237
	v_mul_f32_e32 v218, v218, v237
	v_mul_f32_e32 v219, v219, v237
	v_mul_f32_e32 v210, v210, v192
	v_mul_f32_e32 v211, v211, v193
	v_mul_f32_e32 v212, v212, v194
	v_mul_f32_e32 v213, v213, v195
	v_mul_f32_e32 v214, v214, v196
	v_mul_f32_e32 v215, v215, v197
	v_mul_f32_e32 v216, v216, v198
	v_mul_f32_e32 v217, v217, v199
	v_mul_f32_e32 v218, v218, v200
	v_mul_f32_e32 v219, v219, v201
	v_cvt_pk_bf16_f32 v120, v210, v211
	v_cvt_pk_bf16_f32 v121, v212, v213
	v_cvt_pk_bf16_f32 v122, v214, v215
	v_cvt_pk_bf16_f32 v123, v216, v217
	v_cvt_pk_bf16_f32 v125, v218, v219
	global_store_dword v157, v120, s[24:25]
	global_store_dword v157, v121, s[24:25] offset:256
	global_store_dword v157, v122, s[24:25] offset:512
	global_store_dword v157, v123, s[26:27]
	global_store_dword v157, v125, s[26:27] offset:256
	s_add_u32 s24, s24, 0x300
	s_addc_u32 s25, s25, 0
	s_add_u32 s26, s26, 0x200
	s_addc_u32 s27, s27, 0
	s_waitcnt vmcnt(24)
	v_lshlrev_b32_e32 v112, 16, v134
	v_and_b32_e32 v113, s56, v134
	v_lshlrev_b32_e32 v114, 16, v135
	v_and_b32_e32 v115, s56, v135
	v_lshlrev_b32_e32 v116, 16, v136
	v_and_b32_e32 v117, s56, v136
	v_lshlrev_b32_e32 v118, 16, v137
	v_and_b32_e32 v119, s56, v137
	v_cndmask_b32_e64 v234, v144, v146, s[52:53]
	v_cndmask_b32_e64 v235, v145, v147, s[52:53]
	v_cndmask_b32_e64 v232, v146, v144, s[52:53]
	v_cndmask_b32_e64 v233, v147, v145, s[52:53]
	v_lshlrev_b32_e32 v220, 16, v234
	v_and_b32_e32 v221, s56, v234
	v_lshlrev_b32_e32 v222, 16, v235
	v_and_b32_e32 v223, s56, v235
	v_lshlrev_b32_e32 v224, 16, v232
	v_and_b32_e32 v225, s56, v232
	v_lshlrev_b32_e32 v226, 16, v233
	v_and_b32_e32 v227, s56, v233
	v_xor_b32_e32 v234, v185, v149
	v_mul_f32_e32 v224, v224, v234
	v_fmac_f32_e32 v224, v220, v148
	v_xor_b32_e32 v234, v185, v151
	v_mul_f32_e32 v225, v225, v234
	v_fmac_f32_e32 v225, v221, v150
	v_xor_b32_e32 v234, v185, v153
	v_mul_f32_e32 v226, v226, v234
	v_fmac_f32_e32 v226, v222, v152
	v_xor_b32_e32 v234, v185, v155
	v_mul_f32_e32 v227, v227, v234
	v_fmac_f32_e32 v227, v223, v154
	v_cvt_pk_bf16_f32 v238, v224, v225
	v_cvt_pk_bf16_f32 v239, v226, v227
	v_lshlrev_b32_e32 v210, 16, v138
	v_and_b32_e32 v211, s56, v138
	v_lshlrev_b32_e32 v212, 16, v139
	v_and_b32_e32 v213, s56, v139
	v_lshlrev_b32_e32 v214, 16, v140
	v_and_b32_e32 v215, s56, v140
	v_lshlrev_b32_e32 v216, 16, v141
	v_and_b32_e32 v217, s56, v141
	v_lshlrev_b32_e32 v218, 16, v142
	v_and_b32_e32 v219, s56, v142
	v_mul_f32_e32 v232, v210, v210
	v_mul_f32_e32 v233, v216, v216
	v_fmac_f32_e32 v232, v211, v211
	v_fmac_f32_e32 v233, v217, v217
	v_fmac_f32_e32 v232, v212, v212
	v_fmac_f32_e32 v233, v218, v218
	v_fmac_f32_e32 v232, v213, v213
	v_fmac_f32_e32 v233, v219, v219
	v_fmac_f32_e32 v232, v214, v214
	v_fmac_f32_e32 v232, v215, v215
	v_add_f32_e32 v202, v112, v104
	v_add_f32_e32 v203, v113, v105
	v_add_f32_e32 v204, v114, v106
	v_add_f32_e32 v205, v115, v107
	v_add_f32_e32 v206, v116, v108
	v_add_f32_e32 v207, v117, v109
	v_add_f32_e32 v208, v118, v110
	v_add_f32_e32 v209, v119, v111
	s_mov_b64 exec, s[46:47]
	v_add_f32_e32 v202, v202, v96
	v_add_f32_e32 v203, v203, v97
	v_add_f32_e32 v204, v204, v98
	v_add_f32_e32 v205, v205, v99
	v_add_f32_e32 v206, v206, v100
	v_add_f32_e32 v207, v207, v101
	v_add_f32_e32 v208, v208, v102
	v_add_f32_e32 v209, v209, v103
	v_add_f32_e32 v202, v202, v88
	v_add_f32_e32 v203, v203, v89
	v_add_f32_e32 v204, v204, v90
	v_add_f32_e32 v205, v205, v91
	v_add_f32_e32 v206, v206, v92
	v_add_f32_e32 v207, v207, v93
	v_add_f32_e32 v208, v208, v94
	v_add_f32_e32 v209, v209, v95
	s_mov_b64 exec, s[48:49]
	v_add_f32_e32 v202, v202, v80
	v_add_f32_e32 v203, v203, v81
	v_add_f32_e32 v204, v204, v82
	v_add_f32_e32 v205, v205, v83
	v_add_f32_e32 v206, v206, v84
	v_add_f32_e32 v207, v207, v85
	v_add_f32_e32 v208, v208, v86
	v_add_f32_e32 v209, v209, v87
	v_add_f32_e32 v202, v202, v72
	v_add_f32_e32 v203, v203, v73
	v_add_f32_e32 v204, v204, v74
	v_add_f32_e32 v205, v205, v75
	v_add_f32_e32 v206, v206, v76
	v_add_f32_e32 v207, v207, v77
	v_add_f32_e32 v208, v208, v78
	v_add_f32_e32 v209, v209, v79
	v_add_f32_e32 v202, v202, v64
	v_add_f32_e32 v203, v203, v65
	v_add_f32_e32 v204, v204, v66
	v_add_f32_e32 v205, v205, v67
	v_add_f32_e32 v206, v206, v68
	v_add_f32_e32 v207, v207, v69
	v_add_f32_e32 v208, v208, v70
	v_add_f32_e32 v209, v209, v71
	v_add_f32_e32 v202, v202, v56
	v_add_f32_e32 v203, v203, v57
	v_add_f32_e32 v204, v204, v58
	v_add_f32_e32 v205, v205, v59
	v_add_f32_e32 v206, v206, v60
	v_add_f32_e32 v207, v207, v61
	v_add_f32_e32 v208, v208, v62
	v_add_f32_e32 v209, v209, v63
	s_mov_b64 exec, s[50:51]
	v_add_f32_e32 v202, v202, v48
	v_add_f32_e32 v203, v203, v49
	v_add_f32_e32 v204, v204, v50
	v_add_f32_e32 v205, v205, v51
	v_add_f32_e32 v206, v206, v52
	v_add_f32_e32 v207, v207, v53
	v_add_f32_e32 v208, v208, v54
	v_add_f32_e32 v209, v209, v55
	v_add_f32_e32 v202, v202, v40
	v_add_f32_e32 v203, v203, v41
	v_add_f32_e32 v204, v204, v42
	v_add_f32_e32 v205, v205, v43
	v_add_f32_e32 v206, v206, v44
	v_add_f32_e32 v207, v207, v45
	v_add_f32_e32 v208, v208, v46
	v_add_f32_e32 v209, v209, v47
	v_add_f32_e32 v202, v202, v32
	v_add_f32_e32 v203, v203, v33
	v_add_f32_e32 v204, v204, v34
	v_add_f32_e32 v205, v205, v35
	v_add_f32_e32 v206, v206, v36
	v_add_f32_e32 v207, v207, v37
	v_add_f32_e32 v208, v208, v38
	v_add_f32_e32 v209, v209, v39
	v_add_f32_e32 v202, v202, v24
	v_add_f32_e32 v203, v203, v25
	v_add_f32_e32 v204, v204, v26
	v_add_f32_e32 v205, v205, v27
	v_add_f32_e32 v206, v206, v28
	v_add_f32_e32 v207, v207, v29
	v_add_f32_e32 v208, v208, v30
	v_add_f32_e32 v209, v209, v31
	v_add_f32_e32 v202, v202, v16
	v_add_f32_e32 v203, v203, v17
	v_add_f32_e32 v204, v204, v18
	v_add_f32_e32 v205, v205, v19
	v_add_f32_e32 v206, v206, v20
	v_add_f32_e32 v207, v207, v21
	v_add_f32_e32 v208, v208, v22
	v_add_f32_e32 v209, v209, v23
	v_add_f32_e32 v202, v202, v8
	v_add_f32_e32 v203, v203, v9
	v_add_f32_e32 v204, v204, v10
	v_add_f32_e32 v205, v205, v11
	v_add_f32_e32 v206, v206, v12
	v_add_f32_e32 v207, v207, v13
	v_add_f32_e32 v208, v208, v14
	v_add_f32_e32 v209, v209, v15
	v_add_f32_e32 v202, v202, v0
	v_add_f32_e32 v203, v203, v1
	v_add_f32_e32 v204, v204, v2
	v_add_f32_e32 v205, v205, v3
	v_add_f32_e32 v206, v206, v4
	v_add_f32_e32 v207, v207, v5
	v_add_f32_e32 v208, v208, v6
	v_add_f32_e32 v209, v209, v7
	v_add_f32_e32 v202, v202, v126
	v_add_f32_e32 v203, v203, v127
	v_add_f32_e32 v204, v204, v128
	v_add_f32_e32 v205, v205, v129
	v_add_f32_e32 v206, v206, v130
	v_add_f32_e32 v207, v207, v131
	v_add_f32_e32 v208, v208, v132
	v_add_f32_e32 v209, v209, v133
	s_mov_b64 exec, -1
	v_fma_f32 v202, v202, v186, -v112
	v_fma_f32 v203, v203, v186, -v113
	v_add_f32_dpp v232, v232, v232 quad_perm:[1,0,3,2] row_mask:0xf bank_mask:0xf
	v_add_f32_dpp v233, v233, v233 quad_perm:[1,0,3,2] row_mask:0xf bank_mask:0xf
	v_fma_f32 v204, v204, v186, -v114
	v_fma_f32 v205, v205, v186, -v115
	v_add_f32_dpp v232, v232, v232 quad_perm:[2,3,0,1] row_mask:0xf bank_mask:0xf
	v_add_f32_dpp v233, v233, v233 quad_perm:[2,3,0,1] row_mask:0xf bank_mask:0xf
	v_fma_f32 v206, v206, v186, -v116
	v_fma_f32 v207, v207, v186, -v117
	v_add_f32_dpp v232, v232, v232 row_half_mirror row_mask:0xf bank_mask:0xf
	v_add_f32_dpp v233, v233, v233 row_half_mirror row_mask:0xf bank_mask:0xf
	v_fma_f32 v208, v208, v186, -v118
	v_fma_f32 v209, v209, v186, -v119
	v_add_f32_dpp v232, v232, v232 row_mirror row_mask:0xf bank_mask:0xf
	v_add_f32_dpp v233, v233, v233 row_mirror row_mask:0xf bank_mask:0xf
	v_cvt_pk_bf16_f32 v228, v202, v203
	v_cvt_pk_bf16_f32 v229, v204, v205
	v_mov_b32_e32 v234, v232
	v_mov_b32_e32 v235, v233
	v_cvt_pk_bf16_f32 v230, v206, v207
	v_cvt_pk_bf16_f32 v231, v208, v209
	v_permlane16_swap_b32_e32 v232, v234
	v_permlane16_swap_b32_e32 v233, v235
	s_nop 0
	v_add_f32_e32 v232, v232, v234
	v_add_f32_e32 v233, v233, v235
	global_store_dwordx4 v156, v[228:231], s[22:23]
	global_store_dwordx2 v184, v[238:239], s[28:29]
	v_mov_b32_e32 v234, v232
	v_mov_b32_e32 v235, v233
	s_nop 1
	v_permlane32_swap_b32_e32 v232, v234
	v_permlane32_swap_b32_e32 v233, v235
	s_nop 0
	v_add_f32_e32 v232, v232, v234
	v_add_f32_e32 v233, v233, v235
	v_fma_f32 v232, v232, s58, v187
	v_fma_f32 v233, v233, s59, v187
	v_rsq_f32_e32 v236, v232
	v_rsq_f32_e32 v237, v233
	s_add_u32 s22, s22, 0x400
	s_addc_u32 s23, s23, 0
	s_add_u32 s28, s28, 0x600
	s_addc_u32 s29, s29, 0
	v_mul_f32_e32 v236, s57, v236
	v_mul_f32_e32 v210, v210, v236
	v_mul_f32_e32 v211, v211, v236
	v_mul_f32_e32 v212, v212, v236
	v_mul_f32_e32 v213, v213, v236
	v_mul_f32_e32 v214, v214, v236
	v_mul_f32_e32 v215, v215, v236
	v_mul_f32_e32 v216, v216, v237
	v_mul_f32_e32 v217, v217, v237
	v_mul_f32_e32 v218, v218, v237
	v_mul_f32_e32 v219, v219, v237
	v_mul_f32_e32 v210, v210, v192
	v_mul_f32_e32 v211, v211, v193
	v_mul_f32_e32 v212, v212, v194
	v_mul_f32_e32 v213, v213, v195
	v_mul_f32_e32 v214, v214, v196
	v_mul_f32_e32 v215, v215, v197
	v_mul_f32_e32 v216, v216, v198
	v_mul_f32_e32 v217, v217, v199
	v_mul_f32_e32 v218, v218, v200
	v_mul_f32_e32 v219, v219, v201
	v_cvt_pk_bf16_f32 v120, v210, v211
	v_cvt_pk_bf16_f32 v121, v212, v213
	v_cvt_pk_bf16_f32 v122, v214, v215
	v_cvt_pk_bf16_f32 v123, v216, v217
	v_cvt_pk_bf16_f32 v125, v218, v219
	global_store_dword v157, v120, s[24:25]
	global_store_dword v157, v121, s[24:25] offset:256
	global_store_dword v157, v122, s[24:25] offset:512
	global_store_dword v157, v123, s[26:27]
	global_store_dword v157, v125, s[26:27] offset:256
	s_add_u32 s24, s24, 0x300
	s_addc_u32 s25, s25, 0
	s_add_u32 s26, s26, 0x200
	s_addc_u32 s27, s27, 0
	s_waitcnt vmcnt(14)
	v_lshlrev_b32_e32 v126, 16, v162
	v_and_b32_e32 v127, s56, v162
	v_lshlrev_b32_e32 v128, 16, v163
	v_and_b32_e32 v129, s56, v163
	v_lshlrev_b32_e32 v130, 16, v164
	v_and_b32_e32 v131, s56, v164
	v_lshlrev_b32_e32 v132, 16, v165
	v_and_b32_e32 v133, s56, v165
	v_cndmask_b32_e64 v234, v172, v174, s[52:53]
	v_cndmask_b32_e64 v235, v173, v175, s[52:53]
	v_cndmask_b32_e64 v232, v174, v172, s[52:53]
	v_cndmask_b32_e64 v233, v175, v173, s[52:53]
	v_lshlrev_b32_e32 v220, 16, v234
	v_and_b32_e32 v221, s56, v234
	v_lshlrev_b32_e32 v222, 16, v235
	v_and_b32_e32 v223, s56, v235
	v_lshlrev_b32_e32 v224, 16, v232
	v_and_b32_e32 v225, s56, v232
	v_lshlrev_b32_e32 v226, 16, v233
	v_and_b32_e32 v227, s56, v233
	v_xor_b32_e32 v234, v185, v177
	v_mul_f32_e32 v224, v224, v234
	v_fmac_f32_e32 v224, v220, v176
	v_xor_b32_e32 v234, v185, v179
	v_mul_f32_e32 v225, v225, v234
	v_fmac_f32_e32 v225, v221, v178
	v_xor_b32_e32 v234, v185, v181
	v_mul_f32_e32 v226, v226, v234
	v_fmac_f32_e32 v226, v222, v180
	v_xor_b32_e32 v234, v185, v183
	v_mul_f32_e32 v227, v227, v234
	v_fmac_f32_e32 v227, v223, v182
	v_cvt_pk_bf16_f32 v238, v224, v225
	v_cvt_pk_bf16_f32 v239, v226, v227
	v_lshlrev_b32_e32 v210, 16, v166
	v_and_b32_e32 v211, s56, v166
	v_lshlrev_b32_e32 v212, 16, v167
	v_and_b32_e32 v213, s56, v167
	v_lshlrev_b32_e32 v214, 16, v168
	v_and_b32_e32 v215, s56, v168
	v_lshlrev_b32_e32 v216, 16, v169
	v_and_b32_e32 v217, s56, v169
	v_lshlrev_b32_e32 v218, 16, v170
	v_and_b32_e32 v219, s56, v170
	v_mul_f32_e32 v232, v210, v210
	v_mul_f32_e32 v233, v216, v216
	v_fmac_f32_e32 v232, v211, v211
	v_fmac_f32_e32 v233, v217, v217
	v_fmac_f32_e32 v232, v212, v212
	v_fmac_f32_e32 v233, v218, v218
	v_fmac_f32_e32 v232, v213, v213
	v_fmac_f32_e32 v233, v219, v219
	v_fmac_f32_e32 v232, v214, v214
	v_fmac_f32_e32 v232, v215, v215
	v_add_f32_e32 v202, v126, v112
	v_add_f32_e32 v203, v127, v113
	v_add_f32_e32 v204, v128, v114
	v_add_f32_e32 v205, v129, v115
	v_add_f32_e32 v206, v130, v116
	v_add_f32_e32 v207, v131, v117
	v_add_f32_e32 v208, v132, v118
	v_add_f32_e32 v209, v133, v119
	s_mov_b64 exec, s[46:47]
	v_add_f32_e32 v202, v202, v104
	v_add_f32_e32 v203, v203, v105
	v_add_f32_e32 v204, v204, v106
	v_add_f32_e32 v205, v205, v107
	v_add_f32_e32 v206, v206, v108
	v_add_f32_e32 v207, v207, v109
	v_add_f32_e32 v208, v208, v110
	v_add_f32_e32 v209, v209, v111
	v_add_f32_e32 v202, v202, v96
	v_add_f32_e32 v203, v203, v97
	v_add_f32_e32 v204, v204, v98
	v_add_f32_e32 v205, v205, v99
	v_add_f32_e32 v206, v206, v100
	v_add_f32_e32 v207, v207, v101
	v_add_f32_e32 v208, v208, v102
	v_add_f32_e32 v209, v209, v103
	s_mov_b64 exec, s[48:49]
	v_add_f32_e32 v202, v202, v88
	v_add_f32_e32 v203, v203, v89
	v_add_f32_e32 v204, v204, v90
	v_add_f32_e32 v205, v205, v91
	v_add_f32_e32 v206, v206, v92
	v_add_f32_e32 v207, v207, v93
	v_add_f32_e32 v208, v208, v94
	v_add_f32_e32 v209, v209, v95
	v_add_f32_e32 v202, v202, v80
	v_add_f32_e32 v203, v203, v81
	v_add_f32_e32 v204, v204, v82
	v_add_f32_e32 v205, v205, v83
	v_add_f32_e32 v206, v206, v84
	v_add_f32_e32 v207, v207, v85
	v_add_f32_e32 v208, v208, v86
	v_add_f32_e32 v209, v209, v87
	v_add_f32_e32 v202, v202, v72
	v_add_f32_e32 v203, v203, v73
	v_add_f32_e32 v204, v204, v74
	v_add_f32_e32 v205, v205, v75
	v_add_f32_e32 v206, v206, v76
	v_add_f32_e32 v207, v207, v77
	v_add_f32_e32 v208, v208, v78
	v_add_f32_e32 v209, v209, v79
	v_add_f32_e32 v202, v202, v64
	v_add_f32_e32 v203, v203, v65
	v_add_f32_e32 v204, v204, v66
	v_add_f32_e32 v205, v205, v67
	v_add_f32_e32 v206, v206, v68
	v_add_f32_e32 v207, v207, v69
	v_add_f32_e32 v208, v208, v70
	v_add_f32_e32 v209, v209, v71
	s_mov_b64 exec, s[50:51]
	v_add_f32_e32 v202, v202, v56
	v_add_f32_e32 v203, v203, v57
	v_add_f32_e32 v204, v204, v58
	v_add_f32_e32 v205, v205, v59
	v_add_f32_e32 v206, v206, v60
	v_add_f32_e32 v207, v207, v61
	v_add_f32_e32 v208, v208, v62
	v_add_f32_e32 v209, v209, v63
	v_add_f32_e32 v202, v202, v48
	v_add_f32_e32 v203, v203, v49
	v_add_f32_e32 v204, v204, v50
	v_add_f32_e32 v205, v205, v51
	v_add_f32_e32 v206, v206, v52
	v_add_f32_e32 v207, v207, v53
	v_add_f32_e32 v208, v208, v54
	v_add_f32_e32 v209, v209, v55
	v_add_f32_e32 v202, v202, v40
	v_add_f32_e32 v203, v203, v41
	v_add_f32_e32 v204, v204, v42
	v_add_f32_e32 v205, v205, v43
	v_add_f32_e32 v206, v206, v44
	v_add_f32_e32 v207, v207, v45
	v_add_f32_e32 v208, v208, v46
	v_add_f32_e32 v209, v209, v47
	v_add_f32_e32 v202, v202, v32
	v_add_f32_e32 v203, v203, v33
	v_add_f32_e32 v204, v204, v34
	v_add_f32_e32 v205, v205, v35
	v_add_f32_e32 v206, v206, v36
	v_add_f32_e32 v207, v207, v37
	v_add_f32_e32 v208, v208, v38
	v_add_f32_e32 v209, v209, v39
	v_add_f32_e32 v202, v202, v24
	v_add_f32_e32 v203, v203, v25
	v_add_f32_e32 v204, v204, v26
	v_add_f32_e32 v205, v205, v27
	v_add_f32_e32 v206, v206, v28
	v_add_f32_e32 v207, v207, v29
	v_add_f32_e32 v208, v208, v30
	v_add_f32_e32 v209, v209, v31
	v_add_f32_e32 v202, v202, v16
	v_add_f32_e32 v203, v203, v17
	v_add_f32_e32 v204, v204, v18
	v_add_f32_e32 v205, v205, v19
	v_add_f32_e32 v206, v206, v20
	v_add_f32_e32 v207, v207, v21
	v_add_f32_e32 v208, v208, v22
	v_add_f32_e32 v209, v209, v23
	v_add_f32_e32 v202, v202, v8
	v_add_f32_e32 v203, v203, v9
	v_add_f32_e32 v204, v204, v10
	v_add_f32_e32 v205, v205, v11
	v_add_f32_e32 v206, v206, v12
	v_add_f32_e32 v207, v207, v13
	v_add_f32_e32 v208, v208, v14
	v_add_f32_e32 v209, v209, v15
	v_add_f32_e32 v202, v202, v0
	v_add_f32_e32 v203, v203, v1
	v_add_f32_e32 v204, v204, v2
	v_add_f32_e32 v205, v205, v3
	v_add_f32_e32 v206, v206, v4
	v_add_f32_e32 v207, v207, v5
	v_add_f32_e32 v208, v208, v6
	v_add_f32_e32 v209, v209, v7
	s_mov_b64 exec, -1
	v_fma_f32 v202, v202, v186, -v126
	v_fma_f32 v203, v203, v186, -v127
	v_add_f32_dpp v232, v232, v232 quad_perm:[1,0,3,2] row_mask:0xf bank_mask:0xf
	v_add_f32_dpp v233, v233, v233 quad_perm:[1,0,3,2] row_mask:0xf bank_mask:0xf
	v_fma_f32 v204, v204, v186, -v128
	v_fma_f32 v205, v205, v186, -v129
	v_add_f32_dpp v232, v232, v232 quad_perm:[2,3,0,1] row_mask:0xf bank_mask:0xf
	v_add_f32_dpp v233, v233, v233 quad_perm:[2,3,0,1] row_mask:0xf bank_mask:0xf
	v_fma_f32 v206, v206, v186, -v130
	v_fma_f32 v207, v207, v186, -v131
	v_add_f32_dpp v232, v232, v232 row_half_mirror row_mask:0xf bank_mask:0xf
	v_add_f32_dpp v233, v233, v233 row_half_mirror row_mask:0xf bank_mask:0xf
	v_fma_f32 v208, v208, v186, -v132
	v_fma_f32 v209, v209, v186, -v133
	v_add_f32_dpp v232, v232, v232 row_mirror row_mask:0xf bank_mask:0xf
	v_add_f32_dpp v233, v233, v233 row_mirror row_mask:0xf bank_mask:0xf
	v_cvt_pk_bf16_f32 v228, v202, v203
	v_cvt_pk_bf16_f32 v229, v204, v205
	v_mov_b32_e32 v234, v232
	v_mov_b32_e32 v235, v233
	v_cvt_pk_bf16_f32 v230, v206, v207
	v_cvt_pk_bf16_f32 v231, v208, v209
	v_permlane16_swap_b32_e32 v232, v234
	v_permlane16_swap_b32_e32 v233, v235
	s_nop 0
	v_add_f32_e32 v232, v232, v234
	v_add_f32_e32 v233, v233, v235
	global_store_dwordx4 v156, v[228:231], s[22:23]
	global_store_dwordx2 v184, v[238:239], s[28:29]
	v_mov_b32_e32 v234, v232
	v_mov_b32_e32 v235, v233
	s_nop 1
	v_permlane32_swap_b32_e32 v232, v234
	v_permlane32_swap_b32_e32 v233, v235
	s_nop 0
	v_add_f32_e32 v232, v232, v234
	v_add_f32_e32 v233, v233, v235
	v_fma_f32 v232, v232, s58, v187
	v_fma_f32 v233, v233, s59, v187
	v_rsq_f32_e32 v236, v232
	v_rsq_f32_e32 v237, v233
	s_add_u32 s22, s22, 0x400
	s_addc_u32 s23, s23, 0
	s_add_u32 s28, s28, 0x600
	s_addc_u32 s29, s29, 0
	v_mul_f32_e32 v236, s57, v236
	v_mul_f32_e32 v210, v210, v236
	v_mul_f32_e32 v211, v211, v236
	v_mul_f32_e32 v212, v212, v236
	v_mul_f32_e32 v213, v213, v236
	v_mul_f32_e32 v214, v214, v236
	v_mul_f32_e32 v215, v215, v236
	v_mul_f32_e32 v216, v216, v237
	v_mul_f32_e32 v217, v217, v237
	v_mul_f32_e32 v218, v218, v237
	v_mul_f32_e32 v219, v219, v237
	v_mul_f32_e32 v210, v210, v192
	v_mul_f32_e32 v211, v211, v193
	v_mul_f32_e32 v212, v212, v194
	v_mul_f32_e32 v213, v213, v195
	v_mul_f32_e32 v214, v214, v196
	v_mul_f32_e32 v215, v215, v197
	v_mul_f32_e32 v216, v216, v198
	v_mul_f32_e32 v217, v217, v199
	v_mul_f32_e32 v218, v218, v200
	v_mul_f32_e32 v219, v219, v201
	v_cvt_pk_bf16_f32 v120, v210, v211
	v_cvt_pk_bf16_f32 v121, v212, v213
	v_cvt_pk_bf16_f32 v122, v214, v215
	v_cvt_pk_bf16_f32 v123, v216, v217
	v_cvt_pk_bf16_f32 v125, v218, v219
	global_store_dword v157, v120, s[24:25]
	global_store_dword v157, v121, s[24:25] offset:256
	global_store_dword v157, v122, s[24:25] offset:512
	global_store_dword v157, v123, s[26:27]
	global_store_dword v157, v125, s[26:27] offset:256
	s_add_u32 s24, s24, 0x300
	s_addc_u32 s25, s25, 0
	s_add_u32 s26, s26, 0x200
	s_addc_u32 s27, s27, 0
.Lp2_next:
	s_waitcnt vmcnt(0)
	s_add_i32 s33, s33, s34
	s_branch .Lp2_job
.Lp2_done:
.LBB0_495:
	v_readlane_b32 s0, v240, 26
	s_cmpk_gt_i32 s0, 0xef
	v_readlane_b32 s1, v240, 27
	s_cbranch_scc1 .LBB0_499
	v_readlane_b32 s0, v240, 26
	s_add_i32 s0, s0, 0x8010
	v_readlane_b32 s1, v240, 27
	s_mul_hi_i32 s3, s0, 0x600
	s_mul_i32 s4, s0, 0x600
	v_mov_b32_e32 v0, 0
	s_ashr_i32 s1, s0, 31
	v_lshl_or_b32 v2, v161, 3, s4
	v_mov_b32_e32 v3, s3
	v_mov_b32_e32 v125, v0
	s_waitcnt lgkmcnt(0)
	v_readlane_b32 s12, v240, 28
	v_lshl_add_u64 v[2:3], v[2:3], 0, v[124:125]
	s_mov_b64 s[4:5], 0x18400080
	v_readlane_b32 s13, v240, 29
	s_lshl_b64 s[10:11], s[0:1], 10
	v_lshl_add_u64 v[4:5], v[2:3], 0, s[4:5]
	s_ashr_i32 s13, s12, 31
	s_lshl_b64 s[6:7], s[0:1], 9
	v_lshlrev_b32_e32 v1, 2, v160
	s_mul_hi_i32 s3, s0, 0x300
	s_mul_i32 s8, s0, 0x300
	v_lshl_or_b32 v2, v160, 4, s10
	v_mov_b32_e32 v3, s11
	s_mov_b64 s[10:11], 0x13900000
	s_mul_hi_i32 s5, s12, 0x600
	s_mul_i32 s4, s12, 0x600
	v_or_b32_e32 v6, s6, v1
	v_mov_b32_e32 v7, s7
	s_lshl_b64 s[6:7], s[12:13], 9
	v_or_b32_e32 v8, s8, v1
	v_mov_b32_e32 v9, s3
	s_mul_hi_i32 s9, s12, 0x300
	s_mul_i32 s8, s12, 0x300
	v_lshl_add_u64 v[10:11], v[2:3], 0, s[10:11]
	s_lshl_b64 s[10:11], s[12:13], 10
	v_mov_b32_e32 v1, v0
	v_mov_b32_e32 v2, v0
	v_mov_b32_e32 v3, v0
	v_mov_b32_e32 v12, v0
	v_mov_b32_e32 v13, v0

.LBB0_769:
	s_add_i32 s7, s60, 3
	s_and_b32 s6, s7, 3
	s_xor_b32 s34, s6, 2
	s_mul_i32 s35, s34, 0x3000
	s_add_i32 s36, s35, s55
	s_add_i32 s35, s59, s35
	s_lshl_b32 s34, s34, 13
	s_add_i32 s34, s58, s34
	s_cmp_le_u32 s57, s7
	s_cbranch_scc1 .Latt_inactive
	s_mul_i32 s7, s6, 0x3000
	v_add_u32_e32 v112, s7, v151
	v_lshl_add_u32 v136, s6, 13, v161
	ds_read_b128 v[196:199], v112
	ds_read_b128 v[200:203], v112 offset:512
	ds_read_b128 v[204:207], v112 offset:2048
	ds_read_b128 v[208:211], v112 offset:2560
	ds_read_b128 v[212:215], v112 offset:4096
	ds_read_b128 v[216:219], v112 offset:4608
	ds_read_b128 v[220:223], v112 offset:6144
	ds_read_b128 v[224:227], v112 offset:6656
	ds_read_b128 v[228:231], v112 offset:8192
	ds_read_b128 v[232:235], v112 offset:8704
	ds_read_b128 v[236:239], v112 offset:10240
	ds_read_b128 v[176:179], v112 offset:10752
	s_mov_b32 s37, m0
	s_waitcnt lgkmcnt(11)
	v_mfma_f32_32x32x16_bf16 v[64:79], v[196:199], v[92:95], v[32:47]
	s_waitcnt lgkmcnt(10)
	v_mfma_f32_32x32x16_bf16 v[48:63], v[200:203], v[92:95], v[32:47]
	s_mov_b32 m0, s36
	ds_read_b64_tr_b16 v[132:133], v136 offset:0
	ds_read_b64_tr_b16 v[134:135], v136 offset:512
	ds_read_b64_tr_b16 v[128:129], v136 offset:1024
	global_load_lds_dwordx4 v[158:159], off
	s_waitcnt lgkmcnt(12)
	v_mfma_f32_32x32x16_bf16 v[64:79], v[204:207], v[88:91], v[64:79]
	s_waitcnt lgkmcnt(11)
	v_mfma_f32_32x32x16_bf16 v[48:63], v[208:211], v[88:91], v[48:63]
	ds_read_b64_tr_b16 v[130:131], v136 offset:1536
	ds_read_b64_tr_b16 v[124:125], v136 offset:2048
	ds_read_b64_tr_b16 v[126:127], v136 offset:2560
	s_waitcnt lgkmcnt(13)
	v_mfma_f32_32x32x16_bf16 v[64:79], v[212:215], v[84:87], v[64:79]
	s_waitcnt lgkmcnt(12)
	v_mfma_f32_32x32x16_bf16 v[48:63], v[216:219], v[84:87], v[48:63]
	ds_read_b64_tr_b16 v[120:121], v136 offset:3072
	ds_read_b64_tr_b16 v[122:123], v136 offset:3584
	ds_read_b64_tr_b16 v[116:117], v136 offset:4096
	s_and_b64 vcc, exec, s[4:5]
	s_cbranch_vccnz .Latt_nok2
	v_lshl_add_u64 v[188:189], v[158:159], 0, s[12:13]
	s_mov_b32 m0, s35
	s_nop 0
	global_load_lds_dwordx4 v[188:189], off
.Latt_nok2:
	s_waitcnt lgkmcnt(14)
	v_mfma_f32_32x32x16_bf16 v[64:79], v[220:223], v[80:83], v[64:79]
	s_waitcnt lgkmcnt(13)
	v_mfma_f32_32x32x16_bf16 v[48:63], v[224:227], v[80:83], v[48:63]
	ds_read_b64_tr_b16 v[118:119], v136 offset:4608
	ds_read_b64_tr_b16 v[112:113], v136 offset:5120
	s_waitcnt lgkmcnt(14)
	v_mfma_f32_32x32x16_bf16 v[64:79], v[228:231], v[96:99], v[64:79]
	s_waitcnt lgkmcnt(13)
	v_mfma_f32_32x32x16_bf16 v[48:63], v[232:235], v[96:99], v[48:63]
	ds_read_b64_tr_b16 v[114:115], v136 offset:5632
	ds_read_b64_tr_b16 v[108:109], v136 offset:6144
	s_mov_b32 m0, s34
	s_nop 0
	global_load_lds_dwordx4 v[156:157], off
	s_waitcnt lgkmcnt(14)
	v_mfma_f32_32x32x16_bf16 v[64:79], v[236:239], v[100:103], v[64:79]
	s_waitcnt lgkmcnt(13)
	v_mfma_f32_32x32x16_bf16 v[48:63], v[176:179], v[100:103], v[48:63]
	ds_read_b64_tr_b16 v[110:111], v136 offset:6656
	ds_read_b64_tr_b16 v[104:105], v136 offset:7168
	s_waitcnt lgkmcnt(14)
	ds_read_b64_tr_b16 v[106:107], v136 offset:7680
	s_mov_b32 m0, s37
	s_nop 6
	v_max3_f32 v136, v64, v65, v48
	v_max3_f32 v175, v66, v67, v49
	s_nop 0
	v_max3_f32 v136, v136, v50, v51
	v_max3_f32 v175, v175, v70, v71
	s_nop 0
	v_max3_f32 v136, v136, v68, v69
	v_max3_f32 v175, v175, v54, v55
	s_nop 0
	v_max3_f32 v136, v136, v52, v53
	v_max3_f32 v175, v175, v74, v75
	s_nop 0
	v_max3_f32 v136, v136, v72, v73
	v_max3_f32 v175, v175, v58, v59
	s_nop 0
	v_max3_f32 v136, v136, v56, v57
	v_max3_f32 v175, v175, v78, v79
	s_nop 0
	v_max3_f32 v136, v136, v76, v77
	v_max3_f32 v175, v175, v62, v63
	s_nop 0
	v_max3_f32 v136, v136, v60, v61
	s_nop 0
	v_max_f32_e32 v136, v136, v175
	s_nop 0
	v_mov_b32_e32 v175, v136
	s_nop 1
	v_permlane32_swap_b32_e32 v136, v175
	v_max_f32_e32 v136, v136, v175
	s_nop 0
	v_cmp_lt_f32_e32 vcc, s51, v136
	s_cbranch_vccz .LBB0_763
	v_max_f32_e32 v32, v136, v136
	v_max_f32_e32 v34, 0, v32
	v_exp_f32_e64 v136, -v34
	s_and_saveexec_b64 s[6:7], s[0:1]
	s_cbranch_execz .LBB0_762
	ds_write_b32 v171, v136
	s_branch .LBB0_762
.Latt_inactive:
	s_mov_b32 s37, m0
	s_mov_b32 m0, s36
	s_nop 0
	global_load_lds_dwordx4 v[158:159], off
	s_and_b64 vcc, exec, s[4:5]
	s_cbranch_vccnz .Latt_inact_b
	v_lshl_add_u64 v[188:189], v[158:159], 0, s[12:13]
	s_mov_b32 m0, s35
	s_nop 0
	global_load_lds_dwordx4 v[188:189], off
.Latt_inact_b:
	s_mov_b32 m0, s34
	s_nop 0
	global_load_lds_dwordx4 v[156:157], off
	s_mov_b32 m0, s37
	s_branch .LBB0_764
